# v6: v4 + base/gate loads of the P8 (mid + epilogue), P2 and fused-P12 epilogues issued ahead (rolling prefetch into dead fragment registers, counted waits)
# speedup vs baseline: 1.0019x; 1.0019x over previous
; __host__ __device__ __forceinline__ size_t blk(int r, int k, int K) { return (((size_t)((r >> 8) * (K >> 6) + (k >> 6))) << 14) + (size_t)(((r & 255) << 6) + (k & 63)); }
; __device__ __forceinline__ float bflo(unsigned w) { return __uint_as_float(w << 16); }
; __device__ __forceinline__ float bfhi(unsigned w) { return __uint_as_float(w & 0xffff0000u); }
; __device__ __forceinline__ unsigned pk2(float lo, float hi) { f32x2 v = {lo, hi}; bf16x2_t b = __builtin_convertvector(v, bf16x2_t); return __builtin_bit_cast(unsigned, b); }
;     __device__ __forceinline__ void operator()(f32x4 (&acc)[2][2][4][2], const Unit& u, int wr, int wc, int fr, int fq) const { fused(acc, u, wr, wc, fr, fq, tb, wr * 4 + wc, fq * 16 + fr); }
;     __device__ __forceinline__ void operator()(const f32x4 (&acc)[2][2][4][2], const Unit& u, int wr, int wc, int fr, int fq) const {
;         const int row0 = u.pm * BM + wr * 64 + fr, col0 = u.pn * BM + wc * 32 + 8 * fq;
; #pragma unroll
;         for (int ai = 0; ai < 2; ++ai)
; #pragma unroll
;             for (int m = 0; m < 4; ++m) { const int row = row0 + ai * HALF + m * 16; const size_t off = (size_t)row * D + col0; float s = 0.f;
; #pragma unroll
;                 for (int bj = 0; bj < 2; ++bj) {
;                     f32x4 v0, v1;
;                     if (MODE == 0) { v0 = *(const f32x4*)(base + off + bj * HALF); v1 = *(const f32x4*)(base + off + bj * HALF + 4); }
;                     else { const u32x4 r = *(const u32x4*)(bb + blk(row, col0 + bj * HALF, D)); v0 = (f32x4){bflo(r.x), bfhi(r.x), bflo(r.y), bfhi(r.y)}; v1 = (f32x4){bflo(r.z), bfhi(r.z), bflo(r.w), bfhi(r.w)}; }
;                     v0 += acc[ai][bj][m][0] * alpha; v1 += acc[ai][bj][m][1] * alpha;
;                     if (MODE == 2) { *(f32x4*)(out + off + bj * HALF) = v0; *(f32x4*)(out + off + bj * HALF + 4) = v1; }
;                     else {
;                         s += (v0[0] * v0[0] + v0[1] * v0[1]) + (v0[2] * v0[2] + v0[3] * v0[3]) + (v1[0] * v1[0] + v1[1] * v1[1]) + (v1[2] * v1[2] + v1[3] * v1[3]);
;                         u32x4 w; w.x = pk2(v0[0], v0[1]); w.y = pk2(v0[2], v0[3]); w.z = pk2(v1[0], v1[1]); w.w = pk2(v1[2], v1[3]); *(u32x4*)(xb + blk(row, col0 + bj * HALF, D)) = w; } }
;                 if (MODE != 2) { s += __shfl_xor(s, 16); s += __shfl_xor(s, 32); if (fq == 0) unsafeAtomicAdd(ssq + row, s); } }
.LBB0_203:
	s_lshl_b32 s44, s73, 8
	s_add_i32 s44, s44, s35
	v_or_b32_e32 v150, s44, v1
	s_lshl_b32 s45, s72, 8
	s_or_b32 s45, s45, s56
	v_ashrrev_i32_e32 v151, 31, v150
	v_or_b32_e32 v148, s45, v152
	v_lshlrev_b64 v[158:159], 14, v[150:151]
	v_ashrrev_i32_e32 v149, 31, v148
	v_lshl_add_u64 v[158:159], s[8:9], 0, v[158:159]
	v_lshl_add_u64 v[168:169], v[148:149], 2, v[158:159]
	v_mov_b32_e32 v176, v168
	v_mov_b32_e32 v177, v169
	global_load_dwordx4 v[160:163], v[168:169], off
	global_load_dwordx4 v[164:167], v[168:169], off offset:16
	s_mov_b32 s98, 0x40000
	s_mov_b32 s99, 0
	s_mov_b32 s100, 0x140000
	s_mov_b32 s101, 0
	global_load_dwordx4 v[172:175], v[176:177], off offset:512
	global_load_dwordx4 v[180:183], v[176:177], off offset:528
	v_lshl_add_u64 v[176:177], v[176:177], 0, s[98:99]
	global_load_dwordx4 v[184:187], v[176:177], off
	global_load_dwordx4 v[188:191], v[176:177], off offset:16
	global_load_dwordx4 v[196:199], v[176:177], off offset:512
	global_load_dwordx4 v[200:203], v[176:177], off offset:528
	v_lshl_add_u64 v[176:177], v[176:177], 0, s[98:99]
	global_load_dwordx4 v[204:207], v[176:177], off
	global_load_dwordx4 v[208:211], v[176:177], off offset:16
	global_load_dwordx4 v[212:215], v[176:177], off offset:512
	global_load_dwordx4 v[216:219], v[176:177], off offset:528
	v_lshl_add_u64 v[176:177], v[176:177], 0, s[98:99]
	global_load_dwordx4 v[220:223], v[176:177], off
	s_ashr_i32 s44, s44, 2
	s_ashr_i32 s50, s45, 6
	s_and_b32 s46, s44, 0xffffffc0
	s_add_i32 s44, s46, s50
	v_bitop3_b32 v158, s45, 56, v152 bitop3:0xc8
	s_ashr_i32 s45, s44, 31
	v_lshlrev_b32_e32 v138, 6, v150
	s_lshl_b64 s[44:45], s[44:45], 15
	v_and_or_b32 v138, v138, s62, v158
	s_add_u32 s44, s42, s44
	v_lshlrev_b32_e32 v138, 1, v138
	s_addc_u32 s45, s43, s45
	v_xor_b32_e32 v159, 32, v157
	s_or_b32 s51, s50, 2
	s_add_i32 s46, s46, s51
	s_ashr_i32 s47, s46, 31
	s_lshl_b64 s[46:47], s[46:47], 15
	s_add_u32 s46, s42, s46
	s_addc_u32 s47, s43, s47
	s_waitcnt vmcnt(0)
	v_pk_fma_f32 v[128:129], v[128:129], 0.5, v[162:163] op_sel_hi:[1,0,1]
	v_pk_fma_f32 v[170:171], v[126:127], 0.5, v[160:161] op_sel_hi:[1,0,1]
	v_pk_fma_f32 v[166:167], v[124:125], 0.5, v[166:167] op_sel_hi:[1,0,1]
	v_pk_fma_f32 v[164:165], v[122:123], 0.5, v[164:165] op_sel_hi:[1,0,1]
	v_cvt_pk_bf16_f32 v122, v170, v171
	v_cvt_pk_bf16_f32 v123, v128, v129
	v_cvt_pk_bf16_f32 v124, v164, v165
	v_cvt_pk_bf16_f32 v125, v166, v167
	global_store_dwordx4 v138, v[122:125], s[44:45]
	s_nop 1
	s_nop 0
	s_nop 1
	v_and_b32_e32 v123, 64, v157
	v_xor_b32_e32 v122, 16, v157
	v_add_u32_e32 v123, 64, v123
	v_cmp_lt_i32_e32 vcc, v122, v123
	v_mul_f32_e32 v129, v129, v129
	v_fmac_f32_e32 v129, v128, v128
	v_cndmask_b32_e32 v122, v157, v122, vcc
	v_cmp_lt_i32_e32 vcc, v159, v123
	v_lshlrev_b32_e32 v123, 2, v122
	v_mul_f32_e32 v165, v165, v165
	v_cndmask_b32_e32 v159, v157, v159, vcc
	v_lshlrev_b32_e32 v122, 2, v159
	v_mul_f32_e32 v159, v171, v171
	v_fmac_f32_e32 v159, v170, v170
	v_add_f32_e32 v128, v159, v129
	v_mul_f32_e32 v167, v167, v167
	v_fmac_f32_e32 v165, v164, v164
	v_fmac_f32_e32 v167, v166, v166
	v_add_f32_e32 v128, v165, v128
	v_add_f32_e32 v128, v167, v128
	s_waitcnt vmcnt(11)
	v_mov_b32_e32 v124, v172
	v_mov_b32_e32 v125, v173
	v_mov_b32_e32 v126, v174
	v_mov_b32_e32 v127, v175
	global_load_dwordx4 v[172:175], v[176:177], off offset:16
	v_pk_fma_f32 v[120:121], v[120:121], 0.5, v[126:127] op_sel_hi:[1,0,1]
	v_pk_fma_f32 v[118:119], v[118:119], 0.5, v[124:125] op_sel_hi:[1,0,1]
	s_waitcnt vmcnt(11)
	v_mov_b32_e32 v160, v180
	v_mov_b32_e32 v161, v181
	v_mov_b32_e32 v162, v182
	v_mov_b32_e32 v163, v183
	global_load_dwordx4 v[180:183], v[176:177], off offset:512
	v_pk_fma_f32 v[114:115], v[114:115], 0.5, v[160:161] op_sel_hi:[1,0,1]
	v_mul_f32_e32 v126, v119, v119
	v_mul_f32_e32 v127, v121, v121
	v_pk_fma_f32 v[124:125], v[116:117], 0.5, v[162:163] op_sel_hi:[1,0,1]
	v_mul_f32_e32 v129, v115, v115
	v_fmac_f32_e32 v126, v118, v118
	v_fmac_f32_e32 v127, v120, v120
	v_mul_f32_e32 v159, v125, v125
	v_cvt_pk_bf16_f32 v116, v118, v119
	v_fmac_f32_e32 v129, v114, v114
	v_add_f32_e32 v118, v126, v127
	v_fmac_f32_e32 v159, v124, v124
	v_add_f32_e32 v118, v129, v118
	v_add_f32_e32 v118, v159, v118
	v_cvt_pk_bf16_f32 v117, v120, v121
	v_add_f32_e32 v120, v128, v118
	v_cvt_pk_bf16_f32 v118, v114, v115
	ds_bpermute_b32 v114, v123, v120
	v_cvt_pk_bf16_f32 v119, v124, v125
	global_store_dwordx4 v138, v[116:119], s[46:47]
	s_waitcnt lgkmcnt(0)
	v_add_f32_e32 v114, v120, v114
	ds_bpermute_b32 v115, v122, v114
	s_and_saveexec_b64 s[48:49], s[0:1]
	s_cbranch_execz .LBB0_205
	v_lshl_add_u64 v[116:117], v[150:151], 2, s[10:11]
	s_waitcnt lgkmcnt(0)
	v_add_f32_e32 v114, v114, v115
	global_atomic_add_f32 v[116:117], v114, off
; __host__ __device__ __forceinline__ size_t blk(int r, int k, int K) { return (((size_t)((r >> 8) * (K >> 6) + (k >> 6))) << 14) + (size_t)(((r & 255) << 6) + (k & 63)); }
; __device__ __forceinline__ float bflo(unsigned w) { return __uint_as_float(w << 16); }
; __device__ __forceinline__ float bfhi(unsigned w) { return __uint_as_float(w & 0xffff0000u); }
; __device__ __forceinline__ unsigned pk2(float lo, float hi) { f32x2 v = {lo, hi}; bf16x2_t b = __builtin_convertvector(v, bf16x2_t); return __builtin_bit_cast(unsigned, b); }
;     __device__ __forceinline__ void operator()(const f32x4 (&acc)[2][2][4][2], const Unit& u, int wr, int wc, int fr, int fq) const {
;     ...
;             for (int m = 0; m < 4; ++m) { const int row = row0 + ai * HALF + m * 16; const size_t off = (size_t)row * D + col0; float s = 0.f;
; #pragma unroll
;                 for (int bj = 0; bj < 2; ++bj) {
;                     f32x4 v0, v1;
;                     if (MODE == 0) { v0 = *(const f32x4*)(base + off + bj * HALF); v1 = *(const f32x4*)(base + off + bj * HALF + 4); }
;                     else { const u32x4 r = *(const u32x4*)(bb + blk(row, col0 + bj * HALF, D)); v0 = (f32x4){bflo(r.x), bfhi(r.x), bflo(r.y), bfhi(r.y)}; v1 = (f32x4){bflo(r.z), bfhi(r.z), bflo(r.w), bfhi(r.w)}; }
;                     v0 += acc[ai][bj][m][0] * alpha; v1 += acc[ai][bj][m][1] * alpha;
;                     if (MODE == 2) { *(f32x4*)(out + off + bj * HALF) = v0; *(f32x4*)(out + off + bj * HALF + 4) = v1; }
;                     else {
;                         s += (v0[0] * v0[0] + v0[1] * v0[1]) + (v0[2] * v0[2] + v0[3] * v0[3]) + (v1[0] * v1[0] + v1[1] * v1[1]) + (v1[2] * v1[2] + v1[3] * v1[3]);
;                         u32x4 w; w.x = pk2(v0[0], v0[1]); w.y = pk2(v0[2], v0[3]); w.z = pk2(v1[0], v1[1]); w.w = pk2(v1[2], v1[3]); *(u32x4*)(xb + blk(row, col0 + bj * HALF, D)) = w; } }
;                 if (MODE != 2) { s += __shfl_xor(s, 16); s += __shfl_xor(s, 32); if (fq == 0) unsafeAtomicAdd(ssq + row, s); } }
.LBB0_205:
	s_or_b64 exec, exec, s[48:49]
	v_or_b32_e32 v114, 16, v150
	s_waitcnt lgkmcnt(0)
	v_ashrrev_i32_e32 v115, 31, v114
	v_lshlrev_b64 v[116:117], 14, v[114:115]
	v_lshl_add_u64 v[116:117], s[8:9], 0, v[116:117]
	v_lshl_add_u64 v[120:121], v[148:149], 2, v[116:117]
	s_nop 1
	s_nop 1
	v_lshlrev_b32_e32 v128, 6, v114
	v_and_or_b32 v128, v128, s63, v158
	v_lshlrev_b32_e32 v128, 1, v128
	s_waitcnt vmcnt(12)
	v_mov_b32_e32 v116, v184
	v_mov_b32_e32 v117, v185
	v_mov_b32_e32 v118, v186
	v_mov_b32_e32 v119, v187
	global_load_dwordx4 v[184:187], v[176:177], off offset:528
	v_pk_fma_f32 v[118:119], v[112:113], 0.5, v[118:119] op_sel_hi:[1,0,1]
	v_pk_fma_f32 v[116:117], v[110:111], 0.5, v[116:117] op_sel_hi:[1,0,1]
	s_waitcnt vmcnt(12)
	v_mov_b32_e32 v124, v188
	v_mov_b32_e32 v125, v189
	v_mov_b32_e32 v126, v190
	v_mov_b32_e32 v127, v191
	v_lshl_add_u64 v[176:177], v[176:177], 0, s[100:101]
	global_load_dwordx4 v[188:191], v[176:177], off
	v_pk_fma_f32 v[126:127], v[108:109], 0.5, v[126:127] op_sel_hi:[1,0,1]
	v_pk_fma_f32 v[124:125], v[106:107], 0.5, v[124:125] op_sel_hi:[1,0,1]
	v_cvt_pk_bf16_f32 v106, v116, v117
	v_cvt_pk_bf16_f32 v107, v118, v119
	v_cvt_pk_bf16_f32 v108, v124, v125
	v_cvt_pk_bf16_f32 v109, v126, v127
	global_store_dwordx4 v128, v[106:109], s[44:45]
	s_nop 1
	s_nop 0
	s_nop 1
	v_mul_f32_e32 v117, v117, v117
	v_mul_f32_e32 v119, v119, v119
	v_mul_f32_e32 v120, v125, v125
	v_fmac_f32_e32 v117, v116, v116
	v_fmac_f32_e32 v119, v118, v118
	v_mul_f32_e32 v121, v127, v127
	v_fmac_f32_e32 v120, v124, v124
	v_add_f32_e32 v116, v117, v119
	v_fmac_f32_e32 v121, v126, v126
	v_add_f32_e32 v116, v120, v116
	v_add_f32_e32 v116, v121, v116
	s_waitcnt vmcnt(13)
	v_mov_b32_e32 v106, v196
	v_mov_b32_e32 v107, v197
	v_mov_b32_e32 v108, v198
	v_mov_b32_e32 v109, v199
	global_load_dwordx4 v[196:199], v[176:177], off offset:16
	v_pk_fma_f32 v[104:105], v[104:105], 0.5, v[108:109] op_sel_hi:[1,0,1]
	v_pk_fma_f32 v[102:103], v[102:103], 0.5, v[106:107] op_sel_hi:[1,0,1]
	s_waitcnt vmcnt(13)
	v_mov_b32_e32 v110, v200
	v_mov_b32_e32 v111, v201
	v_mov_b32_e32 v112, v202
	v_mov_b32_e32 v113, v203
	global_load_dwordx4 v[200:203], v[176:177], off offset:512
	v_pk_fma_f32 v[108:109], v[98:99], 0.5, v[110:111] op_sel_hi:[1,0,1]
	v_mul_f32_e32 v98, v103, v103
	v_mul_f32_e32 v99, v105, v105
	v_pk_fma_f32 v[106:107], v[100:101], 0.5, v[112:113] op_sel_hi:[1,0,1]
	v_mul_f32_e32 v100, v109, v109
	v_fmac_f32_e32 v98, v102, v102
	v_fmac_f32_e32 v99, v104, v104
	v_mul_f32_e32 v101, v107, v107
	v_fmac_f32_e32 v100, v108, v108
	v_add_f32_e32 v98, v98, v99
	v_add_f32_e32 v98, v100, v98
	v_fmac_f32_e32 v101, v106, v106
	v_add_f32_e32 v98, v101, v98
	v_add_f32_e32 v98, v116, v98
	ds_bpermute_b32 v99, v123, v98
	v_cvt_pk_bf16_f32 v100, v102, v103
	v_cvt_pk_bf16_f32 v101, v104, v105
	v_cvt_pk_bf16_f32 v102, v108, v109
	v_cvt_pk_bf16_f32 v103, v106, v107
	s_waitcnt lgkmcnt(0)
	v_add_f32_e32 v98, v98, v99
	ds_bpermute_b32 v99, v122, v98
	global_store_dwordx4 v128, v[100:103], s[46:47]
	s_and_saveexec_b64 s[48:49], s[0:1]
	s_cbranch_execz .LBB0_207
	v_lshl_add_u64 v[100:101], v[114:115], 2, s[10:11]
	s_waitcnt lgkmcnt(0)
	v_add_f32_e32 v98, v98, v99
	global_atomic_add_f32 v[100:101], v98, off
.LBB0_207:
	s_or_b64 exec, exec, s[48:49]
	v_or_b32_e32 v98, 32, v150
	s_waitcnt lgkmcnt(0)
	v_ashrrev_i32_e32 v99, 31, v98
	v_lshlrev_b64 v[100:101], 14, v[98:99]
	v_lshl_add_u64 v[100:101], s[8:9], 0, v[100:101]
	v_lshl_add_u64 v[108:109], v[148:149], 2, v[100:101]
	s_nop 1
	s_nop 1
	v_lshlrev_b32_e32 v110, 6, v98
	v_and_or_b32 v110, v110, s64, v158
	v_lshlrev_b32_e32 v110, 1, v110
	s_waitcnt vmcnt(14)
	v_mov_b32_e32 v100, v204
	v_mov_b32_e32 v101, v205
	v_mov_b32_e32 v102, v206
	v_mov_b32_e32 v103, v207
	global_load_dwordx4 v[204:207], v[176:177], off offset:528
	v_pk_fma_f32 v[102:103], v[96:97], 0.5, v[102:103] op_sel_hi:[1,0,1]
	v_pk_fma_f32 v[100:101], v[94:95], 0.5, v[100:101] op_sel_hi:[1,0,1]
	s_waitcnt vmcnt(14)
	v_mov_b32_e32 v104, v208
	v_mov_b32_e32 v105, v209
	v_mov_b32_e32 v106, v210
	v_mov_b32_e32 v107, v211
	v_lshl_add_u64 v[176:177], v[176:177], 0, s[98:99]
	global_load_dwordx4 v[208:211], v[176:177], off
	v_pk_fma_f32 v[106:107], v[92:93], 0.5, v[106:107] op_sel_hi:[1,0,1]
	v_pk_fma_f32 v[104:105], v[90:91], 0.5, v[104:105] op_sel_hi:[1,0,1]
	v_cvt_pk_bf16_f32 v90, v100, v101
	v_cvt_pk_bf16_f32 v91, v102, v103
	v_cvt_pk_bf16_f32 v92, v104, v105
	v_cvt_pk_bf16_f32 v93, v106, v107
	global_store_dwordx4 v110, v[90:93], s[44:45]
	s_nop 1
	s_nop 0
	s_nop 1
	v_mul_f32_e32 v101, v101, v101
	v_mul_f32_e32 v103, v103, v103
	v_mul_f32_e32 v105, v105, v105
	v_fmac_f32_e32 v101, v100, v100
	v_fmac_f32_e32 v103, v102, v102
	v_mul_f32_e32 v107, v107, v107
	v_fmac_f32_e32 v105, v104, v104
	v_add_f32_e32 v100, v101, v103
	v_fmac_f32_e32 v107, v106, v106
	v_add_f32_e32 v100, v105, v100
	v_add_f32_e32 v100, v107, v100
	s_waitcnt vmcnt(15)
	v_mov_b32_e32 v90, v212
	v_mov_b32_e32 v91, v213
	v_mov_b32_e32 v92, v214
	v_mov_b32_e32 v93, v215
	global_load_dwordx4 v[212:215], v[176:177], off offset:16
	v_pk_fma_f32 v[88:89], v[88:89], 0.5, v[92:93] op_sel_hi:[1,0,1]
	v_pk_fma_f32 v[86:87], v[86:87], 0.5, v[90:91] op_sel_hi:[1,0,1]
	s_waitcnt vmcnt(15)
	v_mov_b32_e32 v94, v216
	v_mov_b32_e32 v95, v217
	v_mov_b32_e32 v96, v218
	v_mov_b32_e32 v97, v219
	global_load_dwordx4 v[216:219], v[176:177], off offset:512
	v_pk_fma_f32 v[92:93], v[82:83], 0.5, v[94:95] op_sel_hi:[1,0,1]
	v_mul_f32_e32 v82, v87, v87
	v_mul_f32_e32 v83, v89, v89
	v_pk_fma_f32 v[90:91], v[84:85], 0.5, v[96:97] op_sel_hi:[1,0,1]
	v_mul_f32_e32 v84, v93, v93
	v_fmac_f32_e32 v82, v86, v86
	v_fmac_f32_e32 v83, v88, v88
	v_mul_f32_e32 v85, v91, v91
	v_fmac_f32_e32 v84, v92, v92
	v_add_f32_e32 v82, v82, v83
	v_add_f32_e32 v82, v84, v82
	v_fmac_f32_e32 v85, v90, v90
	v_add_f32_e32 v82, v85, v82
	v_add_f32_e32 v82, v100, v82
	ds_bpermute_b32 v83, v123, v82
	v_cvt_pk_bf16_f32 v84, v86, v87
	v_cvt_pk_bf16_f32 v85, v88, v89
	v_cvt_pk_bf16_f32 v86, v92, v93
	v_cvt_pk_bf16_f32 v87, v90, v91
	s_waitcnt lgkmcnt(0)
	v_add_f32_e32 v82, v82, v83
	ds_bpermute_b32 v83, v122, v82
	global_store_dwordx4 v110, v[84:87], s[46:47]
	s_and_saveexec_b64 s[48:49], s[0:1]
	s_cbranch_execz .LBB0_209
	v_lshl_add_u64 v[84:85], v[98:99], 2, s[10:11]
	s_waitcnt lgkmcnt(0)
	v_add_f32_e32 v82, v82, v83
	global_atomic_add_f32 v[84:85], v82, off
; __host__ __device__ __forceinline__ size_t blk(int r, int k, int K) { return (((size_t)((r >> 8) * (K >> 6) + (k >> 6))) << 14) + (size_t)(((r & 255) << 6) + (k & 63)); }
; __device__ __forceinline__ float bflo(unsigned w) { return __uint_as_float(w << 16); }
; __device__ __forceinline__ float bfhi(unsigned w) { return __uint_as_float(w & 0xffff0000u); }
; __device__ __forceinline__ unsigned pk2(float lo, float hi) { f32x2 v = {lo, hi}; bf16x2_t b = __builtin_convertvector(v, bf16x2_t); return __builtin_bit_cast(unsigned, b); }
;     __device__ __forceinline__ void operator()(const f32x4 (&acc)[2][2][4][2], const Unit& u, int wr, int wc, int fr, int fq) const {
;     ...
;             for (int m = 0; m < 4; ++m) { const int row = row0 + ai * HALF + m * 16; const size_t off = (size_t)row * D + col0; float s = 0.f;
; #pragma unroll
;                 for (int bj = 0; bj < 2; ++bj) {
;                     f32x4 v0, v1;
;                     if (MODE == 0) { v0 = *(const f32x4*)(base + off + bj * HALF); v1 = *(const f32x4*)(base + off + bj * HALF + 4); }
;                     else { const u32x4 r = *(const u32x4*)(bb + blk(row, col0 + bj * HALF, D)); v0 = (f32x4){bflo(r.x), bfhi(r.x), bflo(r.y), bfhi(r.y)}; v1 = (f32x4){bflo(r.z), bfhi(r.z), bflo(r.w), bfhi(r.w)}; }
;                     v0 += acc[ai][bj][m][0] * alpha; v1 += acc[ai][bj][m][1] * alpha;
;                     if (MODE == 2) { *(f32x4*)(out + off + bj * HALF) = v0; *(f32x4*)(out + off + bj * HALF + 4) = v1; }
;                     else {
;                         s += (v0[0] * v0[0] + v0[1] * v0[1]) + (v0[2] * v0[2] + v0[3] * v0[3]) + (v1[0] * v1[0] + v1[1] * v1[1]) + (v1[2] * v1[2] + v1[3] * v1[3]);
;                         u32x4 w; w.x = pk2(v0[0], v0[1]); w.y = pk2(v0[2], v0[3]); w.z = pk2(v1[0], v1[1]); w.w = pk2(v1[2], v1[3]); *(u32x4*)(xb + blk(row, col0 + bj * HALF, D)) = w; } }
;                 if (MODE != 2) { s += __shfl_xor(s, 16); s += __shfl_xor(s, 32); if (fq == 0) unsafeAtomicAdd(ssq + row, s); } }
.LBB0_209:
	s_or_b64 exec, exec, s[48:49]
	v_or_b32_e32 v82, 48, v150
	s_waitcnt lgkmcnt(0)
	v_ashrrev_i32_e32 v83, 31, v82
	v_lshlrev_b64 v[84:85], 14, v[82:83]
	v_lshl_add_u64 v[84:85], s[8:9], 0, v[84:85]
	v_lshl_add_u64 v[92:93], v[148:149], 2, v[84:85]
	s_nop 1
	s_nop 1
	v_lshlrev_b32_e32 v94, 6, v82
	v_and_or_b32 v94, v94, s65, v158
	v_lshlrev_b32_e32 v94, 1, v94
	s_waitcnt vmcnt(16)
	v_mov_b32_e32 v84, v220
	v_mov_b32_e32 v85, v221
	v_mov_b32_e32 v86, v222
	v_mov_b32_e32 v87, v223
	global_load_dwordx4 v[220:223], v[176:177], off offset:528
	v_pk_fma_f32 v[86:87], v[80:81], 0.5, v[86:87] op_sel_hi:[1,0,1]
	v_pk_fma_f32 v[84:85], v[78:79], 0.5, v[84:85] op_sel_hi:[1,0,1]
	s_waitcnt vmcnt(15)
	v_mov_b32_e32 v88, v172
	v_mov_b32_e32 v89, v173
	v_mov_b32_e32 v90, v174
	v_mov_b32_e32 v91, v175
	v_lshl_add_u64 v[176:177], v[176:177], 0, s[98:99]
	global_load_dwordx4 v[172:175], v[176:177], off
	v_pk_fma_f32 v[90:91], v[76:77], 0.5, v[90:91] op_sel_hi:[1,0,1]
	v_pk_fma_f32 v[88:89], v[74:75], 0.5, v[88:89] op_sel_hi:[1,0,1]
	v_cvt_pk_bf16_f32 v74, v84, v85
	v_cvt_pk_bf16_f32 v75, v86, v87
	v_cvt_pk_bf16_f32 v76, v88, v89
	v_cvt_pk_bf16_f32 v77, v90, v91
	global_store_dwordx4 v94, v[74:77], s[44:45]
	s_nop 1
	s_nop 0
	s_nop 1
	v_mul_f32_e32 v85, v85, v85
	v_mul_f32_e32 v87, v87, v87
	v_mul_f32_e32 v89, v89, v89
	v_fmac_f32_e32 v85, v84, v84
	v_fmac_f32_e32 v87, v86, v86
	v_mul_f32_e32 v91, v91, v91
	v_fmac_f32_e32 v89, v88, v88
	v_add_f32_e32 v84, v85, v87
	v_fmac_f32_e32 v91, v90, v90
	v_add_f32_e32 v84, v89, v84
	v_add_f32_e32 v84, v91, v84
	s_waitcnt vmcnt(16)
	v_mov_b32_e32 v74, v180
	v_mov_b32_e32 v75, v181
	v_mov_b32_e32 v76, v182
	v_mov_b32_e32 v77, v183
	global_load_dwordx4 v[180:183], v[176:177], off offset:16
	v_pk_fma_f32 v[72:73], v[72:73], 0.5, v[76:77] op_sel_hi:[1,0,1]
	v_pk_fma_f32 v[70:71], v[70:71], 0.5, v[74:75] op_sel_hi:[1,0,1]
	s_waitcnt vmcnt(15)
	v_mov_b32_e32 v78, v184
	v_mov_b32_e32 v79, v185
	v_mov_b32_e32 v80, v186
	v_mov_b32_e32 v81, v187
	global_load_dwordx4 v[184:187], v[176:177], off offset:512
	v_pk_fma_f32 v[76:77], v[66:67], 0.5, v[78:79] op_sel_hi:[1,0,1]
	v_mul_f32_e32 v66, v71, v71
	v_mul_f32_e32 v67, v73, v73
	v_pk_fma_f32 v[74:75], v[68:69], 0.5, v[80:81] op_sel_hi:[1,0,1]
	v_mul_f32_e32 v68, v77, v77
	v_fmac_f32_e32 v66, v70, v70
	v_fmac_f32_e32 v67, v72, v72
	v_mul_f32_e32 v69, v75, v75
	v_fmac_f32_e32 v68, v76, v76
	v_add_f32_e32 v66, v66, v67
	v_add_f32_e32 v66, v68, v66
	v_fmac_f32_e32 v69, v74, v74
	v_add_f32_e32 v66, v69, v66
	v_add_f32_e32 v66, v84, v66
	ds_bpermute_b32 v67, v123, v66
	v_cvt_pk_bf16_f32 v68, v70, v71
	v_cvt_pk_bf16_f32 v69, v72, v73
	v_cvt_pk_bf16_f32 v70, v76, v77
	v_cvt_pk_bf16_f32 v71, v74, v75
	s_waitcnt lgkmcnt(0)
	v_add_f32_e32 v66, v66, v67
	ds_bpermute_b32 v67, v122, v66
	global_store_dwordx4 v94, v[68:71], s[46:47]
	s_and_saveexec_b64 s[44:45], s[0:1]
	s_cbranch_execz .LBB0_211
	v_lshl_add_u64 v[68:69], v[82:83], 2, s[10:11]
	s_waitcnt lgkmcnt(0)
	v_add_f32_e32 v66, v66, v67
	global_atomic_add_f32 v[68:69], v66, off
.LBB0_211:
	s_or_b64 exec, exec, s[44:45]
	v_add_u32_e32 v68, 0x80, v150
	v_ashrrev_i32_e32 v69, 31, v68
	s_waitcnt lgkmcnt(0)
	v_lshlrev_b64 v[66:67], 14, v[68:69]
	v_lshl_add_u64 v[66:67], s[8:9], 0, v[66:67]
	v_lshl_add_u64 v[78:79], v[148:149], 2, v[66:67]
	s_nop 1
	s_nop 1
	v_ashrrev_i32_e32 v66, 2, v68
	v_lshlrev_b32_e32 v67, 6, v68
	v_and_b32_e32 v82, 0xffffffc0, v66
	v_and_or_b32 v67, v67, s62, v158
	v_add_u32_e32 v66, s50, v82
	v_lshlrev_b32_e32 v138, 1, v67
	v_ashrrev_i32_e32 v67, 31, v66
	v_lshlrev_b64 v[66:67], 15, v[66:67]
	v_lshl_add_u64 v[66:67], s[42:43], 0, v[66:67]
	v_lshl_add_u64 v[80:81], v[66:67], 0, v[138:139]
	s_waitcnt vmcnt(16)
	v_mov_b32_e32 v70, v188
	v_mov_b32_e32 v71, v189
	v_mov_b32_e32 v72, v190
	v_mov_b32_e32 v73, v191
	global_load_dwordx4 v[188:191], v[176:177], off offset:528
	v_pk_fma_f32 v[72:73], v[64:65], 0.5, v[72:73] op_sel_hi:[1,0,1]
	v_pk_fma_f32 v[70:71], v[62:63], 0.5, v[70:71] op_sel_hi:[1,0,1]
	s_waitcnt vmcnt(15)
	v_mov_b32_e32 v74, v196
	v_mov_b32_e32 v75, v197
	v_mov_b32_e32 v76, v198
	v_mov_b32_e32 v77, v199
	v_lshl_add_u64 v[176:177], v[176:177], 0, s[98:99]
	global_load_dwordx4 v[196:199], v[176:177], off
	v_pk_fma_f32 v[76:77], v[60:61], 0.5, v[76:77] op_sel_hi:[1,0,1]
	v_pk_fma_f32 v[74:75], v[58:59], 0.5, v[74:75] op_sel_hi:[1,0,1]
	v_cvt_pk_bf16_f32 v58, v70, v71
	v_cvt_pk_bf16_f32 v59, v72, v73
	v_cvt_pk_bf16_f32 v60, v74, v75
	v_cvt_pk_bf16_f32 v61, v76, v77
	global_store_dwordx4 v[80:81], v[58:61], off
	s_nop 1
	s_nop 0
	s_nop 1
	v_mul_f32_e32 v71, v71, v71
	v_mul_f32_e32 v73, v73, v73
	v_mul_f32_e32 v75, v75, v75
	v_fmac_f32_e32 v71, v70, v70
	v_fmac_f32_e32 v73, v72, v72
	v_mul_f32_e32 v77, v77, v77
	v_fmac_f32_e32 v75, v74, v74
	v_add_f32_e32 v70, v71, v73
	v_fmac_f32_e32 v77, v76, v76
	v_add_f32_e32 v70, v75, v70
	v_add_f32_e32 v70, v77, v70
	s_waitcnt vmcnt(16)
	v_mov_b32_e32 v58, v200
	v_mov_b32_e32 v59, v201
	v_mov_b32_e32 v60, v202
	v_mov_b32_e32 v61, v203
	global_load_dwordx4 v[200:203], v[176:177], off offset:16
	v_pk_fma_f32 v[56:57], v[56:57], 0.5, v[60:61] op_sel_hi:[1,0,1]
	v_pk_fma_f32 v[58:59], v[54:55], 0.5, v[58:59] op_sel_hi:[1,0,1]
	s_waitcnt vmcnt(15)
	v_mov_b32_e32 v62, v204
	v_mov_b32_e32 v63, v205
	v_mov_b32_e32 v64, v206
	v_mov_b32_e32 v65, v207
	global_load_dwordx4 v[204:207], v[176:177], off offset:512
	v_pk_fma_f32 v[50:51], v[50:51], 0.5, v[62:63] op_sel_hi:[1,0,1]
	v_mul_f32_e32 v55, v59, v59
	v_mul_f32_e32 v60, v57, v57
	v_pk_fma_f32 v[52:53], v[52:53], 0.5, v[64:65] op_sel_hi:[1,0,1]
	v_mul_f32_e32 v61, v51, v51
	v_fmac_f32_e32 v55, v58, v58
	v_fmac_f32_e32 v60, v56, v56
	v_mul_f32_e32 v62, v53, v53
	v_fmac_f32_e32 v61, v50, v50
	v_add_f32_e32 v55, v55, v60
	v_fmac_f32_e32 v62, v52, v52
	v_add_f32_e32 v55, v61, v55
	v_add_f32_e32 v55, v62, v55
	v_cvt_pk_bf16_f32 v54, v58, v59
	v_add_f32_e32 v58, v70, v55
	ds_bpermute_b32 v59, v123, v58
	v_cvt_pk_bf16_f32 v55, v56, v57
	v_cvt_pk_bf16_f32 v57, v52, v53
	v_cvt_pk_bf16_f32 v56, v50, v51
	v_add_u32_e32 v50, s51, v82
	s_waitcnt lgkmcnt(0)
	v_add_f32_e32 v52, v58, v59
	ds_bpermute_b32 v53, v122, v52
	v_ashrrev_i32_e32 v51, 31, v50
	v_lshlrev_b64 v[50:51], 15, v[50:51]
	v_lshl_add_u64 v[50:51], s[42:43], 0, v[50:51]
	v_lshl_add_u64 v[58:59], v[50:51], 0, v[138:139]
	global_store_dwordx4 v[58:59], v[54:57], off
	s_and_saveexec_b64 s[44:45], s[0:1]
	s_cbranch_execz .LBB0_213
	v_lshl_add_u64 v[54:55], v[68:69], 2, s[10:11]
	s_waitcnt lgkmcnt(0)
	v_add_f32_e32 v52, v52, v53
	global_atomic_add_f32 v[54:55], v52, off
; __host__ __device__ __forceinline__ size_t blk(int r, int k, int K) { return (((size_t)((r >> 8) * (K >> 6) + (k >> 6))) << 14) + (size_t)(((r & 255) << 6) + (k & 63)); }
; __device__ __forceinline__ float bflo(unsigned w) { return __uint_as_float(w << 16); }
; __device__ __forceinline__ float bfhi(unsigned w) { return __uint_as_float(w & 0xffff0000u); }
; __device__ __forceinline__ unsigned pk2(float lo, float hi) { f32x2 v = {lo, hi}; bf16x2_t b = __builtin_convertvector(v, bf16x2_t); return __builtin_bit_cast(unsigned, b); }
;     __device__ __forceinline__ void operator()(const f32x4 (&acc)[2][2][4][2], const Unit& u, int wr, int wc, int fr, int fq) const {
;     ...
;             for (int m = 0; m < 4; ++m) { const int row = row0 + ai * HALF + m * 16; const size_t off = (size_t)row * D + col0; float s = 0.f;
; #pragma unroll
;                 for (int bj = 0; bj < 2; ++bj) {
;                     f32x4 v0, v1;
;                     if (MODE == 0) { v0 = *(const f32x4*)(base + off + bj * HALF); v1 = *(const f32x4*)(base + off + bj * HALF + 4); }
;                     else { const u32x4 r = *(const u32x4*)(bb + blk(row, col0 + bj * HALF, D)); v0 = (f32x4){bflo(r.x), bfhi(r.x), bflo(r.y), bfhi(r.y)}; v1 = (f32x4){bflo(r.z), bfhi(r.z), bflo(r.w), bfhi(r.w)}; }
;                     v0 += acc[ai][bj][m][0] * alpha; v1 += acc[ai][bj][m][1] * alpha;
;                     if (MODE == 2) { *(f32x4*)(out + off + bj * HALF) = v0; *(f32x4*)(out + off + bj * HALF + 4) = v1; }
;                     else {
;                         s += (v0[0] * v0[0] + v0[1] * v0[1]) + (v0[2] * v0[2] + v0[3] * v0[3]) + (v1[0] * v1[0] + v1[1] * v1[1]) + (v1[2] * v1[2] + v1[3] * v1[3]);
;                         u32x4 w; w.x = pk2(v0[0], v0[1]); w.y = pk2(v0[2], v0[3]); w.z = pk2(v1[0], v1[1]); w.w = pk2(v1[2], v1[3]); *(u32x4*)(xb + blk(row, col0 + bj * HALF, D)) = w; } }
;                 if (MODE != 2) { s += __shfl_xor(s, 16); s += __shfl_xor(s, 32); if (fq == 0) unsafeAtomicAdd(ssq + row, s); } }
.LBB0_213:
	s_or_b64 exec, exec, s[44:45]
	v_add_u32_e32 v52, 0x90, v150
	s_waitcnt lgkmcnt(0)
	v_ashrrev_i32_e32 v53, 31, v52
	v_lshlrev_b64 v[54:55], 14, v[52:53]
	v_lshl_add_u64 v[54:55], s[8:9], 0, v[54:55]
	v_lshl_add_u64 v[62:63], v[148:149], 2, v[54:55]
	s_nop 1
	s_nop 1
	v_lshlrev_b32_e32 v64, 6, v52
	v_and_or_b32 v64, v64, s63, v158
	v_lshlrev_b32_e32 v138, 1, v64
	v_lshl_add_u64 v[64:65], v[66:67], 0, v[138:139]
	s_waitcnt vmcnt(16)
	v_mov_b32_e32 v54, v208
	v_mov_b32_e32 v55, v209
	v_mov_b32_e32 v56, v210
	v_mov_b32_e32 v57, v211
	global_load_dwordx4 v[208:211], v[176:177], off offset:528
	v_pk_fma_f32 v[56:57], v[48:49], 0.5, v[56:57] op_sel_hi:[1,0,1]
	v_pk_fma_f32 v[54:55], v[46:47], 0.5, v[54:55] op_sel_hi:[1,0,1]
	s_waitcnt vmcnt(15)
	v_mov_b32_e32 v58, v212
	v_mov_b32_e32 v59, v213
	v_mov_b32_e32 v60, v214
	v_mov_b32_e32 v61, v215
	v_pk_fma_f32 v[60:61], v[44:45], 0.5, v[60:61] op_sel_hi:[1,0,1]
	v_pk_fma_f32 v[58:59], v[42:43], 0.5, v[58:59] op_sel_hi:[1,0,1]
	v_cvt_pk_bf16_f32 v42, v54, v55
	v_cvt_pk_bf16_f32 v43, v56, v57
	v_cvt_pk_bf16_f32 v44, v58, v59
	v_cvt_pk_bf16_f32 v45, v60, v61
	global_store_dwordx4 v[64:65], v[42:45], off
	s_nop 1
	s_nop 0
	s_nop 1
	v_mul_f32_e32 v55, v55, v55
	v_mul_f32_e32 v57, v57, v57
	v_mul_f32_e32 v59, v59, v59
	v_fmac_f32_e32 v55, v54, v54
	v_fmac_f32_e32 v57, v56, v56
	v_mul_f32_e32 v61, v61, v61
	v_fmac_f32_e32 v59, v58, v58
	v_add_f32_e32 v54, v55, v57
	v_fmac_f32_e32 v61, v60, v60
	v_add_f32_e32 v54, v59, v54
	v_add_f32_e32 v54, v61, v54
	s_waitcnt vmcnt(15)
	v_mov_b32_e32 v42, v216
	v_mov_b32_e32 v43, v217
	v_mov_b32_e32 v44, v218
	v_mov_b32_e32 v45, v219
	v_pk_fma_f32 v[40:41], v[40:41], 0.5, v[44:45] op_sel_hi:[1,0,1]
	v_pk_fma_f32 v[38:39], v[38:39], 0.5, v[42:43] op_sel_hi:[1,0,1]
	s_waitcnt vmcnt(13)
	v_mov_b32_e32 v46, v220
	v_mov_b32_e32 v47, v221
	v_mov_b32_e32 v48, v222
	v_mov_b32_e32 v49, v223
	v_pk_fma_f32 v[44:45], v[34:35], 0.5, v[46:47] op_sel_hi:[1,0,1]
	v_mul_f32_e32 v34, v39, v39
	v_mul_f32_e32 v35, v41, v41
	v_pk_fma_f32 v[42:43], v[36:37], 0.5, v[48:49] op_sel_hi:[1,0,1]
	v_mul_f32_e32 v36, v45, v45
	v_fmac_f32_e32 v34, v38, v38
	v_fmac_f32_e32 v35, v40, v40
	v_mul_f32_e32 v37, v43, v43
	v_fmac_f32_e32 v36, v44, v44
	v_add_f32_e32 v34, v34, v35
	v_add_f32_e32 v34, v36, v34
	v_fmac_f32_e32 v37, v42, v42
	v_add_f32_e32 v34, v37, v34
	v_add_f32_e32 v34, v54, v34
	ds_bpermute_b32 v35, v123, v34
	v_cvt_pk_bf16_f32 v36, v38, v39
	v_cvt_pk_bf16_f32 v37, v40, v41
	v_cvt_pk_bf16_f32 v38, v44, v45
	v_cvt_pk_bf16_f32 v39, v42, v43
	s_waitcnt lgkmcnt(0)
	v_add_f32_e32 v34, v34, v35
	ds_bpermute_b32 v35, v122, v34
	v_lshl_add_u64 v[40:41], v[50:51], 0, v[138:139]
	global_store_dwordx4 v[40:41], v[36:39], off
	s_and_saveexec_b64 s[44:45], s[0:1]
	s_cbranch_execz .LBB0_215
	v_lshl_add_u64 v[36:37], v[52:53], 2, s[10:11]
	s_waitcnt lgkmcnt(0)
	v_add_f32_e32 v34, v34, v35
	global_atomic_add_f32 v[36:37], v34, off
; __host__ __device__ __forceinline__ size_t blk(int r, int k, int K) { return (((size_t)((r >> 8) * (K >> 6) + (k >> 6))) << 14) + (size_t)(((r & 255) << 6) + (k & 63)); }
; __device__ __forceinline__ float bflo(unsigned w) { return __uint_as_float(w << 16); }
; __device__ __forceinline__ float bfhi(unsigned w) { return __uint_as_float(w & 0xffff0000u); }
; __device__ __forceinline__ unsigned pk2(float lo, float hi) { f32x2 v = {lo, hi}; bf16x2_t b = __builtin_convertvector(v, bf16x2_t); return __builtin_bit_cast(unsigned, b); }
;     __device__ __forceinline__ void operator()(const f32x4 (&acc)[2][2][4][2], const Unit& u, int wr, int wc, int fr, int fq) const {
;     ...
;             for (int m = 0; m < 4; ++m) { const int row = row0 + ai * HALF + m * 16; const size_t off = (size_t)row * D + col0; float s = 0.f;
; #pragma unroll
;                 for (int bj = 0; bj < 2; ++bj) {
;                     f32x4 v0, v1;
;                     if (MODE == 0) { v0 = *(const f32x4*)(base + off + bj * HALF); v1 = *(const f32x4*)(base + off + bj * HALF + 4); }
;                     else { const u32x4 r = *(const u32x4*)(bb + blk(row, col0 + bj * HALF, D)); v0 = (f32x4){bflo(r.x), bfhi(r.x), bflo(r.y), bfhi(r.y)}; v1 = (f32x4){bflo(r.z), bfhi(r.z), bflo(r.w), bfhi(r.w)}; }
;                     v0 += acc[ai][bj][m][0] * alpha; v1 += acc[ai][bj][m][1] * alpha;
;                     if (MODE == 2) { *(f32x4*)(out + off + bj * HALF) = v0; *(f32x4*)(out + off + bj * HALF + 4) = v1; }
;                     else {
;                         s += (v0[0] * v0[0] + v0[1] * v0[1]) + (v0[2] * v0[2] + v0[3] * v0[3]) + (v1[0] * v1[0] + v1[1] * v1[1]) + (v1[2] * v1[2] + v1[3] * v1[3]);
;                         u32x4 w; w.x = pk2(v0[0], v0[1]); w.y = pk2(v0[2], v0[3]); w.z = pk2(v1[0], v1[1]); w.w = pk2(v1[2], v1[3]); *(u32x4*)(xb + blk(row, col0 + bj * HALF, D)) = w; } }
;                 if (MODE != 2) { s += __shfl_xor(s, 16); s += __shfl_xor(s, 32); if (fq == 0) unsafeAtomicAdd(ssq + row, s); } }
.LBB0_215:
	s_or_b64 exec, exec, s[44:45]
	v_add_u32_e32 v34, 0xa0, v150
	s_waitcnt lgkmcnt(0)
	v_ashrrev_i32_e32 v35, 31, v34
	v_lshlrev_b64 v[36:37], 14, v[34:35]
	v_lshl_add_u64 v[36:37], s[8:9], 0, v[36:37]
	v_lshl_add_u64 v[44:45], v[148:149], 2, v[36:37]
	s_nop 1
	s_nop 1
	v_lshlrev_b32_e32 v46, 6, v34
	v_and_or_b32 v46, v46, s64, v158
	v_lshlrev_b32_e32 v138, 1, v46
	v_lshl_add_u64 v[46:47], v[66:67], 0, v[138:139]
	s_waitcnt vmcnt(13)
	v_mov_b32_e32 v36, v172
	v_mov_b32_e32 v37, v173
	v_mov_b32_e32 v38, v174
	v_mov_b32_e32 v39, v175
	v_pk_fma_f32 v[38:39], v[32:33], 0.5, v[38:39] op_sel_hi:[1,0,1]
	v_pk_fma_f32 v[36:37], v[30:31], 0.5, v[36:37] op_sel_hi:[1,0,1]
	s_waitcnt vmcnt(11)
	v_mov_b32_e32 v40, v180
	v_mov_b32_e32 v41, v181
	v_mov_b32_e32 v42, v182
	v_mov_b32_e32 v43, v183
	v_pk_fma_f32 v[42:43], v[28:29], 0.5, v[42:43] op_sel_hi:[1,0,1]
	v_pk_fma_f32 v[40:41], v[26:27], 0.5, v[40:41] op_sel_hi:[1,0,1]
	v_cvt_pk_bf16_f32 v26, v36, v37
	v_cvt_pk_bf16_f32 v27, v38, v39
	v_cvt_pk_bf16_f32 v28, v40, v41
	v_cvt_pk_bf16_f32 v29, v42, v43
	global_store_dwordx4 v[46:47], v[26:29], off
	s_nop 1
	s_nop 0
	s_nop 1
	v_mul_f32_e32 v37, v37, v37
	v_mul_f32_e32 v39, v39, v39
	v_mul_f32_e32 v41, v41, v41
	v_fmac_f32_e32 v37, v36, v36
	v_fmac_f32_e32 v39, v38, v38
	v_mul_f32_e32 v43, v43, v43
	v_fmac_f32_e32 v41, v40, v40
	v_add_f32_e32 v36, v37, v39
	v_fmac_f32_e32 v43, v42, v42
	v_add_f32_e32 v36, v41, v36
	v_add_f32_e32 v36, v43, v36
	s_waitcnt vmcnt(11)
	v_mov_b32_e32 v26, v184
	v_mov_b32_e32 v27, v185
	v_mov_b32_e32 v28, v186
	v_mov_b32_e32 v29, v187
	v_pk_fma_f32 v[24:25], v[24:25], 0.5, v[28:29] op_sel_hi:[1,0,1]
	v_pk_fma_f32 v[22:23], v[22:23], 0.5, v[26:27] op_sel_hi:[1,0,1]
	s_waitcnt vmcnt(9)
	v_mov_b32_e32 v30, v188
	v_mov_b32_e32 v31, v189
	v_mov_b32_e32 v32, v190
	v_mov_b32_e32 v33, v191
	v_pk_fma_f32 v[28:29], v[18:19], 0.5, v[30:31] op_sel_hi:[1,0,1]
	v_mul_f32_e32 v18, v23, v23
	v_mul_f32_e32 v19, v25, v25
	v_pk_fma_f32 v[26:27], v[20:21], 0.5, v[32:33] op_sel_hi:[1,0,1]
	v_mul_f32_e32 v20, v29, v29
	v_fmac_f32_e32 v18, v22, v22
	v_fmac_f32_e32 v19, v24, v24
	v_mul_f32_e32 v21, v27, v27
	v_fmac_f32_e32 v20, v28, v28
	v_add_f32_e32 v18, v18, v19
	v_add_f32_e32 v18, v20, v18
	v_fmac_f32_e32 v21, v26, v26
	v_add_f32_e32 v18, v21, v18
	v_add_f32_e32 v18, v36, v18
	ds_bpermute_b32 v19, v123, v18
	v_cvt_pk_bf16_f32 v20, v22, v23
	v_cvt_pk_bf16_f32 v21, v24, v25
	v_cvt_pk_bf16_f32 v22, v28, v29
	v_cvt_pk_bf16_f32 v23, v26, v27
	s_waitcnt lgkmcnt(0)
	v_add_f32_e32 v18, v18, v19
	ds_bpermute_b32 v19, v122, v18
	v_lshl_add_u64 v[24:25], v[50:51], 0, v[138:139]
	global_store_dwordx4 v[24:25], v[20:23], off
	s_and_saveexec_b64 s[44:45], s[0:1]
	s_cbranch_execz .LBB0_217
	v_lshl_add_u64 v[20:21], v[34:35], 2, s[10:11]
	s_waitcnt lgkmcnt(0)
	v_add_f32_e32 v18, v18, v19
	global_atomic_add_f32 v[20:21], v18, off
.LBB0_217:
	s_or_b64 exec, exec, s[44:45]
	v_add_u32_e32 v18, 0xb0, v150
	s_waitcnt lgkmcnt(0)
	v_ashrrev_i32_e32 v19, 31, v18
	v_lshlrev_b64 v[20:21], 14, v[18:19]
	v_lshl_add_u64 v[20:21], s[8:9], 0, v[20:21]
	v_lshl_add_u64 v[28:29], v[148:149], 2, v[20:21]
	s_nop 1
	s_nop 1
	v_lshlrev_b32_e32 v30, 6, v18
	v_and_or_b32 v30, v30, s65, v158
	v_lshlrev_b32_e32 v138, 1, v30
	v_lshl_add_u64 v[30:31], v[66:67], 0, v[138:139]
	s_waitcnt vmcnt(9)
	v_mov_b32_e32 v20, v196
	v_mov_b32_e32 v21, v197
	v_mov_b32_e32 v22, v198
	v_mov_b32_e32 v23, v199
	v_pk_fma_f32 v[22:23], v[16:17], 0.5, v[22:23] op_sel_hi:[1,0,1]
	v_pk_fma_f32 v[20:21], v[14:15], 0.5, v[20:21] op_sel_hi:[1,0,1]
	s_waitcnt vmcnt(7)
	v_mov_b32_e32 v24, v200
	v_mov_b32_e32 v25, v201
	v_mov_b32_e32 v26, v202
	v_mov_b32_e32 v27, v203
	v_pk_fma_f32 v[26:27], v[12:13], 0.5, v[26:27] op_sel_hi:[1,0,1]
	v_pk_fma_f32 v[24:25], v[10:11], 0.5, v[24:25] op_sel_hi:[1,0,1]
	v_cvt_pk_bf16_f32 v10, v20, v21
	v_cvt_pk_bf16_f32 v11, v22, v23
	v_cvt_pk_bf16_f32 v12, v24, v25
	v_cvt_pk_bf16_f32 v13, v26, v27
	global_store_dwordx4 v[30:31], v[10:13], off
	s_nop 1
	s_nop 0
	s_nop 1
	v_mul_f32_e32 v21, v21, v21
	v_mul_f32_e32 v23, v23, v23
	v_mul_f32_e32 v25, v25, v25
	v_fmac_f32_e32 v21, v20, v20
	v_fmac_f32_e32 v23, v22, v22
	v_mul_f32_e32 v27, v27, v27
	v_fmac_f32_e32 v25, v24, v24
	v_add_f32_e32 v20, v21, v23
	v_fmac_f32_e32 v27, v26, v26
	v_add_f32_e32 v20, v25, v20
	v_add_f32_e32 v20, v27, v20
	s_waitcnt vmcnt(7)
	v_mov_b32_e32 v10, v204
	v_mov_b32_e32 v11, v205
	v_mov_b32_e32 v12, v206
	v_mov_b32_e32 v13, v207
	v_pk_fma_f32 v[8:9], v[8:9], 0.5, v[12:13] op_sel_hi:[1,0,1]
	v_pk_fma_f32 v[6:7], v[6:7], 0.5, v[10:11] op_sel_hi:[1,0,1]
	s_waitcnt vmcnt(5)
	v_mov_b32_e32 v14, v208
	v_mov_b32_e32 v15, v209
	v_mov_b32_e32 v16, v210
	v_mov_b32_e32 v17, v211
	v_pk_fma_f32 v[12:13], v[2:3], 0.5, v[14:15] op_sel_hi:[1,0,1]
	v_mul_f32_e32 v2, v7, v7
	v_mul_f32_e32 v3, v9, v9
	v_pk_fma_f32 v[10:11], v[4:5], 0.5, v[16:17] op_sel_hi:[1,0,1]
	v_mul_f32_e32 v4, v13, v13
	v_fmac_f32_e32 v2, v6, v6
	v_fmac_f32_e32 v3, v8, v8
	v_mul_f32_e32 v5, v11, v11
	v_fmac_f32_e32 v4, v12, v12
	v_add_f32_e32 v2, v2, v3
	v_add_f32_e32 v2, v4, v2
	v_fmac_f32_e32 v5, v10, v10
	v_add_f32_e32 v2, v5, v2
	v_add_f32_e32 v2, v20, v2
	ds_bpermute_b32 v3, v123, v2
	v_cvt_pk_bf16_f32 v4, v6, v7
	v_cvt_pk_bf16_f32 v5, v8, v9
	v_cvt_pk_bf16_f32 v6, v12, v13
	v_cvt_pk_bf16_f32 v7, v10, v11
	s_waitcnt lgkmcnt(0)
	v_add_f32_e32 v2, v2, v3
	ds_bpermute_b32 v3, v122, v2
	v_lshl_add_u64 v[8:9], v[50:51], 0, v[138:139]
	global_store_dwordx4 v[8:9], v[4:7], off
	s_and_saveexec_b64 s[44:45], s[0:1]
	s_cbranch_execz .LBB0_219
	v_lshl_add_u64 v[4:5], v[18:19], 2, s[10:11]
	s_waitcnt lgkmcnt(0)
	v_add_f32_e32 v2, v2, v3
	global_atomic_add_f32 v[4:5], v2, off

; #define PG8_STAGE(bufoff, gbase, voff) do { _Pragma("unroll") for (int _i = 0; _i < 2; ++_i) \
;         __builtin_amdgcn_global_load_lds((const unsigned*)((const char*)(gbase) + (voff)[_i]), (PG8_LAS unsigned*)(lds + (bufoff) + ldsw + _i * 8192), 16, 0, 0); } while (0)
; #define PG8_LDA(dst, b, h) do { _Pragma("unroll") for (int m = 0; m < 4; ++m) _Pragma("unroll") for (int k = 0; k < 2; ++k) dst[m][k] = *(const PG8_LAS bf16x8*)(lds + PG8_SA(b, h) + aoff + m * 2048 + k * 1024); } while (0)
; #define PG8_LDB(dst, b, h) do { _Pragma("unroll") for (int n = 0; n < 2; ++n) _Pragma("unroll") for (int k = 0; k < 2; ++k) dst[n][k] = *(const PG8_LAS bf16x8*)(lds + PG8_SB(b, h) + boff + n * 2048 + k * 1024); } while (0)
; #define PG8_MMA(ai, bj, At, Bt) do { __builtin_amdgcn_s_setprio(1); _Pragma("unroll") for (int m = 0; m < 4; ++m) _Pragma("unroll") for (int n = 0; n < 2; ++n) _Pragma("unroll") for (int k = 0; k < 2; ++k) \
;         acc[ai][bj][m][n] = __builtin_amdgcn_mfma_f32_16x16x32_bf16(Bt[n][k], At[m][k], acc[ai][bj][m][n], 0, 0, 0); __builtin_amdgcn_s_setprio(0); } while (0)
; #define PG8_WAIT_V(n) asm volatile("s_waitcnt vmcnt(" #n ")" ::: "memory")
; #define PG8_WAIT_L(n) asm volatile("s_waitcnt lgkmcnt(" #n ")" ::: "memory")
; #define PG8_BAR __builtin_amdgcn_s_barrier()
; #define PG8_SCHED __builtin_amdgcn_sched_barrier(0)
; template <class Epi, class Sched, bool ALIGN_EPI = false, bool SP2 = false>
; __device__ __forceinline__ void gemm_phase(PG8_LAS unsigned char* lds, const Gemm g, const Sched& S, const Epi& E) {
;     ...
;             PG8_LDB(B0, 0, 0); PG8_LDB(B1, 0, 1); PG8_SCHED; PG8_LDA(At, 0, 0); PG8_STAGE(PG8_SA(1, 1), a1 + hstep, voffA);
;             PG8_WAIT_V(8); PG8_WAIT_L(0); PG8_BAR; PG8_MMA(0, 0, At, B0); PG8_MMA(0, 1, At, B1); PG8_BAR; PG8_SCHED;
;             PG8_LDA(At, 0, 1); PG8_STAGE(PG8_SB(0, 0), b2, voffB); PG8_STAGE(PG8_SB(0, 1), b2 + hstep, voffB); PG8_STAGE(PG8_SA(0, 0), a2, voffA);
;             PG8_WAIT_V(8); PG8_WAIT_L(0); PG8_BAR; PG8_MMA(1, 0, At, B0); PG8_MMA(1, 1, At, B1); PG8_BAR; PG8_SCHED;
.LBB0_682:
	ds_read_b128 v[166:169], v163
	ds_read_b128 v[170:173], v163 offset:1024
	ds_read_b128 v[174:177], v163 offset:2048
	ds_read_b128 v[180:183], v163 offset:3072
	ds_read_b128 v[184:187], v164
	ds_read_b128 v[188:191], v164 offset:1024
	ds_read_b128 v[198:201], v164 offset:2048
	ds_read_b128 v[202:205], v164 offset:3072
	v_lshl_add_u64 v[242:243], v[130:131], 0, s[44:45]
	s_add_i32 s83, s29, 0xc000
	v_lshl_add_u64 v[238:239], v[242:243], 0, s[10:11]
	s_mov_b32 m0, s83
	v_lshl_add_u64 v[244:245], v[132:133], 0, s[44:45]
	s_add_i32 s84, s29, 0xe000
	ds_read_b128 v[206:209], v165
	ds_read_b128 v[210:213], v165 offset:1024
	ds_read_b128 v[214:217], v165 offset:2048
	ds_read_b128 v[218:221], v165 offset:3072
	ds_read_b128 v[222:225], v165 offset:4096
	ds_read_b128 v[226:229], v165 offset:5120
	ds_read_b128 v[230:233], v165 offset:6144
	ds_read_b128 v[234:237], v165 offset:7168
	global_load_lds_dwordx4 v[238:239], off
	v_lshl_add_u64 v[238:239], v[244:245], 0, s[10:11]
	s_mov_b32 m0, s84
	s_nop 0
	global_load_lds_dwordx4 v[238:239], off
	s_waitcnt vmcnt(8)
	s_waitcnt lgkmcnt(0)
	s_barrier
	s_setprio 1
	s_waitcnt lgkmcnt(0)
	v_mfma_f32_16x16x32_bf16 v[14:17], v[166:169], v[206:209], v[14:17]
	v_mfma_f32_16x16x32_bf16 v[10:13], v[174:177], v[206:209], v[10:13]
	v_mfma_f32_16x16x32_bf16 v[38:41], v[166:169], v[214:217], v[38:41]
	v_mfma_f32_16x16x32_bf16 v[34:37], v[174:177], v[214:217], v[34:37]
	v_mfma_f32_16x16x32_bf16 v[70:73], v[166:169], v[222:225], v[70:73]
	v_mfma_f32_16x16x32_bf16 v[66:69], v[174:177], v[222:225], v[66:69]
	v_mfma_f32_16x16x32_bf16 v[94:97], v[166:169], v[230:233], v[94:97]
	v_mfma_f32_16x16x32_bf16 v[90:93], v[174:177], v[230:233], v[90:93]
	v_mfma_f32_16x16x32_bf16 v[14:17], v[170:173], v[210:213], v[14:17]
	v_mfma_f32_16x16x32_bf16 v[10:13], v[180:183], v[210:213], v[10:13]
	v_mfma_f32_16x16x32_bf16 v[38:41], v[170:173], v[218:221], v[38:41]
	v_mfma_f32_16x16x32_bf16 v[34:37], v[180:183], v[218:221], v[34:37]
	v_mfma_f32_16x16x32_bf16 v[70:73], v[170:173], v[226:229], v[70:73]
	v_mfma_f32_16x16x32_bf16 v[66:69], v[180:183], v[226:229], v[66:69]
	v_mfma_f32_16x16x32_bf16 v[94:97], v[170:173], v[234:237], v[94:97]
	v_mfma_f32_16x16x32_bf16 v[90:93], v[180:183], v[234:237], v[90:93]
	s_setprio 0
	s_setprio 1
	v_mfma_f32_16x16x32_bf16 v[30:33], v[184:187], v[206:209], v[30:33]
	v_mfma_f32_16x16x32_bf16 v[26:29], v[198:201], v[206:209], v[26:29]
	v_mfma_f32_16x16x32_bf16 v[54:57], v[184:187], v[214:217], v[54:57]
	v_mfma_f32_16x16x32_bf16 v[50:53], v[198:201], v[214:217], v[50:53]
	v_mfma_f32_16x16x32_bf16 v[86:89], v[184:187], v[222:225], v[86:89]
	v_mfma_f32_16x16x32_bf16 v[82:85], v[198:201], v[222:225], v[82:85]
	v_mfma_f32_16x16x32_bf16 v[110:113], v[184:187], v[230:233], v[110:113]
	v_mfma_f32_16x16x32_bf16 v[106:109], v[198:201], v[230:233], v[106:109]
	v_mfma_f32_16x16x32_bf16 v[30:33], v[188:191], v[210:213], v[30:33]
	v_mfma_f32_16x16x32_bf16 v[26:29], v[202:205], v[210:213], v[26:29]
	v_mfma_f32_16x16x32_bf16 v[54:57], v[188:191], v[218:221], v[54:57]
	v_mfma_f32_16x16x32_bf16 v[50:53], v[202:205], v[218:221], v[50:53]
	v_mfma_f32_16x16x32_bf16 v[86:89], v[188:191], v[226:229], v[86:89]
	v_mfma_f32_16x16x32_bf16 v[82:85], v[202:205], v[226:229], v[82:85]
	v_mfma_f32_16x16x32_bf16 v[110:113], v[188:191], v[234:237], v[110:113]
	v_mfma_f32_16x16x32_bf16 v[106:109], v[202:205], v[234:237], v[106:109]
	s_setprio 0
	s_barrier
	v_lshl_add_u64 v[246:247], v[156:157], 0, s[44:45]
	s_add_i32 s85, s80, s28
	v_lshl_add_u64 v[238:239], v[246:247], 0, s[14:15]
	s_mov_b32 m0, s85
	v_lshl_add_u64 v[248:249], v[158:159], 0, s[44:45]
	s_add_i32 s86, s85, 0x2000
	ds_read_b128 v[206:209], v165 offset:16384
	ds_read_b128 v[210:213], v165 offset:17408
	ds_read_b128 v[214:217], v165 offset:18432
	ds_read_b128 v[218:221], v165 offset:19456
	ds_read_b128 v[222:225], v165 offset:20480
	ds_read_b128 v[226:229], v165 offset:21504
	ds_read_b128 v[230:233], v165 offset:22528
	ds_read_b128 v[234:237], v165 offset:23552
	global_load_lds_dwordx4 v[238:239], off
	v_lshl_add_u64 v[238:239], v[248:249], 0, s[14:15]
	s_mov_b32 m0, s86
	s_add_i32 s87, s81, s28
	global_load_lds_dwordx4 v[238:239], off
	v_lshl_add_u64 v[238:239], v[246:247], 0, s[16:17]
	s_mov_b32 m0, s87
	s_add_i32 s88, s87, 0x2000
	global_load_lds_dwordx4 v[238:239], off
	v_lshl_add_u64 v[238:239], v[248:249], 0, s[16:17]
	s_mov_b32 m0, s88
	s_nop 0
	global_load_lds_dwordx4 v[238:239], off
	v_lshl_add_u64 v[238:239], v[242:243], 0, s[14:15]
	s_mov_b32 m0, s29
	s_nop 0
	global_load_lds_dwordx4 v[238:239], off
	v_lshl_add_u64 v[238:239], v[244:245], 0, s[14:15]
	s_mov_b32 m0, s30
	s_nop 0
	global_load_lds_dwordx4 v[238:239], off
	s_waitcnt vmcnt(8)
	s_waitcnt lgkmcnt(0)
	s_barrier
; #define PG8_STAGE(bufoff, gbase, voff) do { _Pragma("unroll") for (int _i = 0; _i < 2; ++_i) \
;         __builtin_amdgcn_global_load_lds((const unsigned*)((const char*)(gbase) + (voff)[_i]), (PG8_LAS unsigned*)(lds + (bufoff) + ldsw + _i * 8192), 16, 0, 0); } while (0)
; #define PG8_LDA(dst, b, h) do { _Pragma("unroll") for (int m = 0; m < 4; ++m) _Pragma("unroll") for (int k = 0; k < 2; ++k) dst[m][k] = *(const PG8_LAS bf16x8*)(lds + PG8_SA(b, h) + aoff + m * 2048 + k * 1024); } while (0)
; #define PG8_LDB(dst, b, h) do { _Pragma("unroll") for (int n = 0; n < 2; ++n) _Pragma("unroll") for (int k = 0; k < 2; ++k) dst[n][k] = *(const PG8_LAS bf16x8*)(lds + PG8_SB(b, h) + boff + n * 2048 + k * 1024); } while (0)
; #define PG8_MMA(ai, bj, At, Bt) do { __builtin_amdgcn_s_setprio(1); _Pragma("unroll") for (int m = 0; m < 4; ++m) _Pragma("unroll") for (int n = 0; n < 2; ++n) _Pragma("unroll") for (int k = 0; k < 2; ++k) \
;         acc[ai][bj][m][n] = __builtin_amdgcn_mfma_f32_16x16x32_bf16(Bt[n][k], At[m][k], acc[ai][bj][m][n], 0, 0, 0); __builtin_amdgcn_s_setprio(0); } while (0)
; #define PG8_WAIT_V(n) asm volatile("s_waitcnt vmcnt(" #n ")" ::: "memory")
; #define PG8_WAIT_L(n) asm volatile("s_waitcnt lgkmcnt(" #n ")" ::: "memory")
; #define PG8_BAR __builtin_amdgcn_s_barrier()
; #define PG8_SCHED __builtin_amdgcn_sched_barrier(0)
; template <class Epi, class Sched, bool ALIGN_EPI = false, bool SP2 = false>
; __device__ __forceinline__ void gemm_phase(PG8_LAS unsigned char* lds, const Gemm g, const Sched& S, const Epi& E) {
;     ...
;             PG8_LDA(At, 0, 1); PG8_STAGE(PG8_SB(0, 0), b2, voffB); PG8_STAGE(PG8_SB(0, 1), b2 + hstep, voffB); PG8_STAGE(PG8_SA(0, 0), a2, voffA);
;             PG8_WAIT_V(8); PG8_WAIT_L(0); PG8_BAR; PG8_MMA(1, 0, At, B0); PG8_MMA(1, 1, At, B1); PG8_BAR; PG8_SCHED;
;             PG8_LDB(B0, 1, 0); PG8_LDB(B1, 1, 1); PG8_SCHED; PG8_LDA(At, 1, 0); PG8_STAGE(PG8_SA(0, 1), a2 + hstep, voffA);
;             PG8_WAIT_V(8); PG8_WAIT_L(0); PG8_BAR; PG8_MMA(0, 0, At, B0); PG8_MMA(0, 1, At, B1); PG8_BAR; PG8_SCHED;
	s_setprio 1
	s_waitcnt lgkmcnt(0)
	v_mfma_f32_16x16x32_bf16 v[126:129], v[166:169], v[206:209], v[126:129]
	v_mfma_f32_16x16x32_bf16 v[122:125], v[174:177], v[206:209], v[122:125]
	v_mfma_f32_16x16x32_bf16 v[102:105], v[166:169], v[214:217], v[102:105]
	v_mfma_f32_16x16x32_bf16 v[98:101], v[174:177], v[214:217], v[98:101]
	v_mfma_f32_16x16x32_bf16 v[62:65], v[166:169], v[222:225], v[62:65]
	v_mfma_f32_16x16x32_bf16 v[58:61], v[174:177], v[222:225], v[58:61]
	v_mfma_f32_16x16x32_bf16 v[22:25], v[166:169], v[230:233], v[22:25]
	v_mfma_f32_16x16x32_bf16 v[18:21], v[174:177], v[230:233], v[18:21]
	v_mfma_f32_16x16x32_bf16 v[126:129], v[170:173], v[210:213], v[126:129]
	v_mfma_f32_16x16x32_bf16 v[122:125], v[180:183], v[210:213], v[122:125]
	v_mfma_f32_16x16x32_bf16 v[102:105], v[170:173], v[218:221], v[102:105]
	v_mfma_f32_16x16x32_bf16 v[98:101], v[180:183], v[218:221], v[98:101]
	v_mfma_f32_16x16x32_bf16 v[62:65], v[170:173], v[226:229], v[62:65]
	v_mfma_f32_16x16x32_bf16 v[58:61], v[180:183], v[226:229], v[58:61]
	v_mfma_f32_16x16x32_bf16 v[22:25], v[170:173], v[234:237], v[22:25]
	v_mfma_f32_16x16x32_bf16 v[18:21], v[180:183], v[234:237], v[18:21]
	s_setprio 0
	s_setprio 1
	v_mfma_f32_16x16x32_bf16 v[118:121], v[184:187], v[206:209], v[118:121]
	v_mfma_f32_16x16x32_bf16 v[114:117], v[198:201], v[206:209], v[114:117]
	v_mfma_f32_16x16x32_bf16 v[78:81], v[184:187], v[214:217], v[78:81]
	v_mfma_f32_16x16x32_bf16 v[74:77], v[198:201], v[214:217], v[74:77]
	v_mfma_f32_16x16x32_bf16 v[46:49], v[184:187], v[222:225], v[46:49]
	v_mfma_f32_16x16x32_bf16 v[42:45], v[198:201], v[222:225], v[42:45]
	v_mfma_f32_16x16x32_bf16 v[6:9], v[184:187], v[230:233], v[6:9]
	v_mfma_f32_16x16x32_bf16 v[2:5], v[198:201], v[230:233], v[2:5]
	v_mfma_f32_16x16x32_bf16 v[118:121], v[188:191], v[210:213], v[118:121]
	v_mfma_f32_16x16x32_bf16 v[114:117], v[202:205], v[210:213], v[114:117]
	v_mfma_f32_16x16x32_bf16 v[78:81], v[188:191], v[218:221], v[78:81]
	v_mfma_f32_16x16x32_bf16 v[74:77], v[202:205], v[218:221], v[74:77]
	v_mfma_f32_16x16x32_bf16 v[46:49], v[188:191], v[226:229], v[46:49]
	v_mfma_f32_16x16x32_bf16 v[42:45], v[202:205], v[226:229], v[42:45]
	v_mfma_f32_16x16x32_bf16 v[6:9], v[188:191], v[234:237], v[6:9]
	v_mfma_f32_16x16x32_bf16 v[2:5], v[202:205], v[234:237], v[2:5]
	s_setprio 0
	s_barrier
	s_add_i32 s89, 0, 0x18000
	s_add_i32 s91, 0, 0x1c000
	v_add_u32_e32 v142, s89, v161
	v_add_u32_e32 v167, s91, v161
	ds_read_b128 v[168:171], v142
	ds_read_b128 v[172:175], v142 offset:1024
	ds_read_b128 v[180:183], v142 offset:2048
	ds_read_b128 v[184:187], v142 offset:3072
	ds_read_b128 v[188:191], v167
	ds_read_b128 v[198:201], v167 offset:1024
	ds_read_b128 v[202:205], v167 offset:2048
	ds_read_b128 v[206:209], v167 offset:3072
	s_mov_b32 m0, s31
	v_lshl_add_u64 v[176:177], v[242:243], 0, s[16:17]
	ds_read_b128 v[210:213], v165 offset:32768
	ds_read_b128 v[214:217], v165 offset:33792
	ds_read_b128 v[218:221], v165 offset:34816
	ds_read_b128 v[222:225], v165 offset:35840
	ds_read_b128 v[226:229], v165 offset:36864
	ds_read_b128 v[230:233], v165 offset:37888
	ds_read_b128 v[234:237], v165 offset:38912
	ds_read_b128 v[238:241], v165 offset:39936
	global_load_lds_dwordx4 v[176:177], off
	v_lshl_add_u64 v[176:177], v[244:245], 0, s[16:17]
	s_mov_b32 m0, s35
	s_nop 0
	global_load_lds_dwordx4 v[176:177], off
	s_waitcnt vmcnt(8)
	s_waitcnt lgkmcnt(0)
	s_barrier
	s_setprio 1
	s_waitcnt lgkmcnt(0)
	v_mfma_f32_16x16x32_bf16 v[14:17], v[168:171], v[210:213], v[14:17]
	v_mfma_f32_16x16x32_bf16 v[10:13], v[180:183], v[210:213], v[10:13]
	v_mfma_f32_16x16x32_bf16 v[38:41], v[168:171], v[218:221], v[38:41]
	v_mfma_f32_16x16x32_bf16 v[34:37], v[180:183], v[218:221], v[34:37]
	v_mfma_f32_16x16x32_bf16 v[70:73], v[168:171], v[226:229], v[70:73]
	v_mfma_f32_16x16x32_bf16 v[66:69], v[180:183], v[226:229], v[66:69]
	v_mfma_f32_16x16x32_bf16 v[94:97], v[168:171], v[234:237], v[94:97]
	v_mfma_f32_16x16x32_bf16 v[90:93], v[180:183], v[234:237], v[90:93]
	v_mfma_f32_16x16x32_bf16 v[14:17], v[172:175], v[214:217], v[14:17]
	v_mfma_f32_16x16x32_bf16 v[10:13], v[184:187], v[214:217], v[10:13]
	v_mfma_f32_16x16x32_bf16 v[38:41], v[172:175], v[222:225], v[38:41]
	v_mfma_f32_16x16x32_bf16 v[34:37], v[184:187], v[222:225], v[34:37]
	v_mfma_f32_16x16x32_bf16 v[70:73], v[172:175], v[230:233], v[70:73]
	v_mfma_f32_16x16x32_bf16 v[66:69], v[184:187], v[230:233], v[66:69]
	v_mfma_f32_16x16x32_bf16 v[94:97], v[172:175], v[238:241], v[94:97]
	v_mfma_f32_16x16x32_bf16 v[90:93], v[184:187], v[238:241], v[90:93]
	s_setprio 0
	s_setprio 1
	v_mfma_f32_16x16x32_bf16 v[30:33], v[188:191], v[210:213], v[30:33]
	v_mfma_f32_16x16x32_bf16 v[26:29], v[202:205], v[210:213], v[26:29]
	v_mfma_f32_16x16x32_bf16 v[54:57], v[188:191], v[218:221], v[54:57]
	v_mfma_f32_16x16x32_bf16 v[50:53], v[202:205], v[218:221], v[50:53]
	v_mfma_f32_16x16x32_bf16 v[86:89], v[188:191], v[226:229], v[86:89]
	v_mfma_f32_16x16x32_bf16 v[82:85], v[202:205], v[226:229], v[82:85]
	v_mfma_f32_16x16x32_bf16 v[110:113], v[188:191], v[234:237], v[110:113]
	v_mfma_f32_16x16x32_bf16 v[106:109], v[202:205], v[234:237], v[106:109]
	v_mfma_f32_16x16x32_bf16 v[30:33], v[198:201], v[214:217], v[30:33]
	v_mfma_f32_16x16x32_bf16 v[26:29], v[206:209], v[214:217], v[26:29]
	v_mfma_f32_16x16x32_bf16 v[54:57], v[198:201], v[222:225], v[54:57]
	v_mfma_f32_16x16x32_bf16 v[50:53], v[206:209], v[222:225], v[50:53]
	v_mfma_f32_16x16x32_bf16 v[86:89], v[198:201], v[230:233], v[86:89]
	v_mfma_f32_16x16x32_bf16 v[82:85], v[206:209], v[230:233], v[82:85]
	v_mfma_f32_16x16x32_bf16 v[110:113], v[198:201], v[238:241], v[110:113]
	v_mfma_f32_16x16x32_bf16 v[106:109], v[206:209], v[238:241], v[106:109]
	s_setprio 0
	s_barrier
; #define PG8_STAGE(bufoff, gbase, voff) do { _Pragma("unroll") for (int _i = 0; _i < 2; ++_i) \
;         __builtin_amdgcn_global_load_lds((const unsigned*)((const char*)(gbase) + (voff)[_i]), (PG8_LAS unsigned*)(lds + (bufoff) + ldsw + _i * 8192), 16, 0, 0); } while (0)
; #define PG8_LDA(dst, b, h) do { _Pragma("unroll") for (int m = 0; m < 4; ++m) _Pragma("unroll") for (int k = 0; k < 2; ++k) dst[m][k] = *(const PG8_LAS bf16x8*)(lds + PG8_SA(b, h) + aoff + m * 2048 + k * 1024); } while (0)
; #define PG8_LDB(dst, b, h) do { _Pragma("unroll") for (int n = 0; n < 2; ++n) _Pragma("unroll") for (int k = 0; k < 2; ++k) dst[n][k] = *(const PG8_LAS bf16x8*)(lds + PG8_SB(b, h) + boff + n * 2048 + k * 1024); } while (0)
; #define PG8_WAIT_V(n) asm volatile("s_waitcnt vmcnt(" #n ")" ::: "memory")
; #define PG8_WAIT_L(n) asm volatile("s_waitcnt lgkmcnt(" #n ")" ::: "memory")
; #define PG8_BAR __builtin_amdgcn_s_barrier()
; #define PG8_SCHED __builtin_amdgcn_sched_barrier(0)
;     __device__ __forceinline__ void mid(f32x4 (&acc)[2][2][4][2], const Unit& u, int wr, int wc, int fr, int fq) const {
;         int row0 = u.pm * BM + wr * 64 + fr; const int col0 = u.pn * BM + wc * 32 + 8 * fq;
;         asm volatile("" : "+v"(row0));
; #pragma unroll
;         for (int ai = 0; ai < 2; ++ai)
; #pragma unroll
;             for (int m = 0; m < 4; ++m) { const bf16_t* pr = P + (size_t)(row0 + ai * HALF + m * 16) * NP + col0;
; #pragma unroll
;                 for (int bj = 0; bj < 2; ++bj) { const u32x4 a = *(const u32x4*)(pr + PC_GA + bj * HALF), b = *(const u32x4*)(pr + PC_GB + bj * HALF);
; template <class Epi, class Sched, bool ALIGN_EPI = false, bool SP2 = false>
; __device__ __forceinline__ void gemm_phase(PG8_LAS unsigned char* lds, const Gemm g, const Sched& S, const Epi& E) {
;     ...
;             PG8_LDB(B0, 1, 0); PG8_LDB(B1, 1, 1); PG8_SCHED; PG8_LDA(At, 1, 0); PG8_STAGE(PG8_SA(0, 1), a2 + hstep, voffA);
;             PG8_WAIT_V(8); PG8_WAIT_L(0); PG8_BAR; PG8_MMA(0, 0, At, B0); PG8_MMA(0, 1, At, B1); PG8_BAR; PG8_SCHED;
;             PG8_LDA(At, 1, 1); PG8_STAGE(PG8_SB(1, 0), b3, voffB); PG8_STAGE(PG8_SB(1, 1), b3 + hstep, voffB); PG8_STAGE(PG8_SA(1, 0), a3, voffA);
;             PG8_WAIT_V(8); PG8_WAIT_L(0); PG8_BAR; PG8_MMA(1, 0, At, B0); PG8_MMA(1, 1, At, B1); PG8_BAR; PG8_SCHED;
	s_add_i32 s89, s89, s28
	v_lshl_add_u64 v[176:177], v[246:247], 0, s[22:23]
	s_mov_b32 m0, s89
	s_add_i32 s90, s89, 0x2000
	ds_read_b128 v[210:213], v165 offset:49152
	ds_read_b128 v[214:217], v165 offset:50176
	ds_read_b128 v[218:221], v165 offset:51200
	ds_read_b128 v[222:225], v165 offset:52224
	ds_read_b128 v[226:229], v165 offset:53248
	ds_read_b128 v[230:233], v165 offset:54272
	ds_read_b128 v[234:237], v165 offset:55296
	ds_read_b128 v[238:241], v165 offset:56320
	global_load_lds_dwordx4 v[176:177], off
	v_lshl_add_u64 v[176:177], v[248:249], 0, s[22:23]
	s_mov_b32 m0, s90
	s_add_i32 s91, s91, s28
	global_load_lds_dwordx4 v[176:177], off
	v_lshl_add_u64 v[176:177], v[246:247], 0, s[36:37]
	s_mov_b32 m0, s91
	s_add_i32 s92, s91, 0x2000
	global_load_lds_dwordx4 v[176:177], off
	v_lshl_add_u64 v[176:177], v[248:249], 0, s[36:37]
	s_mov_b32 m0, s92
	s_nop 0
	global_load_lds_dwordx4 v[176:177], off
	v_lshl_add_u64 v[176:177], v[242:243], 0, s[22:23]
	s_mov_b32 m0, s75
	s_nop 0
	global_load_lds_dwordx4 v[176:177], off
	v_lshl_add_u64 v[176:177], v[244:245], 0, s[22:23]
	s_mov_b32 m0, s76
	s_nop 0
	global_load_lds_dwordx4 v[176:177], off
	s_waitcnt vmcnt(8)
	s_waitcnt lgkmcnt(0)
	s_barrier
	s_setprio 1
	s_waitcnt lgkmcnt(0)
	v_mfma_f32_16x16x32_bf16 v[126:129], v[168:171], v[210:213], v[126:129]
	v_mfma_f32_16x16x32_bf16 v[122:125], v[180:183], v[210:213], v[122:125]
	v_mfma_f32_16x16x32_bf16 v[102:105], v[168:171], v[218:221], v[102:105]
	v_mfma_f32_16x16x32_bf16 v[98:101], v[180:183], v[218:221], v[98:101]
	v_mfma_f32_16x16x32_bf16 v[62:65], v[168:171], v[226:229], v[62:65]
	v_mfma_f32_16x16x32_bf16 v[58:61], v[180:183], v[226:229], v[58:61]
	v_mfma_f32_16x16x32_bf16 v[22:25], v[168:171], v[234:237], v[22:25]
	v_mfma_f32_16x16x32_bf16 v[18:21], v[180:183], v[234:237], v[18:21]
	v_mfma_f32_16x16x32_bf16 v[126:129], v[172:175], v[214:217], v[126:129]
	v_mfma_f32_16x16x32_bf16 v[122:125], v[184:187], v[214:217], v[122:125]
	v_mfma_f32_16x16x32_bf16 v[102:105], v[172:175], v[222:225], v[102:105]
	v_mfma_f32_16x16x32_bf16 v[98:101], v[184:187], v[222:225], v[98:101]
	v_mfma_f32_16x16x32_bf16 v[62:65], v[172:175], v[230:233], v[62:65]
	v_mfma_f32_16x16x32_bf16 v[58:61], v[184:187], v[230:233], v[58:61]
	v_mfma_f32_16x16x32_bf16 v[22:25], v[172:175], v[238:241], v[22:25]
	v_mfma_f32_16x16x32_bf16 v[18:21], v[184:187], v[238:241], v[18:21]
	s_setprio 0
	s_setprio 1
	v_mfma_f32_16x16x32_bf16 v[118:121], v[188:191], v[210:213], v[118:121]
	v_mfma_f32_16x16x32_bf16 v[114:117], v[202:205], v[210:213], v[114:117]
	v_mfma_f32_16x16x32_bf16 v[78:81], v[188:191], v[218:221], v[78:81]
	v_mfma_f32_16x16x32_bf16 v[74:77], v[202:205], v[218:221], v[74:77]
	v_mfma_f32_16x16x32_bf16 v[46:49], v[188:191], v[226:229], v[46:49]
	v_mfma_f32_16x16x32_bf16 v[42:45], v[202:205], v[226:229], v[42:45]
	v_mfma_f32_16x16x32_bf16 v[6:9], v[188:191], v[234:237], v[6:9]
	v_mfma_f32_16x16x32_bf16 v[2:5], v[202:205], v[234:237], v[2:5]
	v_mfma_f32_16x16x32_bf16 v[118:121], v[198:201], v[214:217], v[118:121]
	v_mfma_f32_16x16x32_bf16 v[114:117], v[206:209], v[214:217], v[114:117]
	v_mfma_f32_16x16x32_bf16 v[78:81], v[198:201], v[222:225], v[78:81]
	v_mfma_f32_16x16x32_bf16 v[74:77], v[206:209], v[222:225], v[74:77]
	v_mfma_f32_16x16x32_bf16 v[46:49], v[198:201], v[230:233], v[46:49]
	v_mfma_f32_16x16x32_bf16 v[42:45], v[206:209], v[230:233], v[42:45]
	v_mfma_f32_16x16x32_bf16 v[6:9], v[198:201], v[238:241], v[6:9]
	v_mfma_f32_16x16x32_bf16 v[2:5], v[206:209], v[238:241], v[2:5]
	s_setprio 0
	s_barrier
	s_add_i32 s27, s27, 2
	s_add_u32 s44, s44, 0x10000
	s_addc_u32 s45, s45, 0
	s_cmp_lt_u32 s27, 30
	s_cbranch_scc1 .LBB0_682
	s_ashr_i32 s41, s40, 31
	s_lshl_b64 s[44:45], s[40:41], 21
	s_add_u32 s44, s18, s44
	s_addc_u32 s45, s19, s45
	s_ashr_i32 s39, s38, 31
	s_lshl_b64 s[46:47], s[38:39], 21
	v_readlane_b32 s58, v255, 15
	v_readlane_b32 s59, v255, 16
	s_add_u32 s46, s58, s46
	s_addc_u32 s47, s59, s47
	s_lshl_b32 s39, s26, 8
	v_or_b32_e32 v130, s39, v162
	v_ashrrev_i32_e32 v131, 31, v130
	v_lshl_add_u32 v166, s70, 8, v160
	v_lshl_add_u64 v[156:157], v[130:131], 1, s[24:25]
	v_mov_b32_e32 v168, v166
	s_and_b64 s[26:27], s[0:1], exec
	v_mad_i64_i32 v[158:159], s[58:59], v168, s78, v[156:157]
	v_add_co_u32_e32 v174, vcc, s61, v158
	s_cselect_b32 s41, s45, s51
	s_nop 0
	v_addc_co_u32_e32 v175, vcc, 0, v159, vcc
	v_add_co_u32_e32 v158, vcc, s77, v158
	v_mov_b32_e32 v230, v174
	v_mov_b32_e32 v231, v175
	global_load_dwordx4 v[130:133], v[174:175], off
	s_nop 0
	v_addc_co_u32_e32 v159, vcc, 0, v159, vcc
	global_load_dwordx4 v[170:173], v[158:159], off
	s_mov_b32 s100, 0x2000
	s_mov_b32 s101, 0
	v_lshl_add_u64 v[232:233], v[230:231], 0, s[100:101]
	s_mov_b32 s98, 0xa0000
	s_mov_b32 s99, 0
	s_mov_b32 s100, 0x320000
	s_mov_b32 s101, 0
	global_load_dwordx4 v[184:187], v[230:231], off offset:256
	global_load_dwordx4 v[188:191], v[232:233], off offset:256
	v_lshl_add_u64 v[230:231], v[230:231], 0, s[98:99]
	v_lshl_add_u64 v[232:233], v[232:233], 0, s[98:99]
	global_load_dwordx4 v[198:201], v[230:231], off
	global_load_dwordx4 v[202:205], v[232:233], off
	global_load_dwordx4 v[206:209], v[230:231], off offset:256
	global_load_dwordx4 v[210:213], v[232:233], off offset:256
	v_lshl_add_u64 v[230:231], v[230:231], 0, s[98:99]
	v_lshl_add_u64 v[232:233], v[232:233], 0, s[98:99]
	global_load_dwordx4 v[214:217], v[230:231], off
	global_load_dwordx4 v[218:221], v[232:233], off
	global_load_dwordx4 v[222:225], v[230:231], off offset:256
	global_load_dwordx4 v[226:229], v[232:233], off offset:256
	s_cselect_b32 s93, s44, s50
	s_cselect_b32 s27, s47, s49
	s_cselect_b32 s97, s46, s48
	s_add_u32 s50, s50, 0x10c000
	s_addc_u32 s51, s51, 0
	s_add_u32 s26, s48, 0x110000
	s_addc_u32 s33, s49, 0
	s_mov_b32 s56, 30
	s_waitcnt vmcnt(0)
; __device__ __forceinline__ float bflo(unsigned w) { return __uint_as_float(w << 16); }
; __device__ __forceinline__ float bfhi(unsigned w) { return __uint_as_float(w & 0xffff0000u); }
;     __device__ __forceinline__ void mid(f32x4 (&acc)[2][2][4][2], const Unit& u, int wr, int wc, int fr, int fq) const {
;     ...
;             for (int m = 0; m < 4; ++m) { const bf16_t* pr = P + (size_t)(row0 + ai * HALF + m * 16) * NP + col0;
; #pragma unroll
;                 for (int bj = 0; bj < 2; ++bj) { const u32x4 a = *(const u32x4*)(pr + PC_GA + bj * HALF), b = *(const u32x4*)(pr + PC_GB + bj * HALF);
;                     const f32x4 b0 = {bflo(b.x), bfhi(b.x), bflo(b.y), bfhi(b.y)}, b1 = {bflo(b.z), bfhi(b.z), bflo(b.w), bfhi(b.w)};
;                     const f32x4 a0 = {bflo(a.x), bfhi(a.x), bflo(a.y), bfhi(a.y)}, a1 = {bflo(a.z), bfhi(a.z), bflo(a.w), bfhi(a.w)};
;                     f32x4 r0, r1;
; #pragma unroll
;                     for (int j = 0; j < 4; ++j) { r0[j] = a0[j] * __builtin_amdgcn_rcpf(fmaxf(b0[j], 1e-30f)); r1[j] = a1[j] * __builtin_amdgcn_rcpf(fmaxf(b1[j], 1e-30f)); }
;                     acc[ai][bj][m][0] *= r0; acc[ai][bj][m][1] *= r1; }
	v_and_b32_e32 v177, 0xffff0000, v130
	v_lshlrev_b32_e32 v169, 16, v170
	v_max_f32_e32 v169, v169, v169
	v_lshlrev_b32_e32 v178, 16, v171
	v_and_b32_e32 v179, 0xffff0000, v171
	v_lshlrev_b32_e32 v171, 16, v172
	v_max_f32_e32 v169, 0xda24260, v169
	v_and_b32_e32 v176, 0xffff0000, v170
	v_rcp_f32_e32 v170, v169
	v_max_f32_e32 v169, v171, v171
	v_max_f32_e32 v169, 0xda24260, v169
	v_and_b32_e32 v180, 0xffff0000, v172
	v_rcp_f32_e32 v172, v169
	v_max_f32_e32 v169, v176, v176
	v_max_f32_e32 v169, 0xda24260, v169
	v_lshlrev_b32_e32 v176, 16, v130
	v_max_f32_e32 v130, v180, v180
	v_rcp_f32_e32 v171, v169
	v_max_f32_e32 v130, 0xda24260, v130
	v_lshlrev_b32_e32 v181, 16, v173
	v_and_b32_e32 v182, 0xffff0000, v173
	v_rcp_f32_e32 v173, v130
	v_max_f32_e32 v130, v178, v178
	v_pk_mul_f32 v[170:171], v[170:171], v[176:177]
	v_lshlrev_b32_e32 v176, 16, v132
	v_and_b32_e32 v177, 0xffff0000, v132
	v_max_f32_e32 v130, 0xda24260, v130
	v_pk_mul_f32 v[172:173], v[172:173], v[176:177]
	v_rcp_f32_e32 v176, v130
	v_max_f32_e32 v130, v181, v181
	v_lshlrev_b32_e32 v180, 16, v131
	v_and_b32_e32 v181, 0xffff0000, v131
	v_max_f32_e32 v131, v182, v182
	v_max_f32_e32 v130, 0xda24260, v130
	v_max_f32_e32 v131, 0xda24260, v131
	v_rcp_f32_e32 v130, v130
	v_rcp_f32_e32 v131, v131
	v_max_f32_e32 v132, v179, v179
	v_max_f32_e32 v132, 0xda24260, v132
	v_rcp_f32_e32 v177, v132
	v_lshlrev_b32_e32 v132, 16, v133
	v_and_b32_e32 v133, 0xffff0000, v133
	v_pk_mul_f32 v[130:131], v[130:131], v[132:133]
	v_pk_mul_f32 v[14:15], v[14:15], v[170:171]
	v_pk_mul_f32 v[12:13], v[12:13], v[130:131]
	v_pk_mul_f32 v[10:11], v[10:11], v[172:173]
	s_nop 0
	s_nop 0
	v_pk_mul_f32 v[176:177], v[176:177], v[180:181]
	s_waitcnt vmcnt(9)
	v_mov_b32_e32 v130, v184
	v_mov_b32_e32 v131, v185
	v_mov_b32_e32 v132, v186
	v_mov_b32_e32 v133, v187
	v_lshl_add_u64 v[230:231], v[230:231], 0, s[98:99]
	v_lshl_add_u64 v[232:233], v[232:233], 0, s[98:99]
	global_load_dwordx4 v[184:187], v[230:231], off
	s_waitcnt vmcnt(9)
	v_mov_b32_e32 v170, v188
	v_mov_b32_e32 v171, v189
	v_mov_b32_e32 v172, v190
	v_mov_b32_e32 v173, v191
	global_load_dwordx4 v[188:191], v[232:233], off
	v_lshlrev_b32_e32 v158, 16, v170
	v_and_b32_e32 v159, 0xffff0000, v170
	v_lshlrev_b32_e32 v169, 16, v171
	v_and_b32_e32 v174, 0xffff0000, v171
	v_lshlrev_b32_e32 v170, 16, v172
	v_and_b32_e32 v171, 0xffff0000, v172
	v_max_f32_e32 v158, v158, v158
	v_max_f32_e32 v159, v159, v159
	v_pk_mul_f32 v[16:17], v[16:17], v[176:177]
	v_lshlrev_b32_e32 v175, 16, v173
	v_and_b32_e32 v176, 0xffff0000, v173
	v_max_f32_e32 v158, 0xda24260, v158
	v_max_f32_e32 v170, v170, v170
	v_max_f32_e32 v159, 0xda24260, v159
	v_lshlrev_b32_e32 v172, 16, v130
	v_and_b32_e32 v173, 0xffff0000, v130
	v_max_f32_e32 v130, v171, v171
	v_rcp_f32_e32 v158, v158
	v_max_f32_e32 v170, 0xda24260, v170
	v_rcp_f32_e32 v159, v159
	v_max_f32_e32 v130, 0xda24260, v130
	v_rcp_f32_e32 v170, v170
	v_rcp_f32_e32 v171, v130
	v_max_f32_e32 v130, v169, v169
	v_pk_mul_f32 v[158:159], v[158:159], v[172:173]
	v_lshlrev_b32_e32 v172, 16, v132
	v_and_b32_e32 v173, 0xffff0000, v132
	v_max_f32_e32 v130, 0xda24260, v130
	v_pk_mul_f32 v[170:171], v[170:171], v[172:173]
	v_rcp_f32_e32 v172, v130
	v_max_f32_e32 v130, v175, v175
	v_max_f32_e32 v132, v174, v174
	v_lshlrev_b32_e32 v174, 16, v131
	v_and_b32_e32 v175, 0xffff0000, v131
	v_max_f32_e32 v131, v176, v176
	v_max_f32_e32 v130, 0xda24260, v130
	v_max_f32_e32 v131, 0xda24260, v131
	v_rcp_f32_e32 v130, v130
	v_rcp_f32_e32 v131, v131
	v_max_f32_e32 v132, 0xda24260, v132
	v_rcp_f32_e32 v173, v132
	v_lshlrev_b32_e32 v132, 16, v133
	v_and_b32_e32 v133, 0xffff0000, v133
	v_pk_mul_f32 v[130:131], v[130:131], v[132:133]
	v_pk_mul_f32 v[30:31], v[30:31], v[158:159]
	v_pk_mul_f32 v[28:29], v[28:29], v[130:131]
	v_add_u32_e32 v130, 16, v168
	v_mad_i64_i32 v[158:159], s[58:59], v130, s78, v[156:157]
	v_pk_mul_f32 v[172:173], v[172:173], v[174:175]
	v_add_co_u32_e32 v174, vcc, s61, v158
	v_pk_mul_f32 v[32:33], v[32:33], v[172:173]
	s_nop 0
	v_addc_co_u32_e32 v175, vcc, 0, v159, vcc
	v_add_co_u32_e32 v158, vcc, s77, v158
	v_pk_mul_f32 v[26:27], v[26:27], v[170:171]
	s_nop 0
	v_addc_co_u32_e32 v159, vcc, 0, v159, vcc
	s_nop 0
	s_nop 0
	s_waitcnt vmcnt(9)
	v_mov_b32_e32 v130, v198
	v_mov_b32_e32 v131, v199
	v_mov_b32_e32 v132, v200
	v_mov_b32_e32 v133, v201
	global_load_dwordx4 v[198:201], v[230:231], off offset:256
	v_and_b32_e32 v177, 0xffff0000, v130
	s_waitcnt vmcnt(9)
	v_mov_b32_e32 v170, v202
	v_mov_b32_e32 v171, v203
	v_mov_b32_e32 v172, v204
	v_mov_b32_e32 v173, v205
	global_load_dwordx4 v[202:205], v[232:233], off offset:256
	v_lshlrev_b32_e32 v169, 16, v170
	v_max_f32_e32 v169, v169, v169
	v_lshlrev_b32_e32 v178, 16, v171
	v_and_b32_e32 v179, 0xffff0000, v171
	v_lshlrev_b32_e32 v171, 16, v172
	v_max_f32_e32 v169, 0xda24260, v169
	v_and_b32_e32 v176, 0xffff0000, v170
	v_rcp_f32_e32 v170, v169
	v_max_f32_e32 v169, v171, v171
	v_max_f32_e32 v169, 0xda24260, v169
	v_and_b32_e32 v180, 0xffff0000, v172
	v_rcp_f32_e32 v172, v169
	v_max_f32_e32 v169, v176, v176
	v_max_f32_e32 v169, 0xda24260, v169
	v_lshlrev_b32_e32 v176, 16, v130
	v_max_f32_e32 v130, v180, v180
	v_rcp_f32_e32 v171, v169
	v_max_f32_e32 v130, 0xda24260, v130
	v_lshlrev_b32_e32 v181, 16, v173
	v_and_b32_e32 v182, 0xffff0000, v173
	v_rcp_f32_e32 v173, v130
	v_max_f32_e32 v130, v178, v178
	v_pk_mul_f32 v[170:171], v[170:171], v[176:177]
	v_lshlrev_b32_e32 v176, 16, v132
	v_and_b32_e32 v177, 0xffff0000, v132
	v_max_f32_e32 v130, 0xda24260, v130
	v_pk_mul_f32 v[172:173], v[172:173], v[176:177]
	v_rcp_f32_e32 v176, v130
	v_max_f32_e32 v130, v181, v181
	v_lshlrev_b32_e32 v180, 16, v131
	v_and_b32_e32 v181, 0xffff0000, v131
	v_max_f32_e32 v131, v182, v182
	v_max_f32_e32 v130, 0xda24260, v130
	v_max_f32_e32 v131, 0xda24260, v131
	v_rcp_f32_e32 v130, v130
	v_rcp_f32_e32 v131, v131
	v_max_f32_e32 v132, v179, v179
	v_max_f32_e32 v132, 0xda24260, v132
	v_rcp_f32_e32 v177, v132
	v_lshlrev_b32_e32 v132, 16, v133
	v_and_b32_e32 v133, 0xffff0000, v133
	v_pk_mul_f32 v[130:131], v[130:131], v[132:133]
	v_pk_mul_f32 v[38:39], v[38:39], v[170:171]
	v_pk_mul_f32 v[36:37], v[36:37], v[130:131]
	v_pk_mul_f32 v[34:35], v[34:35], v[172:173]
	s_nop 0
	s_nop 0
	v_pk_mul_f32 v[176:177], v[176:177], v[180:181]
	s_waitcnt vmcnt(9)
; __device__ __forceinline__ float bflo(unsigned w) { return __uint_as_float(w << 16); }
; __device__ __forceinline__ float bfhi(unsigned w) { return __uint_as_float(w & 0xffff0000u); }
;     __device__ __forceinline__ void mid(f32x4 (&acc)[2][2][4][2], const Unit& u, int wr, int wc, int fr, int fq) const {
;     ...
;             for (int m = 0; m < 4; ++m) { const bf16_t* pr = P + (size_t)(row0 + ai * HALF + m * 16) * NP + col0;
; #pragma unroll
;                 for (int bj = 0; bj < 2; ++bj) { const u32x4 a = *(const u32x4*)(pr + PC_GA + bj * HALF), b = *(const u32x4*)(pr + PC_GB + bj * HALF);
;                     const f32x4 b0 = {bflo(b.x), bfhi(b.x), bflo(b.y), bfhi(b.y)}, b1 = {bflo(b.z), bfhi(b.z), bflo(b.w), bfhi(b.w)};
;                     const f32x4 a0 = {bflo(a.x), bfhi(a.x), bflo(a.y), bfhi(a.y)}, a1 = {bflo(a.z), bfhi(a.z), bflo(a.w), bfhi(a.w)};
;                     f32x4 r0, r1;
; #pragma unroll
;                     for (int j = 0; j < 4; ++j) { r0[j] = a0[j] * __builtin_amdgcn_rcpf(fmaxf(b0[j], 1e-30f)); r1[j] = a1[j] * __builtin_amdgcn_rcpf(fmaxf(b1[j], 1e-30f)); }
;                     acc[ai][bj][m][0] *= r0; acc[ai][bj][m][1] *= r1; }
	v_mov_b32_e32 v130, v206
	v_mov_b32_e32 v131, v207
	v_mov_b32_e32 v132, v208
	v_mov_b32_e32 v133, v209
	v_lshl_add_u64 v[230:231], v[230:231], 0, s[100:101]
	v_lshl_add_u64 v[232:233], v[232:233], 0, s[100:101]
	global_load_dwordx4 v[206:209], v[230:231], off
	s_waitcnt vmcnt(9)
	v_mov_b32_e32 v170, v210
	v_mov_b32_e32 v171, v211
	v_mov_b32_e32 v172, v212
	v_mov_b32_e32 v173, v213
	global_load_dwordx4 v[210:213], v[232:233], off
	v_lshlrev_b32_e32 v158, 16, v170
	v_and_b32_e32 v159, 0xffff0000, v170
	v_lshlrev_b32_e32 v169, 16, v171
	v_and_b32_e32 v174, 0xffff0000, v171
	v_lshlrev_b32_e32 v170, 16, v172
	v_and_b32_e32 v171, 0xffff0000, v172
	v_max_f32_e32 v158, v158, v158
	v_max_f32_e32 v159, v159, v159
	v_pk_mul_f32 v[40:41], v[40:41], v[176:177]
	v_lshlrev_b32_e32 v175, 16, v173
	v_and_b32_e32 v176, 0xffff0000, v173
	v_max_f32_e32 v158, 0xda24260, v158
	v_max_f32_e32 v170, v170, v170
	v_max_f32_e32 v159, 0xda24260, v159
	v_lshlrev_b32_e32 v172, 16, v130
	v_and_b32_e32 v173, 0xffff0000, v130
	v_max_f32_e32 v130, v171, v171
	v_rcp_f32_e32 v158, v158
	v_max_f32_e32 v170, 0xda24260, v170
	v_rcp_f32_e32 v159, v159
	v_max_f32_e32 v130, 0xda24260, v130
	v_rcp_f32_e32 v170, v170
	v_rcp_f32_e32 v171, v130
	v_max_f32_e32 v130, v169, v169
	v_pk_mul_f32 v[158:159], v[158:159], v[172:173]
	v_lshlrev_b32_e32 v172, 16, v132
	v_and_b32_e32 v173, 0xffff0000, v132
	v_max_f32_e32 v130, 0xda24260, v130
	v_pk_mul_f32 v[170:171], v[170:171], v[172:173]
	v_rcp_f32_e32 v172, v130
	v_max_f32_e32 v130, v175, v175
	v_max_f32_e32 v132, v174, v174
	v_lshlrev_b32_e32 v174, 16, v131
	v_and_b32_e32 v175, 0xffff0000, v131
	v_max_f32_e32 v131, v176, v176
	v_max_f32_e32 v130, 0xda24260, v130
	v_max_f32_e32 v131, 0xda24260, v131
	v_rcp_f32_e32 v130, v130
	v_rcp_f32_e32 v131, v131
	v_max_f32_e32 v132, 0xda24260, v132
	v_rcp_f32_e32 v173, v132
	v_lshlrev_b32_e32 v132, 16, v133
	v_and_b32_e32 v133, 0xffff0000, v133
	v_pk_mul_f32 v[130:131], v[130:131], v[132:133]
	v_pk_mul_f32 v[54:55], v[54:55], v[158:159]
	v_pk_mul_f32 v[52:53], v[52:53], v[130:131]
	v_add_u32_e32 v130, 32, v168
	v_mad_i64_i32 v[158:159], s[58:59], v130, s78, v[156:157]
	v_pk_mul_f32 v[172:173], v[172:173], v[174:175]
	v_add_co_u32_e32 v174, vcc, s61, v158
	v_pk_mul_f32 v[56:57], v[56:57], v[172:173]
	s_nop 0
	v_addc_co_u32_e32 v175, vcc, 0, v159, vcc
	v_add_co_u32_e32 v158, vcc, s77, v158
	v_pk_mul_f32 v[50:51], v[50:51], v[170:171]
	s_nop 0
	v_addc_co_u32_e32 v159, vcc, 0, v159, vcc
	s_nop 0
	s_nop 0
	s_waitcnt vmcnt(9)
	v_mov_b32_e32 v130, v214
	v_mov_b32_e32 v131, v215
	v_mov_b32_e32 v132, v216
	v_mov_b32_e32 v133, v217
	global_load_dwordx4 v[214:217], v[230:231], off offset:256
	v_and_b32_e32 v177, 0xffff0000, v130
	s_waitcnt vmcnt(9)
	v_mov_b32_e32 v170, v218
	v_mov_b32_e32 v171, v219
	v_mov_b32_e32 v172, v220
	v_mov_b32_e32 v173, v221
	global_load_dwordx4 v[218:221], v[232:233], off offset:256
	v_lshlrev_b32_e32 v169, 16, v170
	v_max_f32_e32 v169, v169, v169
	v_lshlrev_b32_e32 v178, 16, v171
	v_and_b32_e32 v179, 0xffff0000, v171
	v_lshlrev_b32_e32 v171, 16, v172
	v_max_f32_e32 v169, 0xda24260, v169
	v_and_b32_e32 v176, 0xffff0000, v170
	v_rcp_f32_e32 v170, v169
	v_max_f32_e32 v169, v171, v171
	v_max_f32_e32 v169, 0xda24260, v169
	v_and_b32_e32 v180, 0xffff0000, v172
	v_rcp_f32_e32 v172, v169
	v_max_f32_e32 v169, v176, v176
	v_max_f32_e32 v169, 0xda24260, v169
	v_lshlrev_b32_e32 v176, 16, v130
	v_max_f32_e32 v130, v180, v180
	v_rcp_f32_e32 v171, v169
	v_max_f32_e32 v130, 0xda24260, v130
	v_lshlrev_b32_e32 v181, 16, v173
	v_and_b32_e32 v182, 0xffff0000, v173
	v_rcp_f32_e32 v173, v130
	v_max_f32_e32 v130, v178, v178
	v_pk_mul_f32 v[170:171], v[170:171], v[176:177]
	v_lshlrev_b32_e32 v176, 16, v132
	v_and_b32_e32 v177, 0xffff0000, v132
	v_max_f32_e32 v130, 0xda24260, v130
	v_pk_mul_f32 v[172:173], v[172:173], v[176:177]
	v_rcp_f32_e32 v176, v130
	v_max_f32_e32 v130, v181, v181
	v_lshlrev_b32_e32 v180, 16, v131
	v_and_b32_e32 v181, 0xffff0000, v131
	v_max_f32_e32 v131, v182, v182
	v_max_f32_e32 v130, 0xda24260, v130
	v_max_f32_e32 v131, 0xda24260, v131
	v_rcp_f32_e32 v130, v130
	v_rcp_f32_e32 v131, v131
	v_max_f32_e32 v132, v179, v179
	v_max_f32_e32 v132, 0xda24260, v132
	v_rcp_f32_e32 v177, v132
	v_lshlrev_b32_e32 v132, 16, v133
	v_and_b32_e32 v133, 0xffff0000, v133
	v_pk_mul_f32 v[130:131], v[130:131], v[132:133]
	v_pk_mul_f32 v[70:71], v[70:71], v[170:171]
	v_pk_mul_f32 v[68:69], v[68:69], v[130:131]
	v_pk_mul_f32 v[66:67], v[66:67], v[172:173]
	s_nop 0
	s_nop 0
	v_pk_mul_f32 v[176:177], v[176:177], v[180:181]
	s_waitcnt vmcnt(9)
	v_mov_b32_e32 v130, v222
	v_mov_b32_e32 v131, v223
	v_mov_b32_e32 v132, v224
	v_mov_b32_e32 v133, v225
	v_lshl_add_u64 v[230:231], v[230:231], 0, s[98:99]
	v_lshl_add_u64 v[232:233], v[232:233], 0, s[98:99]
	global_load_dwordx4 v[222:225], v[230:231], off
	s_waitcnt vmcnt(9)
; __device__ __forceinline__ float bflo(unsigned w) { return __uint_as_float(w << 16); }
; __device__ __forceinline__ float bfhi(unsigned w) { return __uint_as_float(w & 0xffff0000u); }
;     __device__ __forceinline__ void mid(f32x4 (&acc)[2][2][4][2], const Unit& u, int wr, int wc, int fr, int fq) const {
;     ...
;             for (int m = 0; m < 4; ++m) { const bf16_t* pr = P + (size_t)(row0 + ai * HALF + m * 16) * NP + col0;
; #pragma unroll
;                 for (int bj = 0; bj < 2; ++bj) { const u32x4 a = *(const u32x4*)(pr + PC_GA + bj * HALF), b = *(const u32x4*)(pr + PC_GB + bj * HALF);
;                     const f32x4 b0 = {bflo(b.x), bfhi(b.x), bflo(b.y), bfhi(b.y)}, b1 = {bflo(b.z), bfhi(b.z), bflo(b.w), bfhi(b.w)};
;                     const f32x4 a0 = {bflo(a.x), bfhi(a.x), bflo(a.y), bfhi(a.y)}, a1 = {bflo(a.z), bfhi(a.z), bflo(a.w), bfhi(a.w)};
;                     f32x4 r0, r1;
; #pragma unroll
;                     for (int j = 0; j < 4; ++j) { r0[j] = a0[j] * __builtin_amdgcn_rcpf(fmaxf(b0[j], 1e-30f)); r1[j] = a1[j] * __builtin_amdgcn_rcpf(fmaxf(b1[j], 1e-30f)); }
;                     acc[ai][bj][m][0] *= r0; acc[ai][bj][m][1] *= r1; }
	v_mov_b32_e32 v170, v226
	v_mov_b32_e32 v171, v227
	v_mov_b32_e32 v172, v228
	v_mov_b32_e32 v173, v229
	global_load_dwordx4 v[226:229], v[232:233], off
	v_lshlrev_b32_e32 v158, 16, v170
	v_and_b32_e32 v159, 0xffff0000, v170
	v_lshlrev_b32_e32 v169, 16, v171
	v_and_b32_e32 v174, 0xffff0000, v171
	v_lshlrev_b32_e32 v170, 16, v172
	v_and_b32_e32 v171, 0xffff0000, v172
	v_max_f32_e32 v158, v158, v158
	v_max_f32_e32 v159, v159, v159
	v_pk_mul_f32 v[72:73], v[72:73], v[176:177]
	v_lshlrev_b32_e32 v175, 16, v173
	v_and_b32_e32 v176, 0xffff0000, v173
	v_max_f32_e32 v158, 0xda24260, v158
	v_max_f32_e32 v170, v170, v170
	v_max_f32_e32 v159, 0xda24260, v159
	v_lshlrev_b32_e32 v172, 16, v130
	v_and_b32_e32 v173, 0xffff0000, v130
	v_max_f32_e32 v130, v171, v171
	v_rcp_f32_e32 v158, v158
	v_max_f32_e32 v170, 0xda24260, v170
	v_rcp_f32_e32 v159, v159
	v_max_f32_e32 v130, 0xda24260, v130
	v_rcp_f32_e32 v170, v170
	v_rcp_f32_e32 v171, v130
	v_max_f32_e32 v130, v169, v169
	v_pk_mul_f32 v[158:159], v[158:159], v[172:173]
	v_lshlrev_b32_e32 v172, 16, v132
	v_and_b32_e32 v173, 0xffff0000, v132
	v_max_f32_e32 v130, 0xda24260, v130
	v_pk_mul_f32 v[170:171], v[170:171], v[172:173]
	v_rcp_f32_e32 v172, v130
	v_max_f32_e32 v130, v175, v175
	v_max_f32_e32 v132, v174, v174
	v_lshlrev_b32_e32 v174, 16, v131
	v_and_b32_e32 v175, 0xffff0000, v131
	v_max_f32_e32 v131, v176, v176
	v_max_f32_e32 v130, 0xda24260, v130
	v_max_f32_e32 v131, 0xda24260, v131
	v_rcp_f32_e32 v130, v130
	v_rcp_f32_e32 v131, v131
	v_max_f32_e32 v132, 0xda24260, v132
	v_rcp_f32_e32 v173, v132
	v_lshlrev_b32_e32 v132, 16, v133
	v_and_b32_e32 v133, 0xffff0000, v133
	v_pk_mul_f32 v[130:131], v[130:131], v[132:133]
	v_pk_mul_f32 v[86:87], v[86:87], v[158:159]
	v_pk_mul_f32 v[84:85], v[84:85], v[130:131]
	v_add_u32_e32 v130, 48, v168
	v_mad_i64_i32 v[158:159], s[58:59], v130, s78, v[156:157]
	v_pk_mul_f32 v[172:173], v[172:173], v[174:175]
	v_add_co_u32_e32 v174, vcc, s61, v158
	v_pk_mul_f32 v[88:89], v[88:89], v[172:173]
	s_nop 0
	v_addc_co_u32_e32 v175, vcc, 0, v159, vcc
	v_add_co_u32_e32 v158, vcc, s77, v158
	v_pk_mul_f32 v[82:83], v[82:83], v[170:171]
	s_nop 0
	v_addc_co_u32_e32 v159, vcc, 0, v159, vcc
	s_nop 0
	s_nop 0
	s_waitcnt vmcnt(9)
	v_mov_b32_e32 v130, v184
	v_mov_b32_e32 v131, v185
	v_mov_b32_e32 v132, v186
	v_mov_b32_e32 v133, v187
	global_load_dwordx4 v[184:187], v[230:231], off offset:256
	v_and_b32_e32 v177, 0xffff0000, v130
	s_waitcnt vmcnt(9)
	v_mov_b32_e32 v170, v188
	v_mov_b32_e32 v171, v189
	v_mov_b32_e32 v172, v190
	v_mov_b32_e32 v173, v191
	global_load_dwordx4 v[188:191], v[232:233], off offset:256
	v_lshlrev_b32_e32 v169, 16, v170
	v_max_f32_e32 v169, v169, v169
	v_lshlrev_b32_e32 v178, 16, v171
	v_and_b32_e32 v179, 0xffff0000, v171
	v_lshlrev_b32_e32 v171, 16, v172
	v_max_f32_e32 v169, 0xda24260, v169
	v_and_b32_e32 v176, 0xffff0000, v170
	v_rcp_f32_e32 v170, v169
	v_max_f32_e32 v169, v171, v171
	v_max_f32_e32 v169, 0xda24260, v169
	v_and_b32_e32 v180, 0xffff0000, v172
	v_rcp_f32_e32 v172, v169
	v_max_f32_e32 v169, v176, v176
	v_max_f32_e32 v169, 0xda24260, v169
	v_lshlrev_b32_e32 v176, 16, v130
	v_max_f32_e32 v130, v180, v180
	v_rcp_f32_e32 v171, v169
	v_max_f32_e32 v130, 0xda24260, v130
	v_lshlrev_b32_e32 v181, 16, v173
	v_and_b32_e32 v182, 0xffff0000, v173
	v_rcp_f32_e32 v173, v130
	v_max_f32_e32 v130, v178, v178
	v_pk_mul_f32 v[170:171], v[170:171], v[176:177]
	v_lshlrev_b32_e32 v176, 16, v132
	v_and_b32_e32 v177, 0xffff0000, v132
	v_max_f32_e32 v130, 0xda24260, v130
	v_pk_mul_f32 v[172:173], v[172:173], v[176:177]
	v_rcp_f32_e32 v176, v130
	v_max_f32_e32 v130, v181, v181
	v_lshlrev_b32_e32 v180, 16, v131
	v_and_b32_e32 v181, 0xffff0000, v131
	v_max_f32_e32 v131, v182, v182
	v_max_f32_e32 v130, 0xda24260, v130
	v_max_f32_e32 v131, 0xda24260, v131
	v_rcp_f32_e32 v130, v130
	v_rcp_f32_e32 v131, v131
	v_max_f32_e32 v132, v179, v179
	v_max_f32_e32 v132, 0xda24260, v132
	v_rcp_f32_e32 v177, v132
	v_lshlrev_b32_e32 v132, 16, v133
	v_and_b32_e32 v133, 0xffff0000, v133
	v_pk_mul_f32 v[130:131], v[130:131], v[132:133]
	v_pk_mul_f32 v[94:95], v[94:95], v[170:171]
	v_pk_mul_f32 v[92:93], v[92:93], v[130:131]
	v_pk_mul_f32 v[90:91], v[90:91], v[172:173]
	s_nop 0
	s_nop 0
	v_pk_mul_f32 v[176:177], v[176:177], v[180:181]
	s_waitcnt vmcnt(9)
	v_mov_b32_e32 v130, v198
	v_mov_b32_e32 v131, v199
	v_mov_b32_e32 v132, v200
	v_mov_b32_e32 v133, v201
	v_lshl_add_u64 v[230:231], v[230:231], 0, s[98:99]
	v_lshl_add_u64 v[232:233], v[232:233], 0, s[98:99]
	global_load_dwordx4 v[198:201], v[230:231], off
	s_waitcnt vmcnt(9)
; __device__ __forceinline__ float bflo(unsigned w) { return __uint_as_float(w << 16); }
; __device__ __forceinline__ float bfhi(unsigned w) { return __uint_as_float(w & 0xffff0000u); }
;     __device__ __forceinline__ void mid(f32x4 (&acc)[2][2][4][2], const Unit& u, int wr, int wc, int fr, int fq) const {
;     ...
;             for (int m = 0; m < 4; ++m) { const bf16_t* pr = P + (size_t)(row0 + ai * HALF + m * 16) * NP + col0;
; #pragma unroll
;                 for (int bj = 0; bj < 2; ++bj) { const u32x4 a = *(const u32x4*)(pr + PC_GA + bj * HALF), b = *(const u32x4*)(pr + PC_GB + bj * HALF);
;                     const f32x4 b0 = {bflo(b.x), bfhi(b.x), bflo(b.y), bfhi(b.y)}, b1 = {bflo(b.z), bfhi(b.z), bflo(b.w), bfhi(b.w)};
;                     const f32x4 a0 = {bflo(a.x), bfhi(a.x), bflo(a.y), bfhi(a.y)}, a1 = {bflo(a.z), bfhi(a.z), bflo(a.w), bfhi(a.w)};
;                     f32x4 r0, r1;
; #pragma unroll
;                     for (int j = 0; j < 4; ++j) { r0[j] = a0[j] * __builtin_amdgcn_rcpf(fmaxf(b0[j], 1e-30f)); r1[j] = a1[j] * __builtin_amdgcn_rcpf(fmaxf(b1[j], 1e-30f)); }
;                     acc[ai][bj][m][0] *= r0; acc[ai][bj][m][1] *= r1; }
	v_mov_b32_e32 v170, v202
	v_mov_b32_e32 v171, v203
	v_mov_b32_e32 v172, v204
	v_mov_b32_e32 v173, v205
	global_load_dwordx4 v[202:205], v[232:233], off
	v_lshlrev_b32_e32 v158, 16, v170
	v_and_b32_e32 v159, 0xffff0000, v170
	v_lshlrev_b32_e32 v169, 16, v171
	v_and_b32_e32 v174, 0xffff0000, v171
	v_lshlrev_b32_e32 v170, 16, v172
	v_and_b32_e32 v171, 0xffff0000, v172
	v_max_f32_e32 v158, v158, v158
	v_max_f32_e32 v159, v159, v159
	v_pk_mul_f32 v[96:97], v[96:97], v[176:177]
	v_lshlrev_b32_e32 v175, 16, v173
	v_and_b32_e32 v176, 0xffff0000, v173
	v_max_f32_e32 v158, 0xda24260, v158
	v_max_f32_e32 v170, v170, v170
	v_max_f32_e32 v159, 0xda24260, v159
	v_lshlrev_b32_e32 v172, 16, v130
	v_and_b32_e32 v173, 0xffff0000, v130
	v_max_f32_e32 v130, v171, v171
	v_rcp_f32_e32 v158, v158
	v_max_f32_e32 v170, 0xda24260, v170
	v_rcp_f32_e32 v159, v159
	v_max_f32_e32 v130, 0xda24260, v130
	v_rcp_f32_e32 v170, v170
	v_rcp_f32_e32 v171, v130
	v_max_f32_e32 v130, v169, v169
	v_pk_mul_f32 v[158:159], v[158:159], v[172:173]
	v_lshlrev_b32_e32 v172, 16, v132
	v_and_b32_e32 v173, 0xffff0000, v132
	v_max_f32_e32 v130, 0xda24260, v130
	v_pk_mul_f32 v[170:171], v[170:171], v[172:173]
	v_rcp_f32_e32 v172, v130
	v_max_f32_e32 v130, v175, v175
	v_max_f32_e32 v132, v174, v174
	v_lshlrev_b32_e32 v174, 16, v131
	v_and_b32_e32 v175, 0xffff0000, v131
	v_max_f32_e32 v131, v176, v176
	v_max_f32_e32 v130, 0xda24260, v130
	v_max_f32_e32 v131, 0xda24260, v131
	v_rcp_f32_e32 v130, v130
	v_rcp_f32_e32 v131, v131
	v_max_f32_e32 v132, 0xda24260, v132
	v_rcp_f32_e32 v173, v132
	v_lshlrev_b32_e32 v132, 16, v133
	v_and_b32_e32 v133, 0xffff0000, v133
	v_pk_mul_f32 v[130:131], v[130:131], v[132:133]
	v_pk_mul_f32 v[110:111], v[110:111], v[158:159]
	v_pk_mul_f32 v[108:109], v[108:109], v[130:131]
	v_add_u32_e32 v130, 0x80, v168
	v_mad_i64_i32 v[158:159], s[58:59], v130, s78, v[156:157]
	v_pk_mul_f32 v[172:173], v[172:173], v[174:175]
	v_add_co_u32_e32 v174, vcc, s61, v158
	v_pk_mul_f32 v[112:113], v[112:113], v[172:173]
	s_nop 0
	v_addc_co_u32_e32 v175, vcc, 0, v159, vcc
	v_add_co_u32_e32 v158, vcc, s77, v158
	v_pk_mul_f32 v[106:107], v[106:107], v[170:171]
	s_nop 0
	v_addc_co_u32_e32 v159, vcc, 0, v159, vcc
	s_nop 0
	s_nop 0
	s_waitcnt vmcnt(9)
	v_mov_b32_e32 v130, v206
	v_mov_b32_e32 v131, v207
	v_mov_b32_e32 v132, v208
	v_mov_b32_e32 v133, v209
	global_load_dwordx4 v[206:209], v[230:231], off offset:256
	v_and_b32_e32 v177, 0xffff0000, v130
	s_waitcnt vmcnt(9)
	v_mov_b32_e32 v170, v210
	v_mov_b32_e32 v171, v211
	v_mov_b32_e32 v172, v212
	v_mov_b32_e32 v173, v213
	global_load_dwordx4 v[210:213], v[232:233], off offset:256
	v_lshlrev_b32_e32 v169, 16, v170
	v_max_f32_e32 v169, v169, v169
	v_lshlrev_b32_e32 v178, 16, v171
	v_and_b32_e32 v179, 0xffff0000, v171
	v_lshlrev_b32_e32 v171, 16, v172
	v_max_f32_e32 v169, 0xda24260, v169
	v_and_b32_e32 v176, 0xffff0000, v170
	v_rcp_f32_e32 v170, v169
	v_max_f32_e32 v169, v171, v171
	v_max_f32_e32 v169, 0xda24260, v169
	v_and_b32_e32 v180, 0xffff0000, v172
	v_rcp_f32_e32 v172, v169
	v_max_f32_e32 v169, v176, v176
	v_max_f32_e32 v169, 0xda24260, v169
	v_lshlrev_b32_e32 v176, 16, v130
	v_max_f32_e32 v130, v180, v180
	v_rcp_f32_e32 v171, v169
	v_max_f32_e32 v130, 0xda24260, v130
	v_lshlrev_b32_e32 v181, 16, v173
	v_and_b32_e32 v182, 0xffff0000, v173
	v_rcp_f32_e32 v173, v130
	v_max_f32_e32 v130, v178, v178
	v_pk_mul_f32 v[170:171], v[170:171], v[176:177]
	v_lshlrev_b32_e32 v176, 16, v132
	v_and_b32_e32 v177, 0xffff0000, v132
	v_max_f32_e32 v130, 0xda24260, v130
	v_pk_mul_f32 v[172:173], v[172:173], v[176:177]
	v_rcp_f32_e32 v176, v130
	v_max_f32_e32 v130, v181, v181
	v_lshlrev_b32_e32 v180, 16, v131
	v_and_b32_e32 v181, 0xffff0000, v131
	v_max_f32_e32 v131, v182, v182
	v_max_f32_e32 v130, 0xda24260, v130
	v_max_f32_e32 v131, 0xda24260, v131
	v_rcp_f32_e32 v130, v130
	v_rcp_f32_e32 v131, v131
	v_max_f32_e32 v132, v179, v179
	v_max_f32_e32 v132, 0xda24260, v132
	v_rcp_f32_e32 v177, v132
	v_lshlrev_b32_e32 v132, 16, v133
	v_and_b32_e32 v133, 0xffff0000, v133
	v_pk_mul_f32 v[130:131], v[130:131], v[132:133]
	v_pk_mul_f32 v[126:127], v[126:127], v[170:171]
	v_pk_mul_f32 v[124:125], v[124:125], v[130:131]
	v_pk_mul_f32 v[122:123], v[122:123], v[172:173]
	s_nop 0
	s_nop 0
	v_pk_mul_f32 v[176:177], v[176:177], v[180:181]
	s_waitcnt vmcnt(9)
	v_mov_b32_e32 v130, v214
	v_mov_b32_e32 v131, v215
	v_mov_b32_e32 v132, v216
	v_mov_b32_e32 v133, v217
	v_lshl_add_u64 v[230:231], v[230:231], 0, s[98:99]
	v_lshl_add_u64 v[232:233], v[232:233], 0, s[98:99]
	global_load_dwordx4 v[214:217], v[230:231], off
	s_waitcnt vmcnt(9)
; __device__ __forceinline__ float bflo(unsigned w) { return __uint_as_float(w << 16); }
; __device__ __forceinline__ float bfhi(unsigned w) { return __uint_as_float(w & 0xffff0000u); }
;     __device__ __forceinline__ void mid(f32x4 (&acc)[2][2][4][2], const Unit& u, int wr, int wc, int fr, int fq) const {
;     ...
;             for (int m = 0; m < 4; ++m) { const bf16_t* pr = P + (size_t)(row0 + ai * HALF + m * 16) * NP + col0;
; #pragma unroll
;                 for (int bj = 0; bj < 2; ++bj) { const u32x4 a = *(const u32x4*)(pr + PC_GA + bj * HALF), b = *(const u32x4*)(pr + PC_GB + bj * HALF);
;                     const f32x4 b0 = {bflo(b.x), bfhi(b.x), bflo(b.y), bfhi(b.y)}, b1 = {bflo(b.z), bfhi(b.z), bflo(b.w), bfhi(b.w)};
;                     const f32x4 a0 = {bflo(a.x), bfhi(a.x), bflo(a.y), bfhi(a.y)}, a1 = {bflo(a.z), bfhi(a.z), bflo(a.w), bfhi(a.w)};
;                     f32x4 r0, r1;
; #pragma unroll
;                     for (int j = 0; j < 4; ++j) { r0[j] = a0[j] * __builtin_amdgcn_rcpf(fmaxf(b0[j], 1e-30f)); r1[j] = a1[j] * __builtin_amdgcn_rcpf(fmaxf(b1[j], 1e-30f)); }
;                     acc[ai][bj][m][0] *= r0; acc[ai][bj][m][1] *= r1; }
	v_mov_b32_e32 v170, v218
	v_mov_b32_e32 v171, v219
	v_mov_b32_e32 v172, v220
	v_mov_b32_e32 v173, v221
	global_load_dwordx4 v[218:221], v[232:233], off
	v_lshlrev_b32_e32 v158, 16, v170
	v_and_b32_e32 v159, 0xffff0000, v170
	v_lshlrev_b32_e32 v169, 16, v171
	v_and_b32_e32 v174, 0xffff0000, v171
	v_lshlrev_b32_e32 v170, 16, v172
	v_and_b32_e32 v171, 0xffff0000, v172
	v_max_f32_e32 v158, v158, v158
	v_max_f32_e32 v159, v159, v159
	v_pk_mul_f32 v[128:129], v[128:129], v[176:177]
	v_lshlrev_b32_e32 v175, 16, v173
	v_and_b32_e32 v176, 0xffff0000, v173
	v_max_f32_e32 v158, 0xda24260, v158
	v_max_f32_e32 v170, v170, v170
	v_max_f32_e32 v159, 0xda24260, v159
	v_lshlrev_b32_e32 v172, 16, v130
	v_and_b32_e32 v173, 0xffff0000, v130
	v_max_f32_e32 v130, v171, v171
	v_rcp_f32_e32 v158, v158
	v_max_f32_e32 v170, 0xda24260, v170
	v_rcp_f32_e32 v159, v159
	v_max_f32_e32 v130, 0xda24260, v130
	v_rcp_f32_e32 v170, v170
	v_rcp_f32_e32 v171, v130
	v_max_f32_e32 v130, v169, v169
	v_pk_mul_f32 v[158:159], v[158:159], v[172:173]
	v_lshlrev_b32_e32 v172, 16, v132
	v_and_b32_e32 v173, 0xffff0000, v132
	v_max_f32_e32 v130, 0xda24260, v130
	v_pk_mul_f32 v[170:171], v[170:171], v[172:173]
	v_rcp_f32_e32 v172, v130
	v_max_f32_e32 v130, v175, v175
	v_max_f32_e32 v132, v174, v174
	v_lshlrev_b32_e32 v174, 16, v131
	v_and_b32_e32 v175, 0xffff0000, v131
	v_max_f32_e32 v131, v176, v176
	v_max_f32_e32 v130, 0xda24260, v130
	v_max_f32_e32 v131, 0xda24260, v131
	v_rcp_f32_e32 v130, v130
	v_rcp_f32_e32 v131, v131
	v_max_f32_e32 v132, 0xda24260, v132
	v_rcp_f32_e32 v173, v132
	v_lshlrev_b32_e32 v132, 16, v133
	v_and_b32_e32 v133, 0xffff0000, v133
	v_pk_mul_f32 v[130:131], v[130:131], v[132:133]
	v_pk_mul_f32 v[118:119], v[118:119], v[158:159]
	v_pk_mul_f32 v[116:117], v[116:117], v[130:131]
	v_add_u32_e32 v130, 0x90, v168
	v_mad_i64_i32 v[158:159], s[58:59], v130, s78, v[156:157]
	v_pk_mul_f32 v[172:173], v[172:173], v[174:175]
	v_add_co_u32_e32 v174, vcc, s61, v158
	v_pk_mul_f32 v[120:121], v[120:121], v[172:173]
	s_nop 0
	v_addc_co_u32_e32 v175, vcc, 0, v159, vcc
	v_add_co_u32_e32 v158, vcc, s77, v158
	v_pk_mul_f32 v[114:115], v[114:115], v[170:171]
	s_nop 0
	v_addc_co_u32_e32 v159, vcc, 0, v159, vcc
	s_nop 0
	s_nop 0
	s_waitcnt vmcnt(9)
	v_mov_b32_e32 v130, v222
	v_mov_b32_e32 v131, v223
	v_mov_b32_e32 v132, v224
	v_mov_b32_e32 v133, v225
	global_load_dwordx4 v[222:225], v[230:231], off offset:256
	v_and_b32_e32 v177, 0xffff0000, v130
	s_waitcnt vmcnt(9)
	v_mov_b32_e32 v170, v226
	v_mov_b32_e32 v171, v227
	v_mov_b32_e32 v172, v228
	v_mov_b32_e32 v173, v229
	global_load_dwordx4 v[226:229], v[232:233], off offset:256
	v_lshlrev_b32_e32 v169, 16, v170
	v_max_f32_e32 v169, v169, v169
	v_lshlrev_b32_e32 v178, 16, v171
	v_and_b32_e32 v179, 0xffff0000, v171
	v_lshlrev_b32_e32 v171, 16, v172
	v_max_f32_e32 v169, 0xda24260, v169
	v_and_b32_e32 v176, 0xffff0000, v170
	v_rcp_f32_e32 v170, v169
	v_max_f32_e32 v169, v171, v171
	v_max_f32_e32 v169, 0xda24260, v169
	v_and_b32_e32 v180, 0xffff0000, v172
	v_rcp_f32_e32 v172, v169
	v_max_f32_e32 v169, v176, v176
	v_max_f32_e32 v169, 0xda24260, v169
	v_lshlrev_b32_e32 v176, 16, v130
	v_max_f32_e32 v130, v180, v180
	v_rcp_f32_e32 v171, v169
	v_max_f32_e32 v130, 0xda24260, v130
	v_lshlrev_b32_e32 v181, 16, v173
	v_and_b32_e32 v182, 0xffff0000, v173
	v_rcp_f32_e32 v173, v130
	v_max_f32_e32 v130, v178, v178
	v_pk_mul_f32 v[170:171], v[170:171], v[176:177]
	v_lshlrev_b32_e32 v176, 16, v132
	v_and_b32_e32 v177, 0xffff0000, v132
	v_max_f32_e32 v130, 0xda24260, v130
	v_pk_mul_f32 v[172:173], v[172:173], v[176:177]
	v_rcp_f32_e32 v176, v130
	v_max_f32_e32 v130, v181, v181
	v_lshlrev_b32_e32 v180, 16, v131
	v_and_b32_e32 v181, 0xffff0000, v131
	v_max_f32_e32 v131, v182, v182
	v_max_f32_e32 v130, 0xda24260, v130
	v_max_f32_e32 v131, 0xda24260, v131
	v_rcp_f32_e32 v130, v130
	v_rcp_f32_e32 v131, v131
	v_max_f32_e32 v132, v179, v179
	v_max_f32_e32 v132, 0xda24260, v132
	v_rcp_f32_e32 v177, v132
	v_lshlrev_b32_e32 v132, 16, v133
	v_and_b32_e32 v133, 0xffff0000, v133
	v_pk_mul_f32 v[130:131], v[130:131], v[132:133]
	v_pk_mul_f32 v[102:103], v[102:103], v[170:171]
	v_pk_mul_f32 v[100:101], v[100:101], v[130:131]
	v_pk_mul_f32 v[98:99], v[98:99], v[172:173]
	s_nop 0
	s_nop 0
	v_pk_mul_f32 v[176:177], v[176:177], v[180:181]
	s_waitcnt vmcnt(9)
	v_mov_b32_e32 v130, v184
	v_mov_b32_e32 v131, v185
	v_mov_b32_e32 v132, v186
	v_mov_b32_e32 v133, v187
	s_waitcnt vmcnt(8)
	v_mov_b32_e32 v170, v188
	v_mov_b32_e32 v171, v189
	v_mov_b32_e32 v172, v190
	v_mov_b32_e32 v173, v191
	v_lshlrev_b32_e32 v158, 16, v170
	v_and_b32_e32 v159, 0xffff0000, v170
	v_lshlrev_b32_e32 v169, 16, v171
	v_and_b32_e32 v174, 0xffff0000, v171
	v_lshlrev_b32_e32 v170, 16, v172
	v_and_b32_e32 v171, 0xffff0000, v172
	v_max_f32_e32 v158, v158, v158
	v_max_f32_e32 v159, v159, v159
	v_pk_mul_f32 v[104:105], v[104:105], v[176:177]
	v_lshlrev_b32_e32 v175, 16, v173
	v_and_b32_e32 v176, 0xffff0000, v173
	v_max_f32_e32 v158, 0xda24260, v158
	v_max_f32_e32 v170, v170, v170
	v_max_f32_e32 v159, 0xda24260, v159
	v_lshlrev_b32_e32 v172, 16, v130
	v_and_b32_e32 v173, 0xffff0000, v130
	v_max_f32_e32 v130, v171, v171
	v_rcp_f32_e32 v158, v158
	v_max_f32_e32 v170, 0xda24260, v170
	v_rcp_f32_e32 v159, v159
	v_max_f32_e32 v130, 0xda24260, v130
	v_rcp_f32_e32 v170, v170
	v_rcp_f32_e32 v171, v130
	v_max_f32_e32 v130, v169, v169
	v_pk_mul_f32 v[158:159], v[158:159], v[172:173]
	v_lshlrev_b32_e32 v172, 16, v132
	v_and_b32_e32 v173, 0xffff0000, v132
	v_max_f32_e32 v130, 0xda24260, v130
	v_pk_mul_f32 v[170:171], v[170:171], v[172:173]
	v_rcp_f32_e32 v172, v130
	v_max_f32_e32 v130, v175, v175
	v_max_f32_e32 v132, v174, v174
	v_lshlrev_b32_e32 v174, 16, v131
	v_and_b32_e32 v175, 0xffff0000, v131
	v_max_f32_e32 v131, v176, v176
	v_max_f32_e32 v130, 0xda24260, v130
	v_max_f32_e32 v131, 0xda24260, v131
	v_rcp_f32_e32 v130, v130
	v_rcp_f32_e32 v131, v131
	v_max_f32_e32 v132, 0xda24260, v132
	v_rcp_f32_e32 v173, v132
	v_lshlrev_b32_e32 v132, 16, v133
	v_and_b32_e32 v133, 0xffff0000, v133
	v_pk_mul_f32 v[130:131], v[130:131], v[132:133]
	v_pk_mul_f32 v[78:79], v[78:79], v[158:159]
	v_pk_mul_f32 v[76:77], v[76:77], v[130:131]
	v_add_u32_e32 v130, 0xa0, v168
	v_mad_i64_i32 v[158:159], s[58:59], v130, s78, v[156:157]
	v_pk_mul_f32 v[172:173], v[172:173], v[174:175]
	v_add_co_u32_e32 v174, vcc, s61, v158
	v_pk_mul_f32 v[80:81], v[80:81], v[172:173]
	s_nop 0
	v_addc_co_u32_e32 v175, vcc, 0, v159, vcc
	v_add_co_u32_e32 v158, vcc, s77, v158
	v_pk_mul_f32 v[74:75], v[74:75], v[170:171]
	s_nop 0
	v_addc_co_u32_e32 v159, vcc, 0, v159, vcc
	s_nop 0
	s_nop 0
	s_waitcnt vmcnt(7)
; __device__ __forceinline__ float bflo(unsigned w) { return __uint_as_float(w << 16); }
; __device__ __forceinline__ float bfhi(unsigned w) { return __uint_as_float(w & 0xffff0000u); }
;     __device__ __forceinline__ void mid(f32x4 (&acc)[2][2][4][2], const Unit& u, int wr, int wc, int fr, int fq) const {
;     ...
;             for (int m = 0; m < 4; ++m) { const bf16_t* pr = P + (size_t)(row0 + ai * HALF + m * 16) * NP + col0;
; #pragma unroll
;                 for (int bj = 0; bj < 2; ++bj) { const u32x4 a = *(const u32x4*)(pr + PC_GA + bj * HALF), b = *(const u32x4*)(pr + PC_GB + bj * HALF);
;                     const f32x4 b0 = {bflo(b.x), bfhi(b.x), bflo(b.y), bfhi(b.y)}, b1 = {bflo(b.z), bfhi(b.z), bflo(b.w), bfhi(b.w)};
;                     const f32x4 a0 = {bflo(a.x), bfhi(a.x), bflo(a.y), bfhi(a.y)}, a1 = {bflo(a.z), bfhi(a.z), bflo(a.w), bfhi(a.w)};
;                     f32x4 r0, r1;
; #pragma unroll
;                     for (int j = 0; j < 4; ++j) { r0[j] = a0[j] * __builtin_amdgcn_rcpf(fmaxf(b0[j], 1e-30f)); r1[j] = a1[j] * __builtin_amdgcn_rcpf(fmaxf(b1[j], 1e-30f)); }
;                     acc[ai][bj][m][0] *= r0; acc[ai][bj][m][1] *= r1; }
	v_mov_b32_e32 v130, v198
	v_mov_b32_e32 v131, v199
	v_mov_b32_e32 v132, v200
	v_mov_b32_e32 v133, v201
	v_and_b32_e32 v177, 0xffff0000, v130
	s_waitcnt vmcnt(6)
	v_mov_b32_e32 v170, v202
	v_mov_b32_e32 v171, v203
	v_mov_b32_e32 v172, v204
	v_mov_b32_e32 v173, v205
	v_lshlrev_b32_e32 v169, 16, v170
	v_max_f32_e32 v169, v169, v169
	v_lshlrev_b32_e32 v178, 16, v171
	v_and_b32_e32 v179, 0xffff0000, v171
	v_lshlrev_b32_e32 v171, 16, v172
	v_max_f32_e32 v169, 0xda24260, v169
	v_and_b32_e32 v176, 0xffff0000, v170
	v_rcp_f32_e32 v170, v169
	v_max_f32_e32 v169, v171, v171
	v_max_f32_e32 v169, 0xda24260, v169
	v_and_b32_e32 v180, 0xffff0000, v172
	v_rcp_f32_e32 v172, v169
	v_max_f32_e32 v169, v176, v176
	v_max_f32_e32 v169, 0xda24260, v169
	v_lshlrev_b32_e32 v176, 16, v130
	v_max_f32_e32 v130, v180, v180
	v_rcp_f32_e32 v171, v169
	v_max_f32_e32 v130, 0xda24260, v130
	v_lshlrev_b32_e32 v181, 16, v173
	v_and_b32_e32 v182, 0xffff0000, v173
	v_rcp_f32_e32 v173, v130
	v_max_f32_e32 v130, v178, v178
	v_pk_mul_f32 v[170:171], v[170:171], v[176:177]
	v_lshlrev_b32_e32 v176, 16, v132
	v_and_b32_e32 v177, 0xffff0000, v132
	v_max_f32_e32 v130, 0xda24260, v130
	v_pk_mul_f32 v[172:173], v[172:173], v[176:177]
	v_rcp_f32_e32 v176, v130
	v_max_f32_e32 v130, v181, v181
	v_lshlrev_b32_e32 v180, 16, v131
	v_and_b32_e32 v181, 0xffff0000, v131
	v_max_f32_e32 v131, v182, v182
	v_max_f32_e32 v130, 0xda24260, v130
	v_max_f32_e32 v131, 0xda24260, v131
	v_rcp_f32_e32 v130, v130
	v_rcp_f32_e32 v131, v131
	v_max_f32_e32 v132, v179, v179
	v_max_f32_e32 v132, 0xda24260, v132
	v_rcp_f32_e32 v177, v132
	v_lshlrev_b32_e32 v132, 16, v133
	v_and_b32_e32 v133, 0xffff0000, v133
	v_pk_mul_f32 v[130:131], v[130:131], v[132:133]
	v_pk_mul_f32 v[62:63], v[62:63], v[170:171]
	v_pk_mul_f32 v[60:61], v[60:61], v[130:131]
	v_pk_mul_f32 v[58:59], v[58:59], v[172:173]
	s_nop 0
	s_nop 0
	v_pk_mul_f32 v[176:177], v[176:177], v[180:181]
	s_waitcnt vmcnt(5)
	v_mov_b32_e32 v130, v206
	v_mov_b32_e32 v131, v207
	v_mov_b32_e32 v132, v208
	v_mov_b32_e32 v133, v209
	s_waitcnt vmcnt(4)
	v_mov_b32_e32 v170, v210
	v_mov_b32_e32 v171, v211
	v_mov_b32_e32 v172, v212
	v_mov_b32_e32 v173, v213
	v_lshlrev_b32_e32 v158, 16, v170
	v_and_b32_e32 v159, 0xffff0000, v170
	v_lshlrev_b32_e32 v169, 16, v171
	v_and_b32_e32 v174, 0xffff0000, v171
	v_lshlrev_b32_e32 v170, 16, v172
	v_and_b32_e32 v171, 0xffff0000, v172
	v_max_f32_e32 v158, v158, v158
	v_max_f32_e32 v159, v159, v159
	v_pk_mul_f32 v[64:65], v[64:65], v[176:177]
	v_lshlrev_b32_e32 v175, 16, v173
	v_and_b32_e32 v176, 0xffff0000, v173
	v_max_f32_e32 v158, 0xda24260, v158
	v_max_f32_e32 v170, v170, v170
	v_max_f32_e32 v159, 0xda24260, v159
	v_lshlrev_b32_e32 v172, 16, v130
	v_and_b32_e32 v173, 0xffff0000, v130
	v_max_f32_e32 v130, v171, v171
	v_rcp_f32_e32 v158, v158
	v_max_f32_e32 v170, 0xda24260, v170
	v_rcp_f32_e32 v159, v159
	v_max_f32_e32 v130, 0xda24260, v130
	v_rcp_f32_e32 v170, v170
	v_rcp_f32_e32 v171, v130
	v_max_f32_e32 v130, v169, v169
	v_pk_mul_f32 v[158:159], v[158:159], v[172:173]
	v_lshlrev_b32_e32 v172, 16, v132
	v_and_b32_e32 v173, 0xffff0000, v132
	v_max_f32_e32 v130, 0xda24260, v130
	v_pk_mul_f32 v[170:171], v[170:171], v[172:173]
	v_rcp_f32_e32 v172, v130
	v_max_f32_e32 v130, v175, v175
	v_max_f32_e32 v132, v174, v174
	v_lshlrev_b32_e32 v174, 16, v131
	v_and_b32_e32 v175, 0xffff0000, v131
	v_max_f32_e32 v131, v176, v176
	v_max_f32_e32 v130, 0xda24260, v130
	v_max_f32_e32 v131, 0xda24260, v131
	v_rcp_f32_e32 v130, v130
	v_rcp_f32_e32 v131, v131
	v_max_f32_e32 v132, 0xda24260, v132
	v_rcp_f32_e32 v173, v132
	v_lshlrev_b32_e32 v132, 16, v133
	v_and_b32_e32 v133, 0xffff0000, v133
	v_pk_mul_f32 v[130:131], v[130:131], v[132:133]
	v_pk_mul_f32 v[46:47], v[46:47], v[158:159]
	v_pk_mul_f32 v[44:45], v[44:45], v[130:131]
	v_add_u32_e32 v130, 0xb0, v168
	v_mad_i64_i32 v[156:157], s[58:59], v130, s78, v[156:157]
	v_add_co_u32_e32 v158, vcc, s61, v156
	v_pk_mul_f32 v[42:43], v[42:43], v[170:171]
	s_nop 0
	v_addc_co_u32_e32 v159, vcc, 0, v157, vcc
	v_add_co_u32_e32 v156, vcc, s77, v156
	s_nop 0
	s_nop 0
	v_addc_co_u32_e32 v157, vcc, 0, v157, vcc
	s_nop 0
	v_pk_mul_f32 v[172:173], v[172:173], v[174:175]
	s_waitcnt vmcnt(3)
; __device__ __forceinline__ float bflo(unsigned w) { return __uint_as_float(w << 16); }
; __device__ __forceinline__ float bfhi(unsigned w) { return __uint_as_float(w & 0xffff0000u); }
;     __device__ __forceinline__ void mid(f32x4 (&acc)[2][2][4][2], const Unit& u, int wr, int wc, int fr, int fq) const {
;     ...
;             for (int m = 0; m < 4; ++m) { const bf16_t* pr = P + (size_t)(row0 + ai * HALF + m * 16) * NP + col0;
; #pragma unroll
;                 for (int bj = 0; bj < 2; ++bj) { const u32x4 a = *(const u32x4*)(pr + PC_GA + bj * HALF), b = *(const u32x4*)(pr + PC_GB + bj * HALF);
;                     const f32x4 b0 = {bflo(b.x), bfhi(b.x), bflo(b.y), bfhi(b.y)}, b1 = {bflo(b.z), bfhi(b.z), bflo(b.w), bfhi(b.w)};
;                     const f32x4 a0 = {bflo(a.x), bfhi(a.x), bflo(a.y), bfhi(a.y)}, a1 = {bflo(a.z), bfhi(a.z), bflo(a.w), bfhi(a.w)};
;                     f32x4 r0, r1;
; #pragma unroll
;                     for (int j = 0; j < 4; ++j) { r0[j] = a0[j] * __builtin_amdgcn_rcpf(fmaxf(b0[j], 1e-30f)); r1[j] = a1[j] * __builtin_amdgcn_rcpf(fmaxf(b1[j], 1e-30f)); }
;                     acc[ai][bj][m][0] *= r0; acc[ai][bj][m][1] *= r1; }
;                 asm volatile("" ::: "memory"); }
	v_mov_b32_e32 v130, v214
	v_mov_b32_e32 v131, v215
	v_mov_b32_e32 v132, v216
	v_mov_b32_e32 v133, v217
	s_waitcnt vmcnt(2)
	v_mov_b32_e32 v168, v218
	v_mov_b32_e32 v169, v219
	v_mov_b32_e32 v170, v220
	v_mov_b32_e32 v171, v221
	v_lshlrev_b32_e32 v174, 16, v169
	v_and_b32_e32 v175, 0xffff0000, v169
	v_lshlrev_b32_e32 v169, 16, v170
	v_max_f32_e32 v169, v169, v169
	v_pk_mul_f32 v[48:49], v[48:49], v[172:173]
	v_lshlrev_b32_e32 v172, 16, v168
	v_and_b32_e32 v173, 0xffff0000, v168
	v_max_f32_e32 v169, 0xda24260, v169
	v_and_b32_e32 v176, 0xffff0000, v170
	v_max_f32_e32 v168, v172, v172
	v_rcp_f32_e32 v170, v169
	v_max_f32_e32 v169, v173, v173
	v_max_f32_e32 v168, 0xda24260, v168
	v_max_f32_e32 v169, 0xda24260, v169
	v_lshlrev_b32_e32 v172, 16, v130
	v_and_b32_e32 v173, 0xffff0000, v130
	v_max_f32_e32 v130, v176, v176
	v_rcp_f32_e32 v168, v168
	v_rcp_f32_e32 v169, v169
	v_max_f32_e32 v130, 0xda24260, v130
	v_lshlrev_b32_e32 v177, 16, v171
	v_and_b32_e32 v178, 0xffff0000, v171
	v_rcp_f32_e32 v171, v130
	v_max_f32_e32 v130, v174, v174
	v_pk_mul_f32 v[168:169], v[168:169], v[172:173]
	v_lshlrev_b32_e32 v172, 16, v132
	v_and_b32_e32 v173, 0xffff0000, v132
	v_max_f32_e32 v130, 0xda24260, v130
	v_pk_mul_f32 v[170:171], v[170:171], v[172:173]
	v_rcp_f32_e32 v172, v130
	v_max_f32_e32 v130, v177, v177
	v_max_f32_e32 v132, v175, v175
	v_lshlrev_b32_e32 v174, 16, v131
	v_and_b32_e32 v175, 0xffff0000, v131
	v_max_f32_e32 v131, v178, v178
	v_max_f32_e32 v130, 0xda24260, v130
	v_max_f32_e32 v131, 0xda24260, v131
	v_rcp_f32_e32 v130, v130
	v_rcp_f32_e32 v131, v131
	v_max_f32_e32 v132, 0xda24260, v132
	v_rcp_f32_e32 v173, v132
	v_lshlrev_b32_e32 v132, 16, v133
	v_and_b32_e32 v133, 0xffff0000, v133
	v_pk_mul_f32 v[130:131], v[130:131], v[132:133]
	v_pk_mul_f32 v[18:19], v[18:19], v[170:171]
	v_pk_mul_f32 v[20:21], v[20:21], v[130:131]
	s_nop 0
	s_nop 0
	s_nop 0
	v_pk_mul_f32 v[172:173], v[172:173], v[174:175]
	v_pk_mul_f32 v[22:23], v[22:23], v[168:169]
	v_pk_mul_f32 v[24:25], v[24:25], v[172:173]
	s_waitcnt vmcnt(1)
	v_mov_b32_e32 v130, v222
	v_mov_b32_e32 v131, v223
	v_mov_b32_e32 v132, v224
	v_mov_b32_e32 v133, v225
	s_waitcnt vmcnt(0)
	v_mov_b32_e32 v156, v226
	v_mov_b32_e32 v157, v227
	v_mov_b32_e32 v158, v228
	v_mov_b32_e32 v159, v229
	v_lshlrev_b32_e32 v170, 16, v157
	v_and_b32_e32 v171, 0xffff0000, v157
	v_lshlrev_b32_e32 v157, 16, v158
	v_max_f32_e32 v157, v157, v157
	v_lshlrev_b32_e32 v168, 16, v156
	v_and_b32_e32 v169, 0xffff0000, v156
	v_max_f32_e32 v157, 0xda24260, v157
	v_and_b32_e32 v172, 0xffff0000, v158
	v_max_f32_e32 v156, v168, v168
	v_rcp_f32_e32 v158, v157
	v_max_f32_e32 v157, v169, v169
	v_max_f32_e32 v156, 0xda24260, v156
	v_max_f32_e32 v157, 0xda24260, v157
	v_lshlrev_b32_e32 v168, 16, v130
	v_and_b32_e32 v169, 0xffff0000, v130
	v_max_f32_e32 v130, v172, v172
	v_rcp_f32_e32 v156, v156
	v_rcp_f32_e32 v157, v157
	v_max_f32_e32 v130, 0xda24260, v130
	v_lshlrev_b32_e32 v173, 16, v159
	v_and_b32_e32 v174, 0xffff0000, v159
	v_rcp_f32_e32 v159, v130
	v_max_f32_e32 v130, v170, v170
	v_pk_mul_f32 v[156:157], v[156:157], v[168:169]
	v_lshlrev_b32_e32 v168, 16, v132
	v_and_b32_e32 v169, 0xffff0000, v132
	v_max_f32_e32 v130, 0xda24260, v130
	v_pk_mul_f32 v[158:159], v[158:159], v[168:169]
	v_rcp_f32_e32 v168, v130
	v_max_f32_e32 v130, v173, v173
	v_max_f32_e32 v132, v171, v171
	v_lshlrev_b32_e32 v170, 16, v131
	v_and_b32_e32 v171, 0xffff0000, v131
	v_max_f32_e32 v131, v174, v174
	v_max_f32_e32 v130, 0xda24260, v130
	v_max_f32_e32 v132, 0xda24260, v132
	v_max_f32_e32 v131, 0xda24260, v131
	v_rcp_f32_e32 v130, v130
	v_rcp_f32_e32 v169, v132
	v_rcp_f32_e32 v131, v131
	v_lshlrev_b32_e32 v132, 16, v133
	v_and_b32_e32 v133, 0xffff0000, v133
	v_pk_mul_f32 v[168:169], v[168:169], v[170:171]
	v_pk_mul_f32 v[130:131], v[130:131], v[132:133]
	v_pk_mul_f32 v[8:9], v[8:9], v[168:169]
	v_pk_mul_f32 v[6:7], v[6:7], v[156:157]
	v_pk_mul_f32 v[4:5], v[4:5], v[130:131]
	v_pk_mul_f32 v[2:3], v[2:3], v[158:159]

; __host__ __device__ __forceinline__ size_t blk(int r, int k, int K) { return (((size_t)((r >> 8) * (K >> 6) + (k >> 6))) << 14) + (size_t)(((r & 255) << 6) + (k & 63)); }
; __device__ __forceinline__ float bflo(unsigned w) { return __uint_as_float(w << 16); }
; __device__ __forceinline__ float bfhi(unsigned w) { return __uint_as_float(w & 0xffff0000u); }
; __device__ __forceinline__ unsigned pk2(float lo, float hi) { f32x2 v = {lo, hi}; bf16x2_t b = __builtin_convertvector(v, bf16x2_t); return __builtin_bit_cast(unsigned, b); }
;     __device__ __forceinline__ void operator()(const f32x4 (&acc)[2][2][4][2], const Unit& u, int wr, int wc, int fr, int fq) const {
;     ...
;             for (int m = 0; m < 4; ++m) { const int row = row0 + ai * HALF + m * 16;
; #pragma unroll
;                 for (int bj = 0; bj < 2; ++bj) { const int c = col0 + bj * HALF; const u32x4 b = *(const u32x4*)(P + (size_t)row * NP + PC_GB + c);
;                     const f32x4 b0 = {bflo(b.x), bfhi(b.x), bflo(b.y), bfhi(b.y)}, b1 = {bflo(b.z), bfhi(b.z), bflo(b.w), bfhi(b.w)};
;                     const f32x4 v0 = acc[ai][bj][m][0] * b0, v1 = acc[ai][bj][m][1] * b1;
;                     u32x4 w; w.x = pk2(v0[0], v0[1]); w.y = pk2(v0[2], v0[3]); w.z = pk2(v1[0], v1[1]); w.w = pk2(v1[2], v1[3]);
;                     *(u32x4*)(MG + blk(row, c, D)) = w; } }
.LBB0_687:
	s_or_b32 s33, s39, s74
	v_or_b32_e32 v130, s33, v1
	v_mov_b64_e32 v[132:133], s[24:25]
	v_ashrrev_i32_e32 v131, 31, v130
	v_mad_i64_i32 v[156:157], s[26:27], v166, s78, v[132:133]
	v_lshl_add_u64 v[172:173], v[156:157], 0, s[8:9]
	v_lshlrev_b64 v[156:157], 1, v[130:131]
	v_lshl_add_u64 v[158:159], v[172:173], 0, v[156:157]
	v_lshl_add_u64 v[230:231], v[172:173], 0, v[156:157]
	global_load_dwordx4 v[168:171], v[158:159], off
	s_mov_b32 s98, 0xa0000
	s_mov_b32 s99, 0
	s_mov_b32 s100, 0x320000
	s_mov_b32 s101, 0
	global_load_dwordx4 v[184:187], v[230:231], off offset:256
	v_lshl_add_u64 v[230:231], v[230:231], 0, s[98:99]
	global_load_dwordx4 v[188:191], v[230:231], off
	global_load_dwordx4 v[198:201], v[230:231], off offset:256
	v_lshl_add_u64 v[230:231], v[230:231], 0, s[98:99]
	global_load_dwordx4 v[202:205], v[230:231], off
	global_load_dwordx4 v[206:209], v[230:231], off offset:256
	v_lshl_add_u64 v[230:231], v[230:231], 0, s[98:99]
	global_load_dwordx4 v[210:213], v[230:231], off
	global_load_dwordx4 v[214:217], v[230:231], off offset:256
	v_lshl_add_u64 v[230:231], v[230:231], 0, s[100:101]
	global_load_dwordx4 v[218:221], v[230:231], off
	global_load_dwordx4 v[222:225], v[230:231], off offset:256
	v_lshl_add_u64 v[230:231], v[230:231], 0, s[98:99]
	global_load_dwordx4 v[226:229], v[230:231], off
	v_ashrrev_i32_e32 v131, 2, v166
	s_ashr_i32 s26, s33, 6
	v_and_b32_e32 v159, 0xffffffc0, v131
	v_add_u32_e32 v176, s26, v159
	v_bitop3_b32 v158, s33, 56, v1 bitop3:0xc8
	v_lshlrev_b32_e32 v142, 6, v166
	v_ashrrev_i32_e32 v177, 31, v176
	v_and_or_b32 v131, v142, s82, v158
	v_or_b32_e32 v174, 0x80, v130
	v_lshlrev_b64 v[176:177], 15, v[176:177]
	v_lshlrev_b32_e32 v142, 1, v131
	v_ashrrev_i32_e32 v175, 31, v174
	v_lshl_add_u64 v[176:177], s[66:67], 0, v[176:177]
	v_lshlrev_b64 v[130:131], 1, v[174:175]
	v_lshl_add_u64 v[176:177], v[176:177], 0, v[142:143]
	v_lshl_add_u64 v[172:173], v[172:173], 0, v[130:131]
	s_andn2_b64 vcc, exec, s[0:1]
	s_mov_b64 s[0:1], -1
	s_waitcnt vmcnt(0)
	v_lshlrev_b32_e32 v180, 16, v168
	v_and_b32_e32 v181, 0xffff0000, v168
	v_lshlrev_b32_e32 v168, 16, v169
	v_and_b32_e32 v169, 0xffff0000, v169
	v_lshlrev_b32_e32 v182, 16, v170
	v_and_b32_e32 v183, 0xffff0000, v170
	v_lshlrev_b32_e32 v170, 16, v171
	v_and_b32_e32 v171, 0xffff0000, v171
	v_pk_mul_f32 v[16:17], v[16:17], v[168:169]
	v_pk_mul_f32 v[14:15], v[14:15], v[180:181]
	v_pk_mul_f32 v[168:169], v[12:13], v[170:171]
	v_pk_mul_f32 v[12:13], v[10:11], v[182:183]
	v_cvt_pk_bf16_f32 v10, v14, v15
	v_cvt_pk_bf16_f32 v11, v16, v17
	v_cvt_pk_bf16_f32 v12, v12, v13
	v_cvt_pk_bf16_f32 v13, v168, v169
	global_store_dwordx4 v[176:177], v[10:13], off
	s_nop 1
	v_mov_b32_e32 v12, v184
	v_mov_b32_e32 v13, v185
	v_mov_b32_e32 v14, v186
	v_mov_b32_e32 v15, v187
	v_lshlrev_b32_e32 v172, 16, v12
	v_ashrrev_i32_e32 v10, 6, v174
	v_add_u32_e32 v168, v159, v10
	v_ashrrev_i32_e32 v169, 31, v168
	v_add_u32_e32 v11, 16, v166
	v_lshlrev_b64 v[168:169], 15, v[168:169]
	v_and_b32_e32 v173, 0xffff0000, v12
	v_lshlrev_b32_e32 v12, 16, v13
	v_and_b32_e32 v13, 0xffff0000, v13
	v_lshlrev_b32_e32 v174, 16, v14
	v_and_b32_e32 v175, 0xffff0000, v14
	v_lshlrev_b32_e32 v14, 16, v15
	v_and_b32_e32 v15, 0xffff0000, v15
	v_mad_i64_i32 v[16:17], s[48:49], v11, s78, v[132:133]
	v_lshl_add_u64 v[168:169], s[66:67], 0, v[168:169]
	v_pk_mul_f32 v[32:33], v[32:33], v[12:13]
	v_pk_mul_f32 v[12:13], v[30:31], v[172:173]
	v_pk_mul_f32 v[28:29], v[28:29], v[14:15]
	v_pk_mul_f32 v[14:15], v[26:27], v[174:175]
	v_lshl_add_u64 v[16:17], v[16:17], 0, s[8:9]
	v_lshl_add_u64 v[168:169], v[168:169], 0, v[142:143]
	v_cvt_pk_bf16_f32 v12, v12, v13
	v_cvt_pk_bf16_f32 v13, v32, v33
	v_cvt_pk_bf16_f32 v14, v14, v15
	v_cvt_pk_bf16_f32 v15, v28, v29
	v_lshl_add_u64 v[170:171], v[16:17], 0, v[156:157]
	global_store_dwordx4 v[168:169], v[12:15], off
	s_nop 1
	v_ashrrev_i32_e32 v26, 2, v11
	v_and_b32_e32 v159, 0xffffffc0, v26
	v_add_u32_e32 v26, s26, v159
	v_lshlrev_b32_e32 v11, 6, v11
	v_ashrrev_i32_e32 v27, 31, v26
	v_and_or_b32 v11, v11, s82, v158
	v_lshlrev_b64 v[26:27], 15, v[26:27]
	v_lshl_add_u64 v[26:27], s[66:67], 0, v[26:27]
	v_lshlrev_b32_e32 v142, 1, v11
	v_lshl_add_u64 v[26:27], v[26:27], 0, v[142:143]
	v_lshl_add_u64 v[16:17], v[16:17], 0, v[130:131]
	v_add_u32_e32 v11, 32, v166
	v_mov_b32_e32 v12, v188
	v_mov_b32_e32 v13, v189
	v_mov_b32_e32 v14, v190
	v_mov_b32_e32 v15, v191
	v_lshlrev_b32_e32 v28, 16, v12
	v_and_b32_e32 v29, 0xffff0000, v12
	v_lshlrev_b32_e32 v12, 16, v13
	v_and_b32_e32 v13, 0xffff0000, v13
	v_lshlrev_b32_e32 v30, 16, v14
	v_and_b32_e32 v31, 0xffff0000, v14
	v_lshlrev_b32_e32 v14, 16, v15
	v_and_b32_e32 v15, 0xffff0000, v15
	v_pk_mul_f32 v[32:33], v[40:41], v[12:13]
	v_pk_mul_f32 v[12:13], v[38:39], v[28:29]
	v_pk_mul_f32 v[28:29], v[36:37], v[14:15]
	v_pk_mul_f32 v[14:15], v[34:35], v[30:31]
	v_cvt_pk_bf16_f32 v12, v12, v13
	v_cvt_pk_bf16_f32 v13, v32, v33
	v_cvt_pk_bf16_f32 v14, v14, v15
	v_cvt_pk_bf16_f32 v15, v28, v29
	global_store_dwordx4 v[26:27], v[12:15], off
	s_nop 1
	v_add_u32_e32 v26, v159, v10
	v_ashrrev_i32_e32 v27, 31, v26
	v_lshlrev_b64 v[26:27], 15, v[26:27]
	v_mad_i64_i32 v[16:17], s[48:49], v11, s78, v[132:133]
	v_lshl_add_u64 v[26:27], s[66:67], 0, v[26:27]
	v_lshl_add_u64 v[16:17], v[16:17], 0, s[8:9]
	v_lshl_add_u64 v[26:27], v[26:27], 0, v[142:143]
	v_lshl_add_u64 v[28:29], v[16:17], 0, v[156:157]
	v_lshl_add_u64 v[16:17], v[16:17], 0, v[130:131]
	v_mov_b32_e32 v12, v198
	v_mov_b32_e32 v13, v199
	v_mov_b32_e32 v14, v200
	v_mov_b32_e32 v15, v201
	v_lshlrev_b32_e32 v30, 16, v12
	v_and_b32_e32 v31, 0xffff0000, v12
	v_lshlrev_b32_e32 v12, 16, v13
; __host__ __device__ __forceinline__ size_t blk(int r, int k, int K) { return (((size_t)((r >> 8) * (K >> 6) + (k >> 6))) << 14) + (size_t)(((r & 255) << 6) + (k & 63)); }
; __device__ __forceinline__ float bflo(unsigned w) { return __uint_as_float(w << 16); }
; __device__ __forceinline__ float bfhi(unsigned w) { return __uint_as_float(w & 0xffff0000u); }
; __device__ __forceinline__ unsigned pk2(float lo, float hi) { f32x2 v = {lo, hi}; bf16x2_t b = __builtin_convertvector(v, bf16x2_t); return __builtin_bit_cast(unsigned, b); }
;     __device__ __forceinline__ void operator()(const f32x4 (&acc)[2][2][4][2], const Unit& u, int wr, int wc, int fr, int fq) const {
;     ...
;             for (int m = 0; m < 4; ++m) { const int row = row0 + ai * HALF + m * 16;
; #pragma unroll
;                 for (int bj = 0; bj < 2; ++bj) { const int c = col0 + bj * HALF; const u32x4 b = *(const u32x4*)(P + (size_t)row * NP + PC_GB + c);
;                     const f32x4 b0 = {bflo(b.x), bfhi(b.x), bflo(b.y), bfhi(b.y)}, b1 = {bflo(b.z), bfhi(b.z), bflo(b.w), bfhi(b.w)};
;                     const f32x4 v0 = acc[ai][bj][m][0] * b0, v1 = acc[ai][bj][m][1] * b1;
;                     u32x4 w; w.x = pk2(v0[0], v0[1]); w.y = pk2(v0[2], v0[3]); w.z = pk2(v1[0], v1[1]); w.w = pk2(v1[2], v1[3]);
;                     *(u32x4*)(MG + blk(row, c, D)) = w; } }
	v_and_b32_e32 v13, 0xffff0000, v13
	v_lshlrev_b32_e32 v32, 16, v14
	v_and_b32_e32 v33, 0xffff0000, v14
	v_lshlrev_b32_e32 v14, 16, v15
	v_and_b32_e32 v15, 0xffff0000, v15
	v_pk_mul_f32 v[34:35], v[56:57], v[12:13]
	v_pk_mul_f32 v[12:13], v[54:55], v[30:31]
	v_pk_mul_f32 v[30:31], v[52:53], v[14:15]
	v_pk_mul_f32 v[14:15], v[50:51], v[32:33]
	v_cvt_pk_bf16_f32 v12, v12, v13
	v_cvt_pk_bf16_f32 v13, v34, v35
	v_cvt_pk_bf16_f32 v14, v14, v15
	v_cvt_pk_bf16_f32 v15, v30, v31
	global_store_dwordx4 v[26:27], v[12:15], off
	s_nop 1
	v_ashrrev_i32_e32 v26, 2, v11
	v_and_b32_e32 v34, 0xffffffc0, v26
	v_add_u32_e32 v26, s26, v34
	v_lshlrev_b32_e32 v11, 6, v11
	v_ashrrev_i32_e32 v27, 31, v26
	v_and_or_b32 v11, v11, s82, v158
	v_lshlrev_b64 v[26:27], 15, v[26:27]
	v_lshl_add_u64 v[26:27], s[66:67], 0, v[26:27]
	v_lshlrev_b32_e32 v142, 1, v11
	v_lshl_add_u64 v[26:27], v[26:27], 0, v[142:143]
	v_add_u32_e32 v11, 48, v166
	v_mov_b32_e32 v12, v202
	v_mov_b32_e32 v13, v203
	v_mov_b32_e32 v14, v204
	v_mov_b32_e32 v15, v205
	v_lshlrev_b32_e32 v28, 16, v12
	v_and_b32_e32 v29, 0xffff0000, v12
	v_lshlrev_b32_e32 v12, 16, v13
	v_and_b32_e32 v13, 0xffff0000, v13
	v_lshlrev_b32_e32 v30, 16, v14
	v_and_b32_e32 v31, 0xffff0000, v14
	v_lshlrev_b32_e32 v14, 16, v15
	v_and_b32_e32 v15, 0xffff0000, v15
	v_pk_mul_f32 v[32:33], v[72:73], v[12:13]
	v_pk_mul_f32 v[12:13], v[70:71], v[28:29]
	v_pk_mul_f32 v[28:29], v[68:69], v[14:15]
	v_pk_mul_f32 v[14:15], v[66:67], v[30:31]
	v_cvt_pk_bf16_f32 v12, v12, v13
	v_cvt_pk_bf16_f32 v13, v32, v33
	v_cvt_pk_bf16_f32 v14, v14, v15
	v_cvt_pk_bf16_f32 v15, v28, v29
	global_store_dwordx4 v[26:27], v[12:15], off
	s_nop 1
	v_add_u32_e32 v26, v34, v10
	v_ashrrev_i32_e32 v27, 31, v26
	v_lshlrev_b64 v[26:27], 15, v[26:27]
	v_mad_i64_i32 v[16:17], s[48:49], v11, s78, v[132:133]
	v_lshl_add_u64 v[26:27], s[66:67], 0, v[26:27]
	v_lshl_add_u64 v[16:17], v[16:17], 0, s[8:9]
	v_lshl_add_u64 v[26:27], v[26:27], 0, v[142:143]
	v_lshl_add_u64 v[28:29], v[16:17], 0, v[156:157]
	v_lshl_add_u64 v[16:17], v[16:17], 0, v[130:131]
	v_mov_b32_e32 v12, v206
	v_mov_b32_e32 v13, v207
	v_mov_b32_e32 v14, v208
	v_mov_b32_e32 v15, v209
	v_lshlrev_b32_e32 v30, 16, v12
	v_and_b32_e32 v31, 0xffff0000, v12
	v_lshlrev_b32_e32 v12, 16, v13
	v_and_b32_e32 v13, 0xffff0000, v13
	v_lshlrev_b32_e32 v32, 16, v14
	v_and_b32_e32 v33, 0xffff0000, v14
	v_lshlrev_b32_e32 v14, 16, v15
	v_and_b32_e32 v15, 0xffff0000, v15
	v_pk_mul_f32 v[34:35], v[88:89], v[12:13]
	v_pk_mul_f32 v[12:13], v[86:87], v[30:31]
	v_pk_mul_f32 v[30:31], v[84:85], v[14:15]
	v_pk_mul_f32 v[14:15], v[82:83], v[32:33]
	v_cvt_pk_bf16_f32 v12, v12, v13
	v_cvt_pk_bf16_f32 v13, v34, v35
	v_cvt_pk_bf16_f32 v14, v14, v15
	v_cvt_pk_bf16_f32 v15, v30, v31
	global_store_dwordx4 v[26:27], v[12:15], off
	s_nop 1
	v_ashrrev_i32_e32 v26, 2, v11
	v_and_b32_e32 v34, 0xffffffc0, v26
	v_add_u32_e32 v26, s26, v34
	v_lshlrev_b32_e32 v11, 6, v11
	v_ashrrev_i32_e32 v27, 31, v26
	v_and_or_b32 v11, v11, s82, v158
	v_lshlrev_b64 v[26:27], 15, v[26:27]
	v_lshl_add_u64 v[26:27], s[66:67], 0, v[26:27]
	v_lshlrev_b32_e32 v142, 1, v11
	v_lshl_add_u64 v[26:27], v[26:27], 0, v[142:143]
	v_add_u32_e32 v11, 0x80, v166
	v_mov_b32_e32 v12, v210
	v_mov_b32_e32 v13, v211
	v_mov_b32_e32 v14, v212
	v_mov_b32_e32 v15, v213
	global_load_dwordx4 v[184:187], v[230:231], off offset:256
	v_lshl_add_u64 v[230:231], v[230:231], 0, s[98:99]
	global_load_dwordx4 v[188:191], v[230:231], off
	global_load_dwordx4 v[198:201], v[230:231], off offset:256
	v_lshl_add_u64 v[230:231], v[230:231], 0, s[98:99]
	global_load_dwordx4 v[202:205], v[230:231], off
	global_load_dwordx4 v[206:209], v[230:231], off offset:256
	v_lshlrev_b32_e32 v28, 16, v12
	v_and_b32_e32 v29, 0xffff0000, v12
	v_lshlrev_b32_e32 v12, 16, v13
	v_and_b32_e32 v13, 0xffff0000, v13
	v_lshlrev_b32_e32 v30, 16, v14
	v_and_b32_e32 v31, 0xffff0000, v14
	v_lshlrev_b32_e32 v14, 16, v15
	v_and_b32_e32 v15, 0xffff0000, v15
	v_pk_mul_f32 v[32:33], v[96:97], v[12:13]
	v_pk_mul_f32 v[12:13], v[94:95], v[28:29]
	v_pk_mul_f32 v[28:29], v[92:93], v[14:15]
	v_pk_mul_f32 v[14:15], v[90:91], v[30:31]
	v_cvt_pk_bf16_f32 v12, v12, v13
	v_cvt_pk_bf16_f32 v13, v32, v33
	v_cvt_pk_bf16_f32 v14, v14, v15
	v_cvt_pk_bf16_f32 v15, v28, v29
	global_store_dwordx4 v[26:27], v[12:15], off
	s_nop 1
	v_add_u32_e32 v26, v34, v10
	v_ashrrev_i32_e32 v27, 31, v26
	v_lshlrev_b64 v[26:27], 15, v[26:27]
	v_mad_i64_i32 v[16:17], s[48:49], v11, s78, v[132:133]
	v_lshl_add_u64 v[26:27], s[66:67], 0, v[26:27]
	v_lshl_add_u64 v[16:17], v[16:17], 0, s[8:9]
	v_lshl_add_u64 v[26:27], v[26:27], 0, v[142:143]
	v_lshl_add_u64 v[28:29], v[16:17], 0, v[156:157]
	v_lshl_add_u64 v[16:17], v[16:17], 0, v[130:131]
	v_mov_b32_e32 v12, v214
	v_mov_b32_e32 v13, v215
	v_mov_b32_e32 v14, v216
	v_mov_b32_e32 v15, v217
	v_lshlrev_b32_e32 v30, 16, v12
	v_and_b32_e32 v31, 0xffff0000, v12
	v_lshlrev_b32_e32 v12, 16, v13
	v_and_b32_e32 v13, 0xffff0000, v13
	v_lshlrev_b32_e32 v32, 16, v14
	v_and_b32_e32 v33, 0xffff0000, v14
	v_lshlrev_b32_e32 v14, 16, v15
	v_and_b32_e32 v15, 0xffff0000, v15
	v_pk_mul_f32 v[34:35], v[112:113], v[12:13]
	v_pk_mul_f32 v[12:13], v[110:111], v[30:31]
	v_pk_mul_f32 v[30:31], v[108:109], v[14:15]
	v_pk_mul_f32 v[14:15], v[106:107], v[32:33]
	v_cvt_pk_bf16_f32 v12, v12, v13
	v_cvt_pk_bf16_f32 v13, v34, v35
	v_cvt_pk_bf16_f32 v14, v14, v15
	v_cvt_pk_bf16_f32 v15, v30, v31
	global_store_dwordx4 v[26:27], v[12:15], off
	s_nop 1
	v_ashrrev_i32_e32 v26, 2, v11
	v_and_b32_e32 v34, 0xffffffc0, v26
	v_add_u32_e32 v26, s26, v34
	v_lshlrev_b32_e32 v11, 6, v11
	v_ashrrev_i32_e32 v27, 31, v26
	v_and_or_b32 v11, v11, s82, v158
	v_lshlrev_b64 v[26:27], 15, v[26:27]
; __host__ __device__ __forceinline__ size_t blk(int r, int k, int K) { return (((size_t)((r >> 8) * (K >> 6) + (k >> 6))) << 14) + (size_t)(((r & 255) << 6) + (k & 63)); }
; __device__ __forceinline__ float bflo(unsigned w) { return __uint_as_float(w << 16); }
; __device__ __forceinline__ float bfhi(unsigned w) { return __uint_as_float(w & 0xffff0000u); }
; __device__ __forceinline__ unsigned pk2(float lo, float hi) { f32x2 v = {lo, hi}; bf16x2_t b = __builtin_convertvector(v, bf16x2_t); return __builtin_bit_cast(unsigned, b); }
;     __device__ __forceinline__ void operator()(const f32x4 (&acc)[2][2][4][2], const Unit& u, int wr, int wc, int fr, int fq) const {
;     ...
;             for (int m = 0; m < 4; ++m) { const int row = row0 + ai * HALF + m * 16;
; #pragma unroll
;                 for (int bj = 0; bj < 2; ++bj) { const int c = col0 + bj * HALF; const u32x4 b = *(const u32x4*)(P + (size_t)row * NP + PC_GB + c);
;                     const f32x4 b0 = {bflo(b.x), bfhi(b.x), bflo(b.y), bfhi(b.y)}, b1 = {bflo(b.z), bfhi(b.z), bflo(b.w), bfhi(b.w)};
;                     const f32x4 v0 = acc[ai][bj][m][0] * b0, v1 = acc[ai][bj][m][1] * b1;
;                     u32x4 w; w.x = pk2(v0[0], v0[1]); w.y = pk2(v0[2], v0[3]); w.z = pk2(v1[0], v1[1]); w.w = pk2(v1[2], v1[3]);
;                     *(u32x4*)(MG + blk(row, c, D)) = w; } }
	v_lshl_add_u64 v[26:27], s[66:67], 0, v[26:27]
	v_lshlrev_b32_e32 v142, 1, v11
	v_lshl_add_u64 v[26:27], v[26:27], 0, v[142:143]
	v_add_u32_e32 v11, 0x90, v166
	v_mov_b32_e32 v12, v218
	v_mov_b32_e32 v13, v219
	v_mov_b32_e32 v14, v220
	v_mov_b32_e32 v15, v221
	v_lshlrev_b32_e32 v28, 16, v12
	v_and_b32_e32 v29, 0xffff0000, v12
	v_lshlrev_b32_e32 v12, 16, v13
	v_and_b32_e32 v13, 0xffff0000, v13
	v_lshlrev_b32_e32 v30, 16, v14
	v_and_b32_e32 v31, 0xffff0000, v14
	v_lshlrev_b32_e32 v14, 16, v15
	v_and_b32_e32 v15, 0xffff0000, v15
	v_pk_mul_f32 v[32:33], v[128:129], v[12:13]
	v_pk_mul_f32 v[12:13], v[126:127], v[28:29]
	v_pk_mul_f32 v[28:29], v[124:125], v[14:15]
	v_pk_mul_f32 v[14:15], v[122:123], v[30:31]
	v_cvt_pk_bf16_f32 v12, v12, v13
	v_cvt_pk_bf16_f32 v13, v32, v33
	v_cvt_pk_bf16_f32 v14, v14, v15
	v_cvt_pk_bf16_f32 v15, v28, v29
	global_store_dwordx4 v[26:27], v[12:15], off
	s_nop 1
	v_add_u32_e32 v26, v34, v10
	v_ashrrev_i32_e32 v27, 31, v26
	v_lshlrev_b64 v[26:27], 15, v[26:27]
	v_mad_i64_i32 v[16:17], s[48:49], v11, s78, v[132:133]
	v_lshl_add_u64 v[26:27], s[66:67], 0, v[26:27]
	v_lshl_add_u64 v[16:17], v[16:17], 0, s[8:9]
	v_lshl_add_u64 v[26:27], v[26:27], 0, v[142:143]
	v_lshl_add_u64 v[28:29], v[16:17], 0, v[156:157]
	v_lshl_add_u64 v[16:17], v[16:17], 0, v[130:131]
	v_mov_b32_e32 v12, v222
	v_mov_b32_e32 v13, v223
	v_mov_b32_e32 v14, v224
	v_mov_b32_e32 v15, v225
	v_lshlrev_b32_e32 v30, 16, v12
	v_and_b32_e32 v31, 0xffff0000, v12
	v_lshlrev_b32_e32 v12, 16, v13
	v_and_b32_e32 v13, 0xffff0000, v13
	v_lshlrev_b32_e32 v32, 16, v14
	v_and_b32_e32 v33, 0xffff0000, v14
	v_lshlrev_b32_e32 v14, 16, v15
	v_and_b32_e32 v15, 0xffff0000, v15
	v_pk_mul_f32 v[34:35], v[120:121], v[12:13]
	v_pk_mul_f32 v[12:13], v[118:119], v[30:31]
	v_pk_mul_f32 v[30:31], v[116:117], v[14:15]
	v_pk_mul_f32 v[14:15], v[114:115], v[32:33]
	v_cvt_pk_bf16_f32 v12, v12, v13
	v_cvt_pk_bf16_f32 v13, v34, v35
	v_cvt_pk_bf16_f32 v14, v14, v15
	v_cvt_pk_bf16_f32 v15, v30, v31
	global_store_dwordx4 v[26:27], v[12:15], off
	s_nop 1
	v_ashrrev_i32_e32 v26, 2, v11
	v_and_b32_e32 v34, 0xffffffc0, v26
	v_add_u32_e32 v26, s26, v34
	v_lshlrev_b32_e32 v11, 6, v11
	v_ashrrev_i32_e32 v27, 31, v26
	v_and_or_b32 v11, v11, s82, v158
	v_lshlrev_b64 v[26:27], 15, v[26:27]
	v_lshl_add_u64 v[26:27], s[66:67], 0, v[26:27]
	v_lshlrev_b32_e32 v142, 1, v11
	v_lshl_add_u64 v[26:27], v[26:27], 0, v[142:143]
	v_add_u32_e32 v11, 0xa0, v166
	v_mov_b32_e32 v12, v226
	v_mov_b32_e32 v13, v227
	v_mov_b32_e32 v14, v228
	v_mov_b32_e32 v15, v229
	v_lshlrev_b32_e32 v28, 16, v12
	v_and_b32_e32 v29, 0xffff0000, v12
	v_lshlrev_b32_e32 v12, 16, v13
	v_and_b32_e32 v13, 0xffff0000, v13
	v_lshlrev_b32_e32 v30, 16, v14
	v_and_b32_e32 v31, 0xffff0000, v14
	v_lshlrev_b32_e32 v14, 16, v15
	v_and_b32_e32 v15, 0xffff0000, v15
	v_pk_mul_f32 v[32:33], v[104:105], v[12:13]
	v_pk_mul_f32 v[12:13], v[102:103], v[28:29]
	v_pk_mul_f32 v[28:29], v[100:101], v[14:15]
	v_pk_mul_f32 v[14:15], v[98:99], v[30:31]
	v_cvt_pk_bf16_f32 v12, v12, v13
	v_cvt_pk_bf16_f32 v13, v32, v33
	v_cvt_pk_bf16_f32 v14, v14, v15
	v_cvt_pk_bf16_f32 v15, v28, v29
	global_store_dwordx4 v[26:27], v[12:15], off
	s_nop 1
	v_add_u32_e32 v26, v34, v10
	v_ashrrev_i32_e32 v27, 31, v26
	v_lshlrev_b64 v[26:27], 15, v[26:27]
	v_mad_i64_i32 v[16:17], s[48:49], v11, s78, v[132:133]
	v_lshl_add_u64 v[26:27], s[66:67], 0, v[26:27]
	v_lshl_add_u64 v[16:17], v[16:17], 0, s[8:9]
	v_lshl_add_u64 v[26:27], v[26:27], 0, v[142:143]
	v_lshl_add_u64 v[28:29], v[16:17], 0, v[156:157]
	v_lshl_add_u64 v[16:17], v[16:17], 0, v[130:131]
	s_waitcnt vmcnt(4)
; __host__ __device__ __forceinline__ size_t blk(int r, int k, int K) { return (((size_t)((r >> 8) * (K >> 6) + (k >> 6))) << 14) + (size_t)(((r & 255) << 6) + (k & 63)); }
; __device__ __forceinline__ float bflo(unsigned w) { return __uint_as_float(w << 16); }
; __device__ __forceinline__ float bfhi(unsigned w) { return __uint_as_float(w & 0xffff0000u); }
; __device__ __forceinline__ unsigned pk2(float lo, float hi) { f32x2 v = {lo, hi}; bf16x2_t b = __builtin_convertvector(v, bf16x2_t); return __builtin_bit_cast(unsigned, b); }
;     __device__ __forceinline__ void operator()(const f32x4 (&acc)[2][2][4][2], const Unit& u, int wr, int wc, int fr, int fq) const {
;     ...
;             for (int m = 0; m < 4; ++m) { const int row = row0 + ai * HALF + m * 16;
; #pragma unroll
;                 for (int bj = 0; bj < 2; ++bj) { const int c = col0 + bj * HALF; const u32x4 b = *(const u32x4*)(P + (size_t)row * NP + PC_GB + c);
;                     const f32x4 b0 = {bflo(b.x), bfhi(b.x), bflo(b.y), bfhi(b.y)}, b1 = {bflo(b.z), bfhi(b.z), bflo(b.w), bfhi(b.w)};
;                     const f32x4 v0 = acc[ai][bj][m][0] * b0, v1 = acc[ai][bj][m][1] * b1;
;                     u32x4 w; w.x = pk2(v0[0], v0[1]); w.y = pk2(v0[2], v0[3]); w.z = pk2(v1[0], v1[1]); w.w = pk2(v1[2], v1[3]);
;                     *(u32x4*)(MG + blk(row, c, D)) = w; } }
	v_mov_b32_e32 v12, v184
	v_mov_b32_e32 v13, v185
	v_mov_b32_e32 v14, v186
	v_mov_b32_e32 v15, v187
	v_lshlrev_b32_e32 v30, 16, v12
	v_and_b32_e32 v31, 0xffff0000, v12
	v_lshlrev_b32_e32 v12, 16, v13
	v_and_b32_e32 v13, 0xffff0000, v13
	v_lshlrev_b32_e32 v32, 16, v14
	v_and_b32_e32 v33, 0xffff0000, v14
	v_lshlrev_b32_e32 v14, 16, v15
	v_and_b32_e32 v15, 0xffff0000, v15
	v_pk_mul_f32 v[34:35], v[80:81], v[12:13]
	v_pk_mul_f32 v[12:13], v[78:79], v[30:31]
	v_pk_mul_f32 v[30:31], v[76:77], v[14:15]
	v_pk_mul_f32 v[14:15], v[74:75], v[32:33]
	v_cvt_pk_bf16_f32 v12, v12, v13
	v_cvt_pk_bf16_f32 v13, v34, v35
	v_cvt_pk_bf16_f32 v14, v14, v15
	v_cvt_pk_bf16_f32 v15, v30, v31
	global_store_dwordx4 v[26:27], v[12:15], off
	s_nop 1
	v_ashrrev_i32_e32 v26, 2, v11
	v_and_b32_e32 v34, 0xffffffc0, v26
	v_add_u32_e32 v26, s26, v34
	v_lshlrev_b32_e32 v11, 6, v11
	v_ashrrev_i32_e32 v27, 31, v26
	v_and_or_b32 v11, v11, s82, v158
	v_lshlrev_b64 v[26:27], 15, v[26:27]
	v_lshl_add_u64 v[26:27], s[66:67], 0, v[26:27]
	v_lshlrev_b32_e32 v142, 1, v11
	v_lshl_add_u64 v[26:27], v[26:27], 0, v[142:143]
	v_add_u32_e32 v11, 0xb0, v166
	v_mov_b32_e32 v12, v188
	v_mov_b32_e32 v13, v189
	v_mov_b32_e32 v14, v190
	v_mov_b32_e32 v15, v191
	v_lshlrev_b32_e32 v28, 16, v12
	v_and_b32_e32 v29, 0xffff0000, v12
	v_lshlrev_b32_e32 v12, 16, v13
	v_and_b32_e32 v13, 0xffff0000, v13
	v_lshlrev_b32_e32 v30, 16, v14
	v_and_b32_e32 v31, 0xffff0000, v14
	v_lshlrev_b32_e32 v14, 16, v15
	v_and_b32_e32 v15, 0xffff0000, v15
	v_pk_mul_f32 v[32:33], v[64:65], v[12:13]
	v_pk_mul_f32 v[12:13], v[62:63], v[28:29]
	v_pk_mul_f32 v[28:29], v[60:61], v[14:15]
	v_pk_mul_f32 v[14:15], v[58:59], v[30:31]
	v_cvt_pk_bf16_f32 v12, v12, v13
	v_cvt_pk_bf16_f32 v13, v32, v33
	v_cvt_pk_bf16_f32 v14, v14, v15
	v_cvt_pk_bf16_f32 v15, v28, v29
	global_store_dwordx4 v[26:27], v[12:15], off
	s_nop 1
	v_add_u32_e32 v26, v34, v10
	v_ashrrev_i32_e32 v27, 31, v26
	v_lshlrev_b64 v[26:27], 15, v[26:27]
	v_mad_i64_i32 v[16:17], s[48:49], v11, s78, v[132:133]
	v_lshl_add_u64 v[26:27], s[66:67], 0, v[26:27]
	v_lshl_add_u64 v[16:17], v[16:17], 0, s[8:9]
	v_lshl_add_u64 v[26:27], v[26:27], 0, v[142:143]
	v_lshl_add_u64 v[28:29], v[16:17], 0, v[156:157]
	v_lshl_add_u64 v[16:17], v[16:17], 0, v[130:131]
	v_mov_b32_e32 v12, v198
	v_mov_b32_e32 v13, v199
	v_mov_b32_e32 v14, v200
	v_mov_b32_e32 v15, v201
	v_lshlrev_b32_e32 v30, 16, v12
	v_and_b32_e32 v31, 0xffff0000, v12
	v_lshlrev_b32_e32 v12, 16, v13
	v_and_b32_e32 v13, 0xffff0000, v13
	v_lshlrev_b32_e32 v32, 16, v14
	v_and_b32_e32 v33, 0xffff0000, v14
	v_lshlrev_b32_e32 v14, 16, v15
	v_and_b32_e32 v15, 0xffff0000, v15
	v_pk_mul_f32 v[34:35], v[48:49], v[12:13]
	v_pk_mul_f32 v[12:13], v[46:47], v[30:31]
	v_pk_mul_f32 v[30:31], v[44:45], v[14:15]
	v_pk_mul_f32 v[14:15], v[42:43], v[32:33]
	v_cvt_pk_bf16_f32 v12, v12, v13
	v_cvt_pk_bf16_f32 v13, v34, v35
	v_cvt_pk_bf16_f32 v14, v14, v15
	v_cvt_pk_bf16_f32 v15, v30, v31
	global_store_dwordx4 v[26:27], v[12:15], off
	s_nop 1
	v_ashrrev_i32_e32 v26, 2, v11
	v_and_b32_e32 v32, 0xffffffc0, v26
	v_add_u32_e32 v26, s26, v32
	v_lshlrev_b32_e32 v11, 6, v11
	v_ashrrev_i32_e32 v27, 31, v26
	v_and_or_b32 v11, v11, s82, v158
	v_lshlrev_b64 v[26:27], 15, v[26:27]
	v_lshl_add_u64 v[26:27], s[66:67], 0, v[26:27]
	v_lshlrev_b32_e32 v142, 1, v11
	v_lshl_add_u64 v[26:27], v[26:27], 0, v[142:143]
	v_add_u32_e32 v10, v32, v10
	v_ashrrev_i32_e32 v11, 31, v10
	v_lshlrev_b64 v[10:11], 15, v[10:11]
	v_lshl_add_u64 v[10:11], s[66:67], 0, v[10:11]
	v_lshl_add_u64 v[10:11], v[10:11], 0, v[142:143]
	v_mov_b32_e32 v12, v202
	v_mov_b32_e32 v13, v203
	v_mov_b32_e32 v14, v204
	v_mov_b32_e32 v15, v205
	v_lshlrev_b32_e32 v28, 16, v12
	v_and_b32_e32 v29, 0xffff0000, v12
	v_lshlrev_b32_e32 v12, 16, v13
	v_and_b32_e32 v13, 0xffff0000, v13
	v_lshlrev_b32_e32 v30, 16, v14
	v_and_b32_e32 v31, 0xffff0000, v14
	v_lshlrev_b32_e32 v14, 16, v15
	v_and_b32_e32 v15, 0xffff0000, v15
	v_pk_mul_f32 v[24:25], v[24:25], v[12:13]
	v_pk_mul_f32 v[12:13], v[22:23], v[28:29]
	v_pk_mul_f32 v[20:21], v[20:21], v[14:15]
	v_pk_mul_f32 v[14:15], v[18:19], v[30:31]
	v_cvt_pk_bf16_f32 v12, v12, v13
	v_cvt_pk_bf16_f32 v13, v24, v25
	v_cvt_pk_bf16_f32 v14, v14, v15
	v_cvt_pk_bf16_f32 v15, v20, v21
	global_store_dwordx4 v[26:27], v[12:15], off
	s_nop 1
	v_mov_b32_e32 v12, v206
	v_mov_b32_e32 v13, v207
	v_mov_b32_e32 v14, v208
	v_mov_b32_e32 v15, v209
	v_lshlrev_b32_e32 v16, 16, v12
	v_and_b32_e32 v17, 0xffff0000, v12
	v_lshlrev_b32_e32 v12, 16, v13
	v_and_b32_e32 v13, 0xffff0000, v13
	v_lshlrev_b32_e32 v18, 16, v14
	v_and_b32_e32 v19, 0xffff0000, v14
	v_lshlrev_b32_e32 v14, 16, v15
	v_and_b32_e32 v15, 0xffff0000, v15
	v_pk_mul_f32 v[8:9], v[8:9], v[12:13]
	v_pk_mul_f32 v[6:7], v[6:7], v[16:17]
	v_pk_mul_f32 v[12:13], v[4:5], v[14:15]
	v_pk_mul_f32 v[4:5], v[2:3], v[18:19]
	v_cvt_pk_bf16_f32 v2, v6, v7
	v_cvt_pk_bf16_f32 v3, v8, v9
	v_cvt_pk_bf16_f32 v4, v4, v5
	v_cvt_pk_bf16_f32 v5, v12, v13
	global_store_dwordx4 v[10:11], v[2:5], off
	s_cbranch_vccnz .LBB0_674
	s_andn2_b64 vcc, exec, s[6:7]
	s_cbranch_vccnz .LBB0_673
	s_barrier
	s_branch .LBB0_673

; __host__ __device__ __forceinline__ size_t blk(int r, int k, int K) { return (((size_t)((r >> 8) * (K >> 6) + (k >> 6))) << 14) + (size_t)(((r & 255) << 6) + (k & 63)); }
; __device__ __forceinline__ float bflo(unsigned w) { return __uint_as_float(w << 16); }
; __device__ __forceinline__ float bfhi(unsigned w) { return __uint_as_float(w & 0xffff0000u); }
;     __device__ __forceinline__ void fused(f32x4 (&acc)[2][2][4][2], const Unit& u, int wr, int wc, int fr, int fq, PG8_LAS unsigned char* lds, int wid, int lane) const {
;     ...
;             for (int m = 0; m < 4; ++m) { const int row = row0 + ai * HALF + m * 16; float sq = 0.f;
; #pragma unroll
;                 for (int bj = 0; bj < 2; ++bj) { const u32x4 r = *(const u32x4*)(bb + blk(row, col0 + bj * HALF, D));
;                     f32x4 v0 = (f32x4){bflo(r.x), bfhi(r.x), bflo(r.y), bfhi(r.y)}, v1 = (f32x4){bflo(r.z), bfhi(r.z), bflo(r.w), bfhi(r.w)};
;                     v0 += acc[ai][bj][m][0] * alpha; v1 += acc[ai][bj][m][1] * alpha; acc[ai][bj][m][0] = v0; acc[ai][bj][m][1] = v1;
;                     sq += (v0[0] * v0[0] + v0[1] * v0[1]) + (v0[2] * v0[2] + v0[3] * v0[3]) + (v1[0] * v1[0] + v1[1] * v1[1]) + (v1[2] * v1[2] + v1[3] * v1[3]); }
;                 sq += __shfl_xor(sq, 16); sq += __shfl_xor(sq, 32);
;                 if (fq == 0) Pt[(ai * HALF + wr * 64 + m * 16 + fr) * 4 + wc] = sq; }
.LBB0_942:
	s_lshl_b32 s56, s33, 8
	v_add_u32_e32 v156, s56, v1
	v_lshrrev_b32_e32 v145, 2, v156
	v_and_b32_e32 v145, 0x1fffffc0, v145
	v_add_u32_e32 v158, s65, v145
	v_add_u32_e32 v160, s66, v145
	v_ashrrev_i32_e32 v159, 31, v158
	v_ashrrev_i32_e32 v161, 31, v160
	v_lshlrev_b64 v[158:159], 15, v[158:159]
	v_lshlrev_b64 v[160:161], 15, v[160:161]
	v_lshl_add_u64 v[158:159], s[18:19], 0, v[158:159]
	v_lshl_add_u64 v[160:161], s[18:19], 0, v[160:161]
	v_lshl_add_u64 v[162:163], v[158:159], 0, v[138:139]
	v_lshl_add_u64 v[164:165], v[160:161], 0, v[138:139]
	v_mov_b32_e32 v248, v162
	v_mov_b32_e32 v249, v163
	global_load_dwordx4 v[196:199], v[162:163], off
	global_load_dwordx4 v[200:203], v[164:165], off
	s_mov_b32 s100, 0x10000
	s_mov_b32 s101, 0
	v_lshl_add_u64 v[250:251], v[248:249], 0, s[100:101]
	s_mov_b32 s98, 0x1000
	s_mov_b32 s99, 0
	s_mov_b32 s100, 0x3000
	s_mov_b32 s101, 0
	global_load_dwordx4 v[212:215], v[248:249], off offset:2048
	global_load_dwordx4 v[216:219], v[250:251], off offset:2048
	v_lshl_add_u64 v[248:249], v[248:249], 0, s[98:99]
	v_lshl_add_u64 v[250:251], v[250:251], 0, s[98:99]
	global_load_dwordx4 v[220:223], v[248:249], off
	global_load_dwordx4 v[224:227], v[250:251], off
	global_load_dwordx4 v[228:231], v[248:249], off offset:2048
	global_load_dwordx4 v[232:235], v[250:251], off offset:2048
	v_lshl_add_u64 v[248:249], v[248:249], 0, s[100:101]
	v_lshl_add_u64 v[250:251], v[250:251], 0, s[100:101]
	global_load_dwordx4 v[236:239], v[248:249], off
	global_load_dwordx4 v[240:243], v[250:251], off
	global_load_dwordx4 v[244:247], v[248:249], off offset:2048
	v_and_b32_e32 v147, 64, v187
	v_xor_b32_e32 v145, 16, v187
	v_add_u32_e32 v147, 64, v147
	v_cmp_lt_i32_e32 vcc, v145, v147
	s_waitcnt vmcnt(0)
	v_lshlrev_b32_e32 v204, 16, v196
	v_and_b32_e32 v205, 0xffff0000, v196
	v_lshlrev_b32_e32 v196, 16, v197
	v_and_b32_e32 v197, 0xffff0000, v197
	v_lshlrev_b32_e32 v208, 16, v200
	v_and_b32_e32 v209, 0xffff0000, v200
	v_lshlrev_b32_e32 v200, 16, v201
	v_and_b32_e32 v201, 0xffff0000, v201
	v_cndmask_b32_e32 v145, v187, v145, vcc
	v_lshlrev_b32_e32 v206, 16, v198
	v_and_b32_e32 v207, 0xffff0000, v198
	v_lshlrev_b32_e32 v210, 16, v202
	v_and_b32_e32 v211, 0xffff0000, v202
	v_pk_fma_f32 v[128:129], v[128:129], 0.5, v[196:197] op_sel_hi:[1,0,1]
	v_pk_fma_f32 v[126:127], v[126:127], 0.5, v[204:205] op_sel_hi:[1,0,1]
	v_pk_fma_f32 v[120:121], v[120:121], 0.5, v[200:201] op_sel_hi:[1,0,1]
	v_pk_fma_f32 v[118:119], v[118:119], 0.5, v[208:209] op_sel_hi:[1,0,1]
	v_lshlrev_b32_e32 v157, 2, v145
	v_lshlrev_b32_e32 v198, 16, v199
	v_and_b32_e32 v199, 0xffff0000, v199
	v_lshlrev_b32_e32 v202, 16, v203
	v_and_b32_e32 v203, 0xffff0000, v203
	v_pk_fma_f32 v[122:123], v[122:123], 0.5, v[206:207] op_sel_hi:[1,0,1]
	v_pk_fma_f32 v[114:115], v[114:115], 0.5, v[210:211] op_sel_hi:[1,0,1]
	v_mul_f32_e32 v145, v127, v127
	v_mul_f32_e32 v149, v129, v129
	v_mul_f32_e32 v195, v119, v119
	v_mul_f32_e32 v196, v121, v121
	v_pk_fma_f32 v[124:125], v[124:125], 0.5, v[198:199] op_sel_hi:[1,0,1]
	v_pk_fma_f32 v[116:117], v[116:117], 0.5, v[202:203] op_sel_hi:[1,0,1]
	v_mul_f32_e32 v151, v123, v123
	v_mul_f32_e32 v197, v115, v115
	v_fmac_f32_e32 v145, v126, v126
	v_fmac_f32_e32 v149, v128, v128
	v_fmac_f32_e32 v195, v118, v118
	v_fmac_f32_e32 v196, v120, v120
	v_mul_f32_e32 v153, v125, v125
	v_mul_f32_e32 v198, v117, v117
	v_fmac_f32_e32 v151, v122, v122
	v_fmac_f32_e32 v197, v114, v114
	v_add_f32_e32 v145, v145, v149
	v_add_f32_e32 v149, v195, v196
	v_fmac_f32_e32 v153, v124, v124
	v_fmac_f32_e32 v198, v116, v116
	v_add_f32_e32 v145, v151, v145
	v_add_f32_e32 v149, v197, v149
	v_add_f32_e32 v145, v153, v145
	v_add_f32_e32 v149, v198, v149
	v_add_f32_e32 v145, v145, v149
	ds_bpermute_b32 v149, v157, v145
	v_xor_b32_e32 v151, 32, v187
	v_cmp_lt_i32_e32 vcc, v151, v147
	s_waitcnt lgkmcnt(0)
	v_add_f32_e32 v145, v145, v149
	v_cndmask_b32_e32 v147, v187, v151, vcc
	v_lshlrev_b32_e32 v195, 2, v147
	ds_bpermute_b32 v147, v195, v145
	s_and_saveexec_b64 s[6:7], s[0:1]
	s_cbranch_execz .LBB0_944
	s_waitcnt lgkmcnt(0)
	v_add_f32_e32 v145, v145, v147
	v_add_u32_e32 v147, s61, v167
	ds_write_b32 v147, v145
.LBB0_944:
	s_or_b64 exec, exec, s[6:7]
	s_nop 0
	s_nop 0
	s_nop 0
	s_waitcnt vmcnt(8)
	v_mov_b32_e32 v196, v212
	v_mov_b32_e32 v197, v213
	v_mov_b32_e32 v198, v214
	v_mov_b32_e32 v199, v215
	global_load_dwordx4 v[212:215], v[250:251], off offset:2048
	v_lshlrev_b32_e32 v200, 16, v196
	v_and_b32_e32 v201, 0xffff0000, v196
	v_lshlrev_b32_e32 v196, 16, v197
	v_and_b32_e32 v197, 0xffff0000, v197
	s_waitcnt vmcnt(8)
	v_mov_b32_e32 v162, v216
	v_mov_b32_e32 v163, v217
	v_mov_b32_e32 v164, v218
	v_mov_b32_e32 v165, v219
	v_lshl_add_u64 v[248:249], v[248:249], 0, s[98:99]
	v_lshl_add_u64 v[250:251], v[250:251], 0, s[98:99]
	global_load_dwordx4 v[216:219], v[248:249], off
	v_lshlrev_b32_e32 v204, 16, v162
	v_and_b32_e32 v205, 0xffff0000, v162
	v_lshlrev_b32_e32 v162, 16, v163
	v_and_b32_e32 v163, 0xffff0000, v163
	v_lshlrev_b32_e32 v202, 16, v198
	v_and_b32_e32 v203, 0xffff0000, v198
	v_lshlrev_b32_e32 v206, 16, v164
	v_and_b32_e32 v207, 0xffff0000, v164
	v_pk_fma_f32 v[112:113], v[112:113], 0.5, v[196:197] op_sel_hi:[1,0,1]
	v_pk_fma_f32 v[110:111], v[110:111], 0.5, v[200:201] op_sel_hi:[1,0,1]
	v_pk_fma_f32 v[104:105], v[104:105], 0.5, v[162:163] op_sel_hi:[1,0,1]
	v_pk_fma_f32 v[102:103], v[102:103], 0.5, v[204:205] op_sel_hi:[1,0,1]
	v_lshlrev_b32_e32 v198, 16, v199
	v_and_b32_e32 v199, 0xffff0000, v199
	v_lshlrev_b32_e32 v164, 16, v165
	v_and_b32_e32 v165, 0xffff0000, v165
	v_pk_fma_f32 v[106:107], v[106:107], 0.5, v[202:203] op_sel_hi:[1,0,1]
	v_pk_fma_f32 v[98:99], v[98:99], 0.5, v[206:207] op_sel_hi:[1,0,1]
	v_mul_f32_e32 v145, v111, v111
	s_waitcnt lgkmcnt(0)
	v_mul_f32_e32 v147, v113, v113
	v_mul_f32_e32 v153, v103, v103
	v_mul_f32_e32 v162, v105, v105
	v_pk_fma_f32 v[108:109], v[108:109], 0.5, v[198:199] op_sel_hi:[1,0,1]
	v_pk_fma_f32 v[100:101], v[100:101], 0.5, v[164:165] op_sel_hi:[1,0,1]
	v_mul_f32_e32 v149, v107, v107
	v_mul_f32_e32 v163, v99, v99
	v_fmac_f32_e32 v145, v110, v110
	v_fmac_f32_e32 v147, v112, v112
	v_fmac_f32_e32 v153, v102, v102
	v_fmac_f32_e32 v162, v104, v104
	v_mul_f32_e32 v151, v109, v109
	v_mul_f32_e32 v164, v101, v101
	v_fmac_f32_e32 v149, v106, v106
	v_fmac_f32_e32 v163, v98, v98
	v_add_f32_e32 v145, v145, v147
	v_add_f32_e32 v147, v153, v162
	v_fmac_f32_e32 v151, v108, v108
	v_fmac_f32_e32 v164, v100, v100
	v_add_f32_e32 v145, v149, v145
	v_add_f32_e32 v147, v163, v147
	v_add_f32_e32 v145, v151, v145
	v_add_f32_e32 v147, v164, v147
	v_add_f32_e32 v145, v145, v147
	ds_bpermute_b32 v147, v157, v145
	s_waitcnt lgkmcnt(0)
	v_add_f32_e32 v145, v145, v147
	ds_bpermute_b32 v147, v195, v145
	s_and_saveexec_b64 s[6:7], s[0:1]
	s_cbranch_execz .LBB0_946
	s_waitcnt lgkmcnt(0)
	v_add_f32_e32 v145, v145, v147
	v_add_u32_e32 v147, s61, v167
	ds_write_b32 v147, v145 offset:256
; __host__ __device__ __forceinline__ size_t blk(int r, int k, int K) { return (((size_t)((r >> 8) * (K >> 6) + (k >> 6))) << 14) + (size_t)(((r & 255) << 6) + (k & 63)); }
; __device__ __forceinline__ float bflo(unsigned w) { return __uint_as_float(w << 16); }
; __device__ __forceinline__ float bfhi(unsigned w) { return __uint_as_float(w & 0xffff0000u); }
;     __device__ __forceinline__ void fused(f32x4 (&acc)[2][2][4][2], const Unit& u, int wr, int wc, int fr, int fq, PG8_LAS unsigned char* lds, int wid, int lane) const {
;     ...
;             for (int m = 0; m < 4; ++m) { const int row = row0 + ai * HALF + m * 16; float sq = 0.f;
; #pragma unroll
;                 for (int bj = 0; bj < 2; ++bj) { const u32x4 r = *(const u32x4*)(bb + blk(row, col0 + bj * HALF, D));
;                     f32x4 v0 = (f32x4){bflo(r.x), bfhi(r.x), bflo(r.y), bfhi(r.y)}, v1 = (f32x4){bflo(r.z), bfhi(r.z), bflo(r.w), bfhi(r.w)};
;                     v0 += acc[ai][bj][m][0] * alpha; v1 += acc[ai][bj][m][1] * alpha; acc[ai][bj][m][0] = v0; acc[ai][bj][m][1] = v1;
;                     sq += (v0[0] * v0[0] + v0[1] * v0[1]) + (v0[2] * v0[2] + v0[3] * v0[3]) + (v1[0] * v1[0] + v1[1] * v1[1]) + (v1[2] * v1[2] + v1[3] * v1[3]); }
;                 sq += __shfl_xor(sq, 16); sq += __shfl_xor(sq, 32);
;                 if (fq == 0) Pt[(ai * HALF + wr * 64 + m * 16 + fr) * 4 + wc] = sq; }
.LBB0_946:
	s_or_b64 exec, exec, s[6:7]
	v_mov_b32_e32 v145, v139
	v_lshl_add_u64 v[162:163], v[158:159], 0, v[144:145]
	v_lshl_add_u64 v[196:197], v[160:161], 0, v[144:145]
	s_nop 0
	s_nop 0
	s_nop 0
	s_waitcnt vmcnt(8)
	v_mov_b32_e32 v162, v220
	v_mov_b32_e32 v163, v221
	v_mov_b32_e32 v164, v222
	v_mov_b32_e32 v165, v223
	global_load_dwordx4 v[220:223], v[250:251], off
	v_lshlrev_b32_e32 v200, 16, v162
	v_and_b32_e32 v201, 0xffff0000, v162
	v_lshlrev_b32_e32 v162, 16, v163
	v_and_b32_e32 v163, 0xffff0000, v163
	s_waitcnt vmcnt(8)
	v_mov_b32_e32 v196, v224
	v_mov_b32_e32 v197, v225
	v_mov_b32_e32 v198, v226
	v_mov_b32_e32 v199, v227
	global_load_dwordx4 v[224:227], v[248:249], off offset:2048
	v_lshlrev_b32_e32 v204, 16, v196
	v_and_b32_e32 v205, 0xffff0000, v196
	v_lshlrev_b32_e32 v196, 16, v197
	v_and_b32_e32 v197, 0xffff0000, v197
	v_lshlrev_b32_e32 v202, 16, v164
	v_and_b32_e32 v203, 0xffff0000, v164
	v_lshlrev_b32_e32 v206, 16, v198
	v_and_b32_e32 v207, 0xffff0000, v198
	v_pk_fma_f32 v[96:97], v[96:97], 0.5, v[162:163] op_sel_hi:[1,0,1]
	v_pk_fma_f32 v[94:95], v[94:95], 0.5, v[200:201] op_sel_hi:[1,0,1]
	v_pk_fma_f32 v[88:89], v[88:89], 0.5, v[196:197] op_sel_hi:[1,0,1]
	v_pk_fma_f32 v[86:87], v[86:87], 0.5, v[204:205] op_sel_hi:[1,0,1]
	v_lshlrev_b32_e32 v164, 16, v165
	v_and_b32_e32 v165, 0xffff0000, v165
	v_lshlrev_b32_e32 v198, 16, v199
	v_and_b32_e32 v199, 0xffff0000, v199
	v_pk_fma_f32 v[90:91], v[90:91], 0.5, v[202:203] op_sel_hi:[1,0,1]
	v_pk_fma_f32 v[82:83], v[82:83], 0.5, v[206:207] op_sel_hi:[1,0,1]
	v_mul_f32_e32 v145, v95, v95
	s_waitcnt lgkmcnt(0)
	v_mul_f32_e32 v147, v97, v97
	v_mul_f32_e32 v153, v87, v87
	v_mul_f32_e32 v162, v89, v89
	v_pk_fma_f32 v[92:93], v[92:93], 0.5, v[164:165] op_sel_hi:[1,0,1]
	v_pk_fma_f32 v[84:85], v[84:85], 0.5, v[198:199] op_sel_hi:[1,0,1]
	v_mul_f32_e32 v149, v91, v91
	v_mul_f32_e32 v163, v83, v83
	v_fmac_f32_e32 v145, v94, v94
	v_fmac_f32_e32 v147, v96, v96
	v_fmac_f32_e32 v153, v86, v86
	v_fmac_f32_e32 v162, v88, v88
	v_mul_f32_e32 v151, v93, v93
	v_mul_f32_e32 v164, v85, v85
	v_fmac_f32_e32 v149, v90, v90
	v_fmac_f32_e32 v163, v82, v82
	v_add_f32_e32 v145, v145, v147
	v_add_f32_e32 v147, v153, v162
	v_fmac_f32_e32 v151, v92, v92
	v_fmac_f32_e32 v164, v84, v84
	v_add_f32_e32 v145, v149, v145
	v_add_f32_e32 v147, v163, v147
	v_add_f32_e32 v145, v151, v145
	v_add_f32_e32 v147, v164, v147
	v_add_f32_e32 v145, v145, v147
	ds_bpermute_b32 v147, v157, v145
	s_waitcnt lgkmcnt(0)
	v_add_f32_e32 v145, v145, v147
	ds_bpermute_b32 v147, v195, v145
	s_and_saveexec_b64 s[6:7], s[0:1]
	s_cbranch_execz .LBB0_948
	s_waitcnt lgkmcnt(0)
	v_add_f32_e32 v145, v145, v147
	v_add_u32_e32 v147, s61, v167
	ds_write_b32 v147, v145 offset:512
.LBB0_948:
	s_or_b64 exec, exec, s[6:7]
	s_waitcnt lgkmcnt(0)
	v_mov_b32_e32 v147, v139
	v_lshl_add_u64 v[158:159], v[158:159], 0, v[146:147]
	s_nop 0
	v_lshl_add_u64 v[158:159], v[160:161], 0, v[146:147]
	s_nop 0
	s_waitcnt vmcnt(8)
	v_mov_b32_e32 v162, v228
	v_mov_b32_e32 v163, v229
	v_mov_b32_e32 v164, v230
	v_mov_b32_e32 v165, v231
	global_load_dwordx4 v[228:231], v[250:251], off offset:2048
	v_lshlrev_b32_e32 v196, 16, v162
	v_and_b32_e32 v197, 0xffff0000, v162
	v_lshlrev_b32_e32 v162, 16, v163
	v_and_b32_e32 v163, 0xffff0000, v163
	s_waitcnt vmcnt(8)
	v_mov_b32_e32 v158, v232
	v_mov_b32_e32 v159, v233
	v_mov_b32_e32 v160, v234
	v_mov_b32_e32 v161, v235
	v_lshlrev_b32_e32 v200, 16, v158
	v_and_b32_e32 v201, 0xffff0000, v158
	v_lshlrev_b32_e32 v158, 16, v159
	v_and_b32_e32 v159, 0xffff0000, v159
	v_lshlrev_b32_e32 v198, 16, v164
	v_and_b32_e32 v199, 0xffff0000, v164
	v_lshlrev_b32_e32 v202, 16, v160
	v_and_b32_e32 v203, 0xffff0000, v160
	v_pk_fma_f32 v[80:81], v[80:81], 0.5, v[162:163] op_sel_hi:[1,0,1]
	v_pk_fma_f32 v[78:79], v[78:79], 0.5, v[196:197] op_sel_hi:[1,0,1]
	v_pk_fma_f32 v[72:73], v[72:73], 0.5, v[158:159] op_sel_hi:[1,0,1]
	v_pk_fma_f32 v[70:71], v[70:71], 0.5, v[200:201] op_sel_hi:[1,0,1]
	v_lshlrev_b32_e32 v164, 16, v165
	v_and_b32_e32 v165, 0xffff0000, v165
	v_lshlrev_b32_e32 v160, 16, v161
	v_and_b32_e32 v161, 0xffff0000, v161
	v_pk_fma_f32 v[74:75], v[74:75], 0.5, v[198:199] op_sel_hi:[1,0,1]
	v_pk_fma_f32 v[66:67], v[66:67], 0.5, v[202:203] op_sel_hi:[1,0,1]
	v_mul_f32_e32 v145, v79, v79
	v_mul_f32_e32 v147, v81, v81
	v_mul_f32_e32 v153, v71, v71
	v_mul_f32_e32 v158, v73, v73
	v_pk_fma_f32 v[76:77], v[76:77], 0.5, v[164:165] op_sel_hi:[1,0,1]
	v_pk_fma_f32 v[68:69], v[68:69], 0.5, v[160:161] op_sel_hi:[1,0,1]
	v_mul_f32_e32 v149, v75, v75
	v_mul_f32_e32 v159, v67, v67
	v_fmac_f32_e32 v145, v78, v78
	v_fmac_f32_e32 v147, v80, v80
	v_fmac_f32_e32 v153, v70, v70
	v_fmac_f32_e32 v158, v72, v72
	v_mul_f32_e32 v151, v77, v77
	v_mul_f32_e32 v160, v69, v69
	v_fmac_f32_e32 v149, v74, v74
	v_fmac_f32_e32 v159, v66, v66
	v_add_f32_e32 v145, v145, v147
	v_add_f32_e32 v147, v153, v158
	v_fmac_f32_e32 v151, v76, v76
	v_fmac_f32_e32 v160, v68, v68
	v_add_f32_e32 v145, v149, v145
	v_add_f32_e32 v147, v159, v147
	v_add_f32_e32 v145, v151, v145
	v_add_f32_e32 v147, v160, v147
	v_add_f32_e32 v145, v145, v147
	ds_bpermute_b32 v147, v157, v145
	s_waitcnt lgkmcnt(0)
	v_add_f32_e32 v145, v145, v147
	ds_bpermute_b32 v147, v195, v145
	s_and_saveexec_b64 s[6:7], s[0:1]
	s_cbranch_execz .LBB0_950
	s_waitcnt lgkmcnt(0)
	v_add_f32_e32 v145, v145, v147
	v_add_u32_e32 v147, s61, v167
	ds_write_b32 v147, v145 offset:768
; __host__ __device__ __forceinline__ size_t blk(int r, int k, int K) { return (((size_t)((r >> 8) * (K >> 6) + (k >> 6))) << 14) + (size_t)(((r & 255) << 6) + (k & 63)); }
; __device__ __forceinline__ float bflo(unsigned w) { return __uint_as_float(w << 16); }
; __device__ __forceinline__ float bfhi(unsigned w) { return __uint_as_float(w & 0xffff0000u); }
;     __device__ __forceinline__ void fused(f32x4 (&acc)[2][2][4][2], const Unit& u, int wr, int wc, int fr, int fq, PG8_LAS unsigned char* lds, int wid, int lane) const {
;     ...
;             for (int m = 0; m < 4; ++m) { const int row = row0 + ai * HALF + m * 16; float sq = 0.f;
; #pragma unroll
;                 for (int bj = 0; bj < 2; ++bj) { const u32x4 r = *(const u32x4*)(bb + blk(row, col0 + bj * HALF, D));
;                     f32x4 v0 = (f32x4){bflo(r.x), bfhi(r.x), bflo(r.y), bfhi(r.y)}, v1 = (f32x4){bflo(r.z), bfhi(r.z), bflo(r.w), bfhi(r.w)};
;                     v0 += acc[ai][bj][m][0] * alpha; v1 += acc[ai][bj][m][1] * alpha; acc[ai][bj][m][0] = v0; acc[ai][bj][m][1] = v1;
;                     sq += (v0[0] * v0[0] + v0[1] * v0[1]) + (v0[2] * v0[2] + v0[3] * v0[3]) + (v1[0] * v1[0] + v1[1] * v1[1]) + (v1[2] * v1[2] + v1[3] * v1[3]); }
;                 sq += __shfl_xor(sq, 16); sq += __shfl_xor(sq, 32);
;                 if (fq == 0) Pt[(ai * HALF + wr * 64 + m * 16 + fr) * 4 + wc] = sq; }
.LBB0_950:
	s_or_b64 exec, exec, s[6:7]
	v_add_u32_e32 v145, 0x80, v156
	s_waitcnt lgkmcnt(0)
	v_lshrrev_b32_e32 v147, 2, v145
	v_and_b32_e32 v147, 0x1fffffc0, v147
	v_add_u32_e32 v158, s65, v147
	v_lshlrev_b32_e32 v145, 6, v145
	v_ashrrev_i32_e32 v159, 31, v158
	v_and_or_b32 v145, v145, s64, v176
	v_lshlrev_b64 v[158:159], 15, v[158:159]
	v_lshl_add_u64 v[158:159], s[18:19], 0, v[158:159]
	v_lshlrev_b32_e32 v196, 1, v145
	v_mov_b32_e32 v197, v139
	v_lshl_add_u64 v[160:161], v[158:159], 0, v[196:197]
	s_nop 0
	v_add_u32_e32 v160, s66, v147
	v_ashrrev_i32_e32 v161, 31, v160
	v_lshlrev_b64 v[160:161], 15, v[160:161]
	v_lshl_add_u64 v[160:161], s[18:19], 0, v[160:161]
	v_lshl_add_u64 v[196:197], v[160:161], 0, v[196:197]
	s_nop 0
	s_waitcnt vmcnt(7)
	v_mov_b32_e32 v162, v236
	v_mov_b32_e32 v163, v237
	v_mov_b32_e32 v164, v238
	v_mov_b32_e32 v165, v239
	v_lshlrev_b32_e32 v200, 16, v162
	v_and_b32_e32 v201, 0xffff0000, v162
	v_lshlrev_b32_e32 v162, 16, v163
	v_and_b32_e32 v163, 0xffff0000, v163
	v_lshlrev_b32_e32 v202, 16, v164
	v_and_b32_e32 v203, 0xffff0000, v164
	s_waitcnt vmcnt(6)
	v_mov_b32_e32 v196, v240
	v_mov_b32_e32 v197, v241
	v_mov_b32_e32 v198, v242
	v_mov_b32_e32 v199, v243
	v_lshlrev_b32_e32 v204, 16, v196
	v_and_b32_e32 v205, 0xffff0000, v196
	v_lshlrev_b32_e32 v196, 16, v197
	v_and_b32_e32 v197, 0xffff0000, v197
	v_lshlrev_b32_e32 v206, 16, v198
	v_and_b32_e32 v207, 0xffff0000, v198
	v_pk_fma_f32 v[64:65], v[64:65], 0.5, v[162:163] op_sel_hi:[1,0,1]
	v_pk_fma_f32 v[62:63], v[62:63], 0.5, v[200:201] op_sel_hi:[1,0,1]
	v_pk_fma_f32 v[56:57], v[56:57], 0.5, v[196:197] op_sel_hi:[1,0,1]
	v_pk_fma_f32 v[54:55], v[54:55], 0.5, v[204:205] op_sel_hi:[1,0,1]
	v_lshlrev_b32_e32 v164, 16, v165
	v_and_b32_e32 v165, 0xffff0000, v165
	v_lshlrev_b32_e32 v198, 16, v199
	v_and_b32_e32 v199, 0xffff0000, v199
	v_pk_fma_f32 v[58:59], v[58:59], 0.5, v[202:203] op_sel_hi:[1,0,1]
	v_pk_fma_f32 v[50:51], v[50:51], 0.5, v[206:207] op_sel_hi:[1,0,1]
	v_mul_f32_e32 v145, v63, v63
	v_mul_f32_e32 v147, v65, v65
	v_mul_f32_e32 v153, v55, v55
	v_mul_f32_e32 v162, v57, v57
	v_pk_fma_f32 v[60:61], v[60:61], 0.5, v[164:165] op_sel_hi:[1,0,1]
	v_pk_fma_f32 v[52:53], v[52:53], 0.5, v[198:199] op_sel_hi:[1,0,1]
	v_mul_f32_e32 v149, v59, v59
	v_mul_f32_e32 v163, v51, v51
	v_fmac_f32_e32 v145, v62, v62
	v_fmac_f32_e32 v147, v64, v64
	v_fmac_f32_e32 v153, v54, v54
	v_fmac_f32_e32 v162, v56, v56
	v_mul_f32_e32 v151, v61, v61
	v_mul_f32_e32 v164, v53, v53
	v_fmac_f32_e32 v149, v58, v58
	v_fmac_f32_e32 v163, v50, v50
	v_add_f32_e32 v145, v145, v147
	v_add_f32_e32 v147, v153, v162
	v_fmac_f32_e32 v151, v60, v60
	v_fmac_f32_e32 v164, v52, v52
	v_add_f32_e32 v145, v149, v145
	v_add_f32_e32 v147, v163, v147
	v_add_f32_e32 v145, v151, v145
	v_add_f32_e32 v147, v164, v147
	v_add_f32_e32 v145, v145, v147
	ds_bpermute_b32 v147, v157, v145
	s_waitcnt lgkmcnt(0)
	v_add_f32_e32 v145, v145, v147
	ds_bpermute_b32 v147, v195, v145
	s_and_saveexec_b64 s[6:7], s[0:1]
	s_cbranch_execz .LBB0_952
	s_waitcnt lgkmcnt(0)
	v_add_f32_e32 v145, v145, v147
	ds_write_b32 v188, v145
.LBB0_952:
	s_or_b64 exec, exec, s[6:7]
	v_mov_b32_e32 v149, v139
	v_lshl_add_u64 v[162:163], v[158:159], 0, v[148:149]
	v_lshl_add_u64 v[196:197], v[160:161], 0, v[148:149]
	s_nop 0
	s_nop 0
	s_nop 0
	s_waitcnt vmcnt(5)
	v_mov_b32_e32 v162, v244
	v_mov_b32_e32 v163, v245
	v_mov_b32_e32 v164, v246
	v_mov_b32_e32 v165, v247
	v_lshlrev_b32_e32 v200, 16, v162
	v_and_b32_e32 v201, 0xffff0000, v162
	v_lshlrev_b32_e32 v162, 16, v163
	v_and_b32_e32 v163, 0xffff0000, v163
	s_waitcnt vmcnt(4)
	v_mov_b32_e32 v196, v212
	v_mov_b32_e32 v197, v213
	v_mov_b32_e32 v198, v214
	v_mov_b32_e32 v199, v215
	v_lshlrev_b32_e32 v204, 16, v196
	v_and_b32_e32 v205, 0xffff0000, v196
	v_lshlrev_b32_e32 v196, 16, v197
	v_and_b32_e32 v197, 0xffff0000, v197
	v_lshlrev_b32_e32 v202, 16, v164
	v_and_b32_e32 v203, 0xffff0000, v164
	v_lshlrev_b32_e32 v206, 16, v198
	v_and_b32_e32 v207, 0xffff0000, v198
	v_pk_fma_f32 v[48:49], v[48:49], 0.5, v[162:163] op_sel_hi:[1,0,1]
	v_pk_fma_f32 v[46:47], v[46:47], 0.5, v[200:201] op_sel_hi:[1,0,1]
	v_pk_fma_f32 v[40:41], v[40:41], 0.5, v[196:197] op_sel_hi:[1,0,1]
	v_pk_fma_f32 v[38:39], v[38:39], 0.5, v[204:205] op_sel_hi:[1,0,1]
	v_lshlrev_b32_e32 v164, 16, v165
	v_and_b32_e32 v165, 0xffff0000, v165
	v_lshlrev_b32_e32 v198, 16, v199
	v_and_b32_e32 v199, 0xffff0000, v199
	v_pk_fma_f32 v[42:43], v[42:43], 0.5, v[202:203] op_sel_hi:[1,0,1]
	v_pk_fma_f32 v[34:35], v[34:35], 0.5, v[206:207] op_sel_hi:[1,0,1]
	v_mul_f32_e32 v145, v47, v47
	s_waitcnt lgkmcnt(0)
	v_mul_f32_e32 v147, v49, v49
	v_mul_f32_e32 v153, v39, v39
	v_mul_f32_e32 v162, v41, v41
	v_pk_fma_f32 v[44:45], v[44:45], 0.5, v[164:165] op_sel_hi:[1,0,1]
	v_pk_fma_f32 v[36:37], v[36:37], 0.5, v[198:199] op_sel_hi:[1,0,1]
	v_mul_f32_e32 v149, v43, v43
	v_mul_f32_e32 v163, v35, v35
	v_fmac_f32_e32 v145, v46, v46
	v_fmac_f32_e32 v147, v48, v48
	v_fmac_f32_e32 v153, v38, v38
	v_fmac_f32_e32 v162, v40, v40
	v_mul_f32_e32 v151, v45, v45
	v_mul_f32_e32 v164, v37, v37
	v_fmac_f32_e32 v149, v42, v42
	v_fmac_f32_e32 v163, v34, v34
	v_add_f32_e32 v145, v145, v147
	v_add_f32_e32 v147, v153, v162
	v_fmac_f32_e32 v151, v44, v44
	v_fmac_f32_e32 v164, v36, v36
	v_add_f32_e32 v145, v149, v145
	v_add_f32_e32 v147, v163, v147
	v_add_f32_e32 v145, v151, v145
	v_add_f32_e32 v147, v164, v147
	v_add_f32_e32 v145, v145, v147
	ds_bpermute_b32 v147, v157, v145
	s_waitcnt lgkmcnt(0)
	v_add_f32_e32 v145, v145, v147
	ds_bpermute_b32 v147, v195, v145
	s_and_saveexec_b64 s[6:7], s[0:1]
	s_cbranch_execz .LBB0_954
	s_waitcnt lgkmcnt(0)
	v_add_f32_e32 v145, v145, v147
	v_add_u32_e32 v147, s61, v167
	ds_write_b32 v147, v145 offset:2304
; __host__ __device__ __forceinline__ size_t blk(int r, int k, int K) { return (((size_t)((r >> 8) * (K >> 6) + (k >> 6))) << 14) + (size_t)(((r & 255) << 6) + (k & 63)); }
; __device__ __forceinline__ float bflo(unsigned w) { return __uint_as_float(w << 16); }
; __device__ __forceinline__ float bfhi(unsigned w) { return __uint_as_float(w & 0xffff0000u); }
;     __device__ __forceinline__ void fused(f32x4 (&acc)[2][2][4][2], const Unit& u, int wr, int wc, int fr, int fq, PG8_LAS unsigned char* lds, int wid, int lane) const {
;     ...
;             for (int m = 0; m < 4; ++m) { const int row = row0 + ai * HALF + m * 16; float sq = 0.f;
; #pragma unroll
;                 for (int bj = 0; bj < 2; ++bj) { const u32x4 r = *(const u32x4*)(bb + blk(row, col0 + bj * HALF, D));
;                     f32x4 v0 = (f32x4){bflo(r.x), bfhi(r.x), bflo(r.y), bfhi(r.y)}, v1 = (f32x4){bflo(r.z), bfhi(r.z), bflo(r.w), bfhi(r.w)};
;                     v0 += acc[ai][bj][m][0] * alpha; v1 += acc[ai][bj][m][1] * alpha; acc[ai][bj][m][0] = v0; acc[ai][bj][m][1] = v1;
;                     sq += (v0[0] * v0[0] + v0[1] * v0[1]) + (v0[2] * v0[2] + v0[3] * v0[3]) + (v1[0] * v1[0] + v1[1] * v1[1]) + (v1[2] * v1[2] + v1[3] * v1[3]); }
;                 sq += __shfl_xor(sq, 16); sq += __shfl_xor(sq, 32);
;                 if (fq == 0) Pt[(ai * HALF + wr * 64 + m * 16 + fr) * 4 + wc] = sq; }
.LBB0_954:
	s_or_b64 exec, exec, s[6:7]
	v_mov_b32_e32 v151, v139
	v_lshl_add_u64 v[162:163], v[158:159], 0, v[150:151]
	v_lshl_add_u64 v[196:197], v[160:161], 0, v[150:151]
	s_nop 0
	s_nop 0
	s_nop 0
	s_waitcnt vmcnt(3)
	v_mov_b32_e32 v162, v216
	v_mov_b32_e32 v163, v217
	v_mov_b32_e32 v164, v218
	v_mov_b32_e32 v165, v219
	v_lshlrev_b32_e32 v200, 16, v162
	v_and_b32_e32 v201, 0xffff0000, v162
	v_lshlrev_b32_e32 v162, 16, v163
	v_and_b32_e32 v163, 0xffff0000, v163
	s_waitcnt vmcnt(2)
	v_mov_b32_e32 v196, v220
	v_mov_b32_e32 v197, v221
	v_mov_b32_e32 v198, v222
	v_mov_b32_e32 v199, v223
	v_lshlrev_b32_e32 v204, 16, v196
	v_and_b32_e32 v205, 0xffff0000, v196
	v_lshlrev_b32_e32 v196, 16, v197
	v_and_b32_e32 v197, 0xffff0000, v197
	v_lshlrev_b32_e32 v202, 16, v164
	v_and_b32_e32 v203, 0xffff0000, v164
	v_lshlrev_b32_e32 v206, 16, v198
	v_and_b32_e32 v207, 0xffff0000, v198
	v_pk_fma_f32 v[32:33], v[32:33], 0.5, v[162:163] op_sel_hi:[1,0,1]
	v_pk_fma_f32 v[30:31], v[30:31], 0.5, v[200:201] op_sel_hi:[1,0,1]
	v_pk_fma_f32 v[24:25], v[24:25], 0.5, v[196:197] op_sel_hi:[1,0,1]
	v_pk_fma_f32 v[22:23], v[22:23], 0.5, v[204:205] op_sel_hi:[1,0,1]
	v_lshlrev_b32_e32 v164, 16, v165
	v_and_b32_e32 v165, 0xffff0000, v165
	v_lshlrev_b32_e32 v198, 16, v199
	v_and_b32_e32 v199, 0xffff0000, v199
	v_pk_fma_f32 v[26:27], v[26:27], 0.5, v[202:203] op_sel_hi:[1,0,1]
	v_pk_fma_f32 v[18:19], v[18:19], 0.5, v[206:207] op_sel_hi:[1,0,1]
	v_mul_f32_e32 v145, v31, v31
	s_waitcnt lgkmcnt(0)
	v_mul_f32_e32 v147, v33, v33
	v_mul_f32_e32 v153, v23, v23
	v_mul_f32_e32 v162, v25, v25
	v_pk_fma_f32 v[28:29], v[28:29], 0.5, v[164:165] op_sel_hi:[1,0,1]
	v_pk_fma_f32 v[20:21], v[20:21], 0.5, v[198:199] op_sel_hi:[1,0,1]
	v_mul_f32_e32 v149, v27, v27
	v_mul_f32_e32 v163, v19, v19
	v_fmac_f32_e32 v145, v30, v30
	v_fmac_f32_e32 v147, v32, v32
	v_fmac_f32_e32 v153, v22, v22
	v_fmac_f32_e32 v162, v24, v24
	v_mul_f32_e32 v151, v29, v29
	v_mul_f32_e32 v164, v21, v21
	v_fmac_f32_e32 v149, v26, v26
	v_fmac_f32_e32 v163, v18, v18
	v_add_f32_e32 v145, v145, v147
	v_add_f32_e32 v147, v153, v162
	v_fmac_f32_e32 v151, v28, v28
	v_fmac_f32_e32 v164, v20, v20
	v_add_f32_e32 v145, v149, v145
	v_add_f32_e32 v147, v163, v147
	v_add_f32_e32 v145, v151, v145
	v_add_f32_e32 v147, v164, v147
	v_add_f32_e32 v145, v145, v147
	ds_bpermute_b32 v147, v157, v145
	s_waitcnt lgkmcnt(0)
	v_add_f32_e32 v145, v145, v147
	ds_bpermute_b32 v147, v195, v145
	s_and_saveexec_b64 s[6:7], s[0:1]
	s_cbranch_execz .LBB0_956
	s_waitcnt lgkmcnt(0)
	v_add_f32_e32 v145, v145, v147
	v_add_u32_e32 v147, s61, v167
	ds_write_b32 v147, v145 offset:2560
.LBB0_956:
	s_or_b64 exec, exec, s[6:7]
	v_mov_b32_e32 v153, v139
	v_lshl_add_u64 v[158:159], v[158:159], 0, v[152:153]
	s_nop 0
	v_lshl_add_u64 v[158:159], v[160:161], 0, v[152:153]
	s_nop 0
	s_waitcnt vmcnt(1)
	v_mov_b32_e32 v162, v224
	v_mov_b32_e32 v163, v225
	v_mov_b32_e32 v164, v226
	v_mov_b32_e32 v165, v227
	v_lshlrev_b32_e32 v196, 16, v162
	v_and_b32_e32 v197, 0xffff0000, v162
	v_lshlrev_b32_e32 v162, 16, v163
	v_and_b32_e32 v163, 0xffff0000, v163
	s_waitcnt vmcnt(0)
	v_mov_b32_e32 v158, v228
	v_mov_b32_e32 v159, v229
	v_mov_b32_e32 v160, v230
	v_mov_b32_e32 v161, v231
	v_lshlrev_b32_e32 v200, 16, v158
	v_and_b32_e32 v201, 0xffff0000, v158
	v_lshlrev_b32_e32 v158, 16, v159
	v_and_b32_e32 v159, 0xffff0000, v159
	v_lshlrev_b32_e32 v198, 16, v164
	v_and_b32_e32 v199, 0xffff0000, v164
	v_lshlrev_b32_e32 v202, 16, v160
	v_and_b32_e32 v203, 0xffff0000, v160
	v_pk_fma_f32 v[16:17], v[16:17], 0.5, v[162:163] op_sel_hi:[1,0,1]
	v_pk_fma_f32 v[14:15], v[14:15], 0.5, v[196:197] op_sel_hi:[1,0,1]
	v_pk_fma_f32 v[8:9], v[8:9], 0.5, v[158:159] op_sel_hi:[1,0,1]
	v_pk_fma_f32 v[6:7], v[6:7], 0.5, v[200:201] op_sel_hi:[1,0,1]
	v_lshlrev_b32_e32 v164, 16, v165
	v_and_b32_e32 v165, 0xffff0000, v165
	v_lshlrev_b32_e32 v160, 16, v161
	v_and_b32_e32 v161, 0xffff0000, v161
	v_pk_fma_f32 v[10:11], v[10:11], 0.5, v[198:199] op_sel_hi:[1,0,1]
	v_pk_fma_f32 v[2:3], v[2:3], 0.5, v[202:203] op_sel_hi:[1,0,1]
	v_mul_f32_e32 v145, v15, v15
	s_waitcnt lgkmcnt(0)
	v_mul_f32_e32 v147, v17, v17
	v_mul_f32_e32 v153, v7, v7
	v_mul_f32_e32 v158, v9, v9
	v_pk_fma_f32 v[12:13], v[12:13], 0.5, v[164:165] op_sel_hi:[1,0,1]
	v_pk_fma_f32 v[4:5], v[4:5], 0.5, v[160:161] op_sel_hi:[1,0,1]
	v_mul_f32_e32 v149, v11, v11
	v_mul_f32_e32 v159, v3, v3
	v_fmac_f32_e32 v145, v14, v14
	v_fmac_f32_e32 v147, v16, v16
	v_fmac_f32_e32 v153, v6, v6
	v_fmac_f32_e32 v158, v8, v8
	v_mul_f32_e32 v151, v13, v13
	v_mul_f32_e32 v160, v5, v5
	v_fmac_f32_e32 v149, v10, v10
	v_fmac_f32_e32 v159, v2, v2
	v_add_f32_e32 v145, v145, v147
	v_add_f32_e32 v147, v153, v158
	v_fmac_f32_e32 v151, v12, v12
	v_fmac_f32_e32 v160, v4, v4
	v_add_f32_e32 v145, v149, v145
	v_add_f32_e32 v147, v159, v147
	v_add_f32_e32 v145, v151, v145
	v_add_f32_e32 v147, v160, v147
	v_add_f32_e32 v145, v145, v147
	ds_bpermute_b32 v147, v157, v145
	s_waitcnt lgkmcnt(0)
	v_add_f32_e32 v145, v145, v147
	ds_bpermute_b32 v147, v195, v145
	s_and_saveexec_b64 s[6:7], s[0:1]
	s_cbranch_execz .LBB0_958
	s_waitcnt lgkmcnt(0)
	v_add_f32_e32 v145, v145, v147
	v_add_u32_e32 v147, s61, v167
	ds_write_b32 v147, v145 offset:2816
